# hgrn_prep q/f loads issued 16 tokens ahead (rolling window) + compressed-tile staging batched; on top of EpiResid de-serialisation
# speedup vs baseline: 1.0317x; 1.0098x over previous
; __device__ __forceinline__ float bflo(unsigned w) { return __uint_as_float(w << 16); }
; __device__ __forceinline__ float bfhi(unsigned w) { return __uint_as_float(w & 0xffff0000u); }
; __device__ __forceinline__ unsigned pk2(float lo, float hi) { return pg8::cvt_pk_bf16(lo, hi); }
; __device__ __forceinline__ float siluf(float x) { return x * __builtin_amdgcn_rcpf(1.0f + __expf(-x)); }
; __device__ __forceinline__ int vpos(int k) { return (k & ~12) | ((k & 4) << 1) | ((k & 8) >> 1); }
; __device__ __forceinline__ void hgrn_prep_phase(const bf16* z, const float* lbv, bf16* hq, float* dd, int tid, int G) {
;     ...
;         if (role == 0) { const int k = 2 * ln; const float lb0 = lbv[h * 128 + k], lb1 = lbv[h * 128 + k + 1], om0 = 1.0f - lb0, om1 = 1.0f - lb1; float bc0 = 0.f, bc1 = 0.f; float kk0[32], kk1[32], bv0[32], bv1[32];
;             const bf16* zq = z + row0 * ZP + C_HQ + h * 128 + k; const bf16* zf = z + row0 * ZP + C_HF + h * 128 + k; const int kp = vpos(k);
; #pragma unroll
;             for (int tau = 0; tau < 32; ++tau) { const unsigned q2 = *(const unsigned*)(zq + (size_t)tau * ZP), f2 = *(const unsigned*)(zf + (size_t)tau * ZP);
;                 const float xf0 = fminf(fmaxf(bflo(f2), -30.f), 30.f), xf1 = fminf(fmaxf(bfhi(f2), -30.f), 30.f);
;                 const float e0 = __expf(-xf0), r0 = __builtin_amdgcn_rcpf(1.0f + e0), e1 = __expf(-xf1), r1 = __builtin_amdgcn_rcpf(1.0f + e1);
;                 const float f0 = lb0 + om0 * r0, f1 = lb1 + om1 * r1, k0v = om0 * (e0 * r0), k1v = om1 * (e1 * r1);
;                 bc0 += __logf(f0); bc1 += __logf(f1); kk0[tau] = k0v; kk1[tau] = k1v; bv0[tau] = bc0; bv1[tau] = bc1;
;                 *(unsigned*)(QT + tile + tau * 128 + kp) = pk2(siluf(bflo(q2)) * __expf(bc0), siluf(bfhi(q2)) * __expf(bc1));
;                 *(unsigned*)(KT + tile + tau * 128 + kp) = pk2(k0v * __expf(-bc0), k1v * __expf(-bc1)); }
.LBB0_598:
	s_or_saveexec_b64 s[16:17], s[4:5]
	v_mov_b64_e32 v[26:27], 0x1fe00000
	s_xor_b64 exec, exec, s[16:17]
	s_cbranch_execz .LBB0_595
	v_lshlrev_b32_e32 v4, 2, v8
	v_lshl_or_b32 v36, s0, 9, v4
	v_mov_b64_e32 v[4:5], s[76:77]
	v_mad_u64_u32 v[4:5], s[4:5], v28, s88, v[4:5]
	v_mov_b32_e32 v6, v5
	v_mad_u64_u32 v[6:7], s[4:5], v9, s88, v[6:7]
	v_mov_b32_e32 v5, v6
	s_lshl_b32 s68, s0, 8
	v_lshl_add_u64 v[4:5], v[4:5], 0, s[68:69]
	v_lshl_add_u64 v[30:31], v[4:5], 0, v[2:3]
	v_mov_b32_e32 v210, v30
	v_mov_b32_e32 v211, v31
	v_mov_b32_e32 v230, 0x5a00
	v_mov_b32_e32 v231, 0
	global_load_dword v164, v[210:211], off
	global_load_dword v165, v[210:211], off offset:1024
	v_lshl_add_u64 v[210:211], v[210:211], 0, v[230:231]
	global_load_dword v166, v[210:211], off
	global_load_dword v167, v[210:211], off offset:1024
	v_lshl_add_u64 v[210:211], v[210:211], 0, v[230:231]
	global_load_dword v168, v[210:211], off
	global_load_dword v169, v[210:211], off offset:1024
	v_lshl_add_u64 v[210:211], v[210:211], 0, v[230:231]
	global_load_dword v170, v[210:211], off
	global_load_dword v171, v[210:211], off offset:1024
	v_lshl_add_u64 v[210:211], v[210:211], 0, v[230:231]
	global_load_dword v186, v[210:211], off
	global_load_dword v187, v[210:211], off offset:1024
	v_lshl_add_u64 v[210:211], v[210:211], 0, v[230:231]
	global_load_dword v188, v[210:211], off
	global_load_dword v189, v[210:211], off offset:1024
	v_lshl_add_u64 v[210:211], v[210:211], 0, v[230:231]
	global_load_dword v190, v[210:211], off
	global_load_dword v191, v[210:211], off offset:1024
	v_lshl_add_u64 v[210:211], v[210:211], 0, v[230:231]
	global_load_dword v192, v[210:211], off
	global_load_dword v193, v[210:211], off offset:1024
	v_lshl_add_u64 v[210:211], v[210:211], 0, v[230:231]
	global_load_dword v194, v[210:211], off
	global_load_dword v195, v[210:211], off offset:1024
	v_lshl_add_u64 v[210:211], v[210:211], 0, v[230:231]
	global_load_dword v196, v[210:211], off
	global_load_dword v197, v[210:211], off offset:1024
	v_lshl_add_u64 v[210:211], v[210:211], 0, v[230:231]
	global_load_dword v198, v[210:211], off
	global_load_dword v199, v[210:211], off offset:1024
	v_lshl_add_u64 v[210:211], v[210:211], 0, v[230:231]
	global_load_dword v200, v[210:211], off
	global_load_dword v201, v[210:211], off offset:1024
	v_lshl_add_u64 v[210:211], v[210:211], 0, v[230:231]
	global_load_dword v202, v[210:211], off
	global_load_dword v203, v[210:211], off offset:1024
	v_lshl_add_u64 v[210:211], v[210:211], 0, v[230:231]
	global_load_dword v204, v[210:211], off
	global_load_dword v205, v[210:211], off offset:1024
	v_lshl_add_u64 v[210:211], v[210:211], 0, v[230:231]
	global_load_dword v206, v[210:211], off
	global_load_dword v207, v[210:211], off offset:1024
	v_lshl_add_u64 v[210:211], v[210:211], 0, v[230:231]
	global_load_dword v208, v[210:211], off
	global_load_dword v209, v[210:211], off offset:1024
	v_lshl_add_u64 v[210:211], v[210:211], 0, v[230:231]
	s_waitcnt vmcnt(30)
	v_mov_b32_e32 v2, v164
	v_mov_b32_e32 v4, v165
	v_lshlrev_b64 v[6:7], 1, v[22:23]
	v_lshl_add_u64 v[62:63], v[12:13], 0, v[6:7]
	v_lshl_add_u64 v[64:65], v[14:15], 0, v[6:7]
	s_mov_b32 s0, 0xb000
	v_lshlrev_b64 v[24:25], 9, v[24:25]
	v_lshl_add_u64 v[24:25], v[16:17], 0, v[24:25]
	v_lshl_add_u64 v[6:7], v[18:19], 0, v[6:7]
	v_lshlrev_b32_e32 v26, 16, v2
	v_and_b32_e32 v27, 0xffff0000, v2
	v_mul_f32_e32 v2, 0xbfb8aa3b, v26
	v_exp_f32_e32 v2, v2
	v_lshlrev_b32_e32 v5, 16, v4
	v_max_f32_e32 v5, v5, v5
	v_and_b32_e32 v4, 0xffff0000, v4
	v_add_f32_e32 v2, 1.0, v2
	v_rcp_f32_e32 v28, v2
	v_mul_f32_e32 v2, 0xbfb8aa3b, v27
	v_exp_f32_e32 v2, v2
	v_med3_f32 v5, v5, s89, v225
	v_max_f32_e32 v4, v4, v4
	v_med3_f32 v9, v4, s89, v225
	v_add_f32_e32 v2, 1.0, v2
	v_rcp_f32_e32 v29, v2
	v_mul_f32_e32 v4, 0xbfb8aa3b, v5
	v_exp_f32_e32 v4, v4
	v_pk_mul_f32 v[34:35], v[28:29], v[26:27]
	global_load_dwordx2 v[28:29], v36, s[14:15]
	v_add_f32_e32 v5, 1.0, v4
	v_rcp_f32_e32 v32, v5
	v_mul_f32_e32 v5, 0xbfb8aa3b, v9
	v_exp_f32_e32 v5, v5
	s_waitcnt vmcnt(0)
	v_pk_add_f32 v[26:27], v[28:29], 1.0 op_sel_hi:[1,0] neg_lo:[1,0] neg_hi:[1,0]
	s_nop 0
	v_fma_f32 v2, v26, v32, v28
	v_add_f32_e32 v9, 1.0, v5
	v_cmp_gt_f32_e32 vcc, s83, v2
	v_rcp_f32_e32 v33, v9
	s_nop 0
	v_cndmask_b32_e64 v9, 0, 32, vcc
	v_ldexp_f32 v2, v2, v9
	v_log_f32_e32 v2, v2
	v_fma_f32 v36, v27, v33, v29
	v_pk_mul_f32 v[4:5], v[4:5], v[32:33]
	v_mul_f32_e32 v9, 0x3f317217, v2
	v_fma_f32 v9, v2, s90, -v9
	v_fmac_f32_e32 v9, 0x3377d1cf, v2
	v_fmac_f32_e32 v9, 0x3f317217, v2
	v_cmp_lt_f32_e64 s[10:11], |v2|, s91
	v_pk_mul_f32 v[4:5], v[26:27], v[4:5]
	s_nop 0
	v_cndmask_b32_e64 v2, v2, v9, s[10:11]
	v_cndmask_b32_e32 v9, 0, v226, vcc
	v_sub_f32_e32 v2, v2, v9
	v_cmp_gt_f32_e32 vcc, s83, v36
	v_add_f32_e32 v9, 0, v2
	s_nop 0
	v_cndmask_b32_e64 v2, 0, 32, vcc
	v_ldexp_f32 v2, v36, v2
	v_log_f32_e32 v2, v2
	s_nop 0
	v_mul_f32_e32 v32, 0x3f317217, v2
	v_fma_f32 v32, v2, s90, -v32
	v_fmac_f32_e32 v32, 0x3377d1cf, v2
	v_fmac_f32_e32 v32, 0x3f317217, v2
	v_cmp_lt_f32_e64 s[10:11], |v2|, s91
	s_nop 1
	v_cndmask_b32_e64 v2, v2, v32, s[10:11]
	v_cndmask_b32_e32 v32, 0, v226, vcc
	v_sub_f32_e32 v2, v2, v32
	v_add_f32_e32 v2, 0, v2
	v_mul_f32_e32 v32, 0x3fb8aa3b, v9
	v_mul_f32_e32 v33, 0x3fb8aa3b, v2
	v_exp_f32_e32 v32, v32
	v_exp_f32_e32 v33, v33
	s_nop 0
	v_pk_mul_f32 v[32:33], v[34:35], v[32:33]
	s_nop 0
	v_cvt_pk_bf16_f32 v32, v32, v33
	global_store_dword v[62:63], v32, off
	v_mul_f32_e32 v32, 0xbfb8aa3b, v9
	v_mul_f32_e32 v33, 0xbfb8aa3b, v2
	v_exp_f32_e32 v32, v32
	v_exp_f32_e32 v33, v33
	s_nop 0
	v_pk_mul_f32 v[32:33], v[4:5], v[32:33]
	s_nop 0
	v_cvt_pk_bf16_f32 v32, v32, v33
; __device__ __forceinline__ float bflo(unsigned w) { return __uint_as_float(w << 16); }
; __device__ __forceinline__ float bfhi(unsigned w) { return __uint_as_float(w & 0xffff0000u); }
; __device__ __forceinline__ unsigned pk2(float lo, float hi) { return pg8::cvt_pk_bf16(lo, hi); }
; __device__ __forceinline__ float siluf(float x) { return x * __builtin_amdgcn_rcpf(1.0f + __expf(-x)); }
; __device__ __forceinline__ void hgrn_prep_phase(const bf16* z, const float* lbv, bf16* hq, float* dd, int tid, int G) {
;     ...
;             for (int tau = 0; tau < 32; ++tau) { const unsigned q2 = *(const unsigned*)(zq + (size_t)tau * ZP), f2 = *(const unsigned*)(zf + (size_t)tau * ZP);
;                 const float xf0 = fminf(fmaxf(bflo(f2), -30.f), 30.f), xf1 = fminf(fmaxf(bfhi(f2), -30.f), 30.f);
;                 const float e0 = __expf(-xf0), r0 = __builtin_amdgcn_rcpf(1.0f + e0), e1 = __expf(-xf1), r1 = __builtin_amdgcn_rcpf(1.0f + e1);
;                 const float f0 = lb0 + om0 * r0, f1 = lb1 + om1 * r1, k0v = om0 * (e0 * r0), k1v = om1 * (e1 * r1);
;                 bc0 += __logf(f0); bc1 += __logf(f1); kk0[tau] = k0v; kk1[tau] = k1v; bv0[tau] = bc0; bv1[tau] = bc1;
;                 *(unsigned*)(QT + tile + tau * 128 + kp) = pk2(siluf(bflo(q2)) * __expf(bc0), siluf(bfhi(q2)) * __expf(bc1));
;                 *(unsigned*)(KT + tile + tau * 128 + kp) = pk2(k0v * __expf(-bc0), k1v * __expf(-bc1)); }
	global_store_dword v[64:65], v32, off
	global_load_dword v164, v[210:211], off
	global_load_dword v165, v[210:211], off offset:1024
	v_lshl_add_u64 v[210:211], v[210:211], 0, v[230:231]
	v_add_co_u32_e32 v32, vcc, s92, v30
	s_nop 1
	v_addc_co_u32_e32 v33, vcc, 0, v31, vcc
	v_mov_b32_e32 v37, v166
	s_nop 0
	v_mov_b32_e32 v32, v167
	v_lshlrev_b32_e32 v33, 16, v32
	v_max_f32_e32 v33, v33, v33
	v_and_b32_e32 v32, 0xffff0000, v32
	v_med3_f32 v33, v33, s89, v225
	v_max_f32_e32 v32, v32, v32
	v_med3_f32 v35, v32, s89, v225
	v_mul_f32_e32 v32, 0xbfb8aa3b, v33
	v_exp_f32_e32 v32, v32
	s_nop 0
	v_add_f32_e32 v33, 1.0, v32
	v_rcp_f32_e32 v34, v33
	v_mul_f32_e32 v33, 0xbfb8aa3b, v35
	v_exp_f32_e32 v33, v33
	v_fma_f32 v36, v26, v34, v28
	v_cmp_gt_f32_e32 vcc, s83, v36
	v_add_f32_e32 v35, 1.0, v33
	v_rcp_f32_e32 v35, v35
	v_cndmask_b32_e64 v39, 0, 32, vcc
	v_ldexp_f32 v36, v36, v39
	v_log_f32_e32 v36, v36
	v_fma_f32 v38, v27, v35, v29
	v_pk_mul_f32 v[32:33], v[32:33], v[34:35]
	v_mul_f32_e32 v39, 0x3f317217, v36
	v_fma_f32 v39, v36, s90, -v39
	v_fmac_f32_e32 v39, 0x3377d1cf, v36
	v_fmac_f32_e32 v39, 0x3f317217, v36
	v_cmp_lt_f32_e64 s[10:11], |v36|, s91
	v_pk_mul_f32 v[32:33], v[26:27], v[32:33]
	s_nop 0
	v_cndmask_b32_e64 v36, v36, v39, s[10:11]
	v_cndmask_b32_e32 v39, 0, v226, vcc
	v_sub_f32_e32 v36, v36, v39
	v_cmp_gt_f32_e32 vcc, s83, v38
	v_add_f32_e32 v97, v9, v36
	s_nop 0
	v_cndmask_b32_e64 v36, 0, 32, vcc
	v_ldexp_f32 v36, v38, v36
	v_log_f32_e32 v36, v36
	s_nop 0
	v_mul_f32_e32 v38, 0x3f317217, v36
	v_fma_f32 v38, v36, s90, -v38
	v_fmac_f32_e32 v38, 0x3377d1cf, v36
	v_fmac_f32_e32 v38, 0x3f317217, v36
	v_cmp_lt_f32_e64 s[10:11], |v36|, s91
	s_nop 1
	v_cndmask_b32_e64 v36, v36, v38, s[10:11]
	v_cndmask_b32_e32 v38, 0, v226, vcc
	v_sub_f32_e32 v36, v36, v38
	v_add_f32_e32 v96, v2, v36
	v_lshlrev_b32_e32 v36, 16, v37
	v_and_b32_e32 v37, 0xffff0000, v37
	v_mul_f32_e32 v40, 0xbfb8aa3b, v36
	v_mul_f32_e32 v41, 0xbfb8aa3b, v37
	v_exp_f32_e32 v40, v40
	v_exp_f32_e32 v41, v41
	v_mul_f32_e32 v38, 0x3fb8aa3b, v97
	v_mul_f32_e32 v39, 0x3fb8aa3b, v96
	v_add_f32_e32 v40, 1.0, v40
	v_add_f32_e32 v41, 1.0, v41
	v_rcp_f32_e32 v40, v40
	v_rcp_f32_e32 v41, v41
	v_exp_f32_e32 v38, v38
	v_exp_f32_e32 v39, v39
	v_pk_mul_f32 v[36:37], v[40:41], v[36:37]
	s_nop 0
	v_pk_mul_f32 v[36:37], v[36:37], v[38:39]
	s_nop 0
	v_cvt_pk_bf16_f32 v36, v36, v37
	global_store_dword v[62:63], v36, off offset:256
	v_mul_f32_e32 v36, 0xbfb8aa3b, v97
	v_mul_f32_e32 v37, 0xbfb8aa3b, v96
	v_exp_f32_e32 v36, v36
	v_exp_f32_e32 v37, v37
	s_nop 0
	v_pk_mul_f32 v[34:35], v[32:33], v[36:37]
	s_nop 0
	v_cvt_pk_bf16_f32 v34, v34, v35
	global_store_dword v[64:65], v34, off offset:256
	global_load_dword v166, v[210:211], off
	global_load_dword v167, v[210:211], off offset:1024
	v_lshl_add_u64 v[210:211], v[210:211], 0, v[230:231]
	v_add_co_u32_e32 v34, vcc, s0, v30
	s_mov_b32 s0, 0x10000
	s_nop 0
	v_addc_co_u32_e32 v35, vcc, 0, v31, vcc
	v_mov_b32_e32 v39, v168
	s_nop 0
	v_mov_b32_e32 v34, v169
	v_lshlrev_b32_e32 v35, 16, v34
	v_max_f32_e32 v35, v35, v35
	v_and_b32_e32 v34, 0xffff0000, v34
	v_med3_f32 v35, v35, s89, v225
	v_max_f32_e32 v34, v34, v34
	v_med3_f32 v37, v34, s89, v225
	v_mul_f32_e32 v34, 0xbfb8aa3b, v35
	v_exp_f32_e32 v34, v34
	s_nop 0
	v_add_f32_e32 v35, 1.0, v34
	v_rcp_f32_e32 v36, v35
	v_mul_f32_e32 v35, 0xbfb8aa3b, v37
	v_exp_f32_e32 v35, v35
	v_fma_f32 v38, v26, v36, v28
	v_cmp_gt_f32_e32 vcc, s83, v38
	v_add_f32_e32 v37, 1.0, v35
	v_rcp_f32_e32 v37, v37
	v_cndmask_b32_e64 v41, 0, 32, vcc
	v_ldexp_f32 v38, v38, v41
	v_log_f32_e32 v38, v38
	v_fma_f32 v40, v27, v37, v29
	v_pk_mul_f32 v[34:35], v[34:35], v[36:37]
	v_mul_f32_e32 v41, 0x3f317217, v38
	v_fma_f32 v41, v38, s90, -v41
	v_fmac_f32_e32 v41, 0x3377d1cf, v38
	v_fmac_f32_e32 v41, 0x3f317217, v38
	v_cmp_lt_f32_e64 s[10:11], |v38|, s91
	v_pk_mul_f32 v[34:35], v[26:27], v[34:35]
	s_nop 0
	v_cndmask_b32_e64 v38, v38, v41, s[10:11]
	v_cndmask_b32_e32 v41, 0, v226, vcc
	v_sub_f32_e32 v38, v38, v41
	v_cmp_gt_f32_e32 vcc, s83, v40
	v_add_f32_e32 v99, v97, v38
	s_nop 0
	v_cndmask_b32_e64 v38, 0, 32, vcc
	v_ldexp_f32 v38, v40, v38
	v_log_f32_e32 v38, v38
	s_nop 0
	v_mul_f32_e32 v40, 0x3f317217, v38
	v_fma_f32 v40, v38, s90, -v40
	v_fmac_f32_e32 v40, 0x3377d1cf, v38
	v_fmac_f32_e32 v40, 0x3f317217, v38
	v_cmp_lt_f32_e64 s[10:11], |v38|, s91
	s_nop 1
	v_cndmask_b32_e64 v38, v38, v40, s[10:11]
	v_cndmask_b32_e32 v40, 0, v226, vcc
	v_sub_f32_e32 v38, v38, v40
	v_add_f32_e32 v98, v96, v38
	v_lshlrev_b32_e32 v38, 16, v39
	v_and_b32_e32 v39, 0xffff0000, v39
	v_mul_f32_e32 v42, 0xbfb8aa3b, v38
	v_mul_f32_e32 v43, 0xbfb8aa3b, v39
	v_exp_f32_e32 v42, v42
	v_exp_f32_e32 v43, v43
	v_mul_f32_e32 v40, 0x3fb8aa3b, v99
	v_mul_f32_e32 v41, 0x3fb8aa3b, v98
	v_add_f32_e32 v42, 1.0, v42
	v_add_f32_e32 v43, 1.0, v43
	v_rcp_f32_e32 v42, v42
	v_rcp_f32_e32 v43, v43
	v_exp_f32_e32 v40, v40
	v_exp_f32_e32 v41, v41
	v_pk_mul_f32 v[38:39], v[42:43], v[38:39]
	s_nop 0
	v_pk_mul_f32 v[38:39], v[38:39], v[40:41]
	s_nop 0
	v_cvt_pk_bf16_f32 v38, v38, v39
	global_store_dword v[62:63], v38, off offset:512
	v_mul_f32_e32 v38, 0xbfb8aa3b, v99
	v_mul_f32_e32 v39, 0xbfb8aa3b, v98
	v_exp_f32_e32 v38, v38
	v_exp_f32_e32 v39, v39
	s_nop 0
	v_pk_mul_f32 v[36:37], v[34:35], v[38:39]
	s_nop 0
	v_cvt_pk_bf16_f32 v36, v36, v37
	global_store_dword v[64:65], v36, off offset:512
	global_load_dword v168, v[210:211], off
	global_load_dword v169, v[210:211], off offset:1024
	v_lshl_add_u64 v[210:211], v[210:211], 0, v[230:231]
	v_add_co_u32_e32 v36, vcc, s0, v30
	s_mov_b32 s0, 0x11000
	s_nop 0
	v_addc_co_u32_e32 v37, vcc, 0, v31, vcc
	v_add_co_u32_e32 v38, vcc, s0, v30
; __device__ __forceinline__ float bflo(unsigned w) { return __uint_as_float(w << 16); }
; __device__ __forceinline__ float bfhi(unsigned w) { return __uint_as_float(w & 0xffff0000u); }
; __device__ __forceinline__ unsigned pk2(float lo, float hi) { return pg8::cvt_pk_bf16(lo, hi); }
; __device__ __forceinline__ float siluf(float x) { return x * __builtin_amdgcn_rcpf(1.0f + __expf(-x)); }
; __device__ __forceinline__ void hgrn_prep_phase(const bf16* z, const float* lbv, bf16* hq, float* dd, int tid, int G) {
;     ...
;             for (int tau = 0; tau < 32; ++tau) { const unsigned q2 = *(const unsigned*)(zq + (size_t)tau * ZP), f2 = *(const unsigned*)(zf + (size_t)tau * ZP);
;                 const float xf0 = fminf(fmaxf(bflo(f2), -30.f), 30.f), xf1 = fminf(fmaxf(bfhi(f2), -30.f), 30.f);
;                 const float e0 = __expf(-xf0), r0 = __builtin_amdgcn_rcpf(1.0f + e0), e1 = __expf(-xf1), r1 = __builtin_amdgcn_rcpf(1.0f + e1);
;                 const float f0 = lb0 + om0 * r0, f1 = lb1 + om1 * r1, k0v = om0 * (e0 * r0), k1v = om1 * (e1 * r1);
;                 bc0 += __logf(f0); bc1 += __logf(f1); kk0[tau] = k0v; kk1[tau] = k1v; bv0[tau] = bc0; bv1[tau] = bc1;
;                 *(unsigned*)(QT + tile + tau * 128 + kp) = pk2(siluf(bflo(q2)) * __expf(bc0), siluf(bfhi(q2)) * __expf(bc1));
;                 *(unsigned*)(KT + tile + tau * 128 + kp) = pk2(k0v * __expf(-bc0), k1v * __expf(-bc1)); }
	v_mov_b32_e32 v36, v170
	s_nop 0
	v_addc_co_u32_e32 v39, vcc, 0, v31, vcc
	v_mov_b32_e32 v37, v171
	s_mov_b32 s0, 0x16000
	v_lshlrev_b32_e32 v38, 16, v37
	v_max_f32_e32 v38, v38, v38
	v_med3_f32 v38, v38, s89, v225
	v_mul_f32_e32 v38, 0xbfb8aa3b, v38
	v_exp_f32_e32 v38, v38
	v_and_b32_e32 v37, 0xffff0000, v37
	v_max_f32_e32 v37, v37, v37
	v_med3_f32 v37, v37, s89, v225
	v_add_f32_e32 v39, 1.0, v38
	v_mul_f32_e32 v37, 0xbfb8aa3b, v37
	v_rcp_f32_e32 v40, v39
	v_exp_f32_e32 v39, v37
	s_nop 0
	v_add_f32_e32 v37, 1.0, v39
	v_rcp_f32_e32 v41, v37
	v_fma_f32 v37, v26, v40, v28
	v_cmp_gt_f32_e32 vcc, s83, v37
	v_fma_f32 v42, v27, v41, v29
	s_nop 0
	v_cndmask_b32_e64 v43, 0, 32, vcc
	v_ldexp_f32 v37, v37, v43
	v_log_f32_e32 v37, v37
	s_nop 0
	v_mul_f32_e32 v43, 0x3f317217, v37
	v_fma_f32 v43, v37, s90, -v43
	v_fmac_f32_e32 v43, 0x3377d1cf, v37
	v_fmac_f32_e32 v43, 0x3f317217, v37
	v_cmp_lt_f32_e64 s[10:11], |v37|, s91
	s_nop 1
	v_cndmask_b32_e64 v37, v37, v43, s[10:11]
	v_cndmask_b32_e32 v43, 0, v226, vcc
	v_sub_f32_e32 v37, v37, v43
	v_cmp_gt_f32_e32 vcc, s83, v42
	v_add_f32_e32 v101, v99, v37
	v_and_b32_e32 v43, 0xffff0000, v36
	v_cndmask_b32_e64 v37, 0, 32, vcc
	v_ldexp_f32 v37, v42, v37
	v_log_f32_e32 v37, v37
	s_nop 0
	v_mul_f32_e32 v42, 0x3f317217, v37
	v_fma_f32 v42, v37, s90, -v42
	v_fmac_f32_e32 v42, 0x3377d1cf, v37
	v_fmac_f32_e32 v42, 0x3f317217, v37
	v_cmp_lt_f32_e64 s[10:11], |v37|, s91
	s_nop 1
	v_cndmask_b32_e64 v37, v37, v42, s[10:11]
	v_cndmask_b32_e32 v42, 0, v226, vcc
	v_sub_f32_e32 v37, v37, v42
	v_add_f32_e32 v100, v98, v37
	v_lshlrev_b32_e32 v42, 16, v36
	v_mul_f32_e32 v37, 0x3fb8aa3b, v101
	v_mul_f32_e32 v36, 0x3fb8aa3b, v100
	v_exp_f32_e32 v44, v37
	v_exp_f32_e32 v45, v36
	v_mul_f32_e32 v36, 0xbfb8aa3b, v42
	v_mul_f32_e32 v37, 0xbfb8aa3b, v43
	v_exp_f32_e32 v36, v36
	v_exp_f32_e32 v37, v37
	v_add_f32_e32 v36, 1.0, v36
	v_add_f32_e32 v37, 1.0, v37
	v_rcp_f32_e32 v36, v36
	v_rcp_f32_e32 v37, v37
	s_nop 0
	v_pk_mul_f32 v[36:37], v[36:37], v[42:43]
	s_nop 0
	v_pk_mul_f32 v[36:37], v[36:37], v[44:45]
	s_nop 0
	v_cvt_pk_bf16_f32 v36, v36, v37
	global_store_dword v[62:63], v36, off offset:768
	v_mul_f32_e32 v36, 0xbfb8aa3b, v101
	v_exp_f32_e32 v42, v36
	v_mul_f32_e32 v36, 0xbfb8aa3b, v100
	v_exp_f32_e32 v43, v36
	v_pk_mul_f32 v[36:37], v[38:39], v[40:41]
	s_nop 0
	v_pk_mul_f32 v[36:37], v[26:27], v[36:37]
	s_nop 0
	v_pk_mul_f32 v[38:39], v[36:37], v[42:43]
	s_nop 0
	v_cvt_pk_bf16_f32 v38, v38, v39
	global_store_dword v[64:65], v38, off offset:768
	global_load_dword v170, v[210:211], off
	global_load_dword v171, v[210:211], off offset:1024
	v_lshl_add_u64 v[210:211], v[210:211], 0, v[230:231]
	v_add_co_u32_e32 v38, vcc, s0, v30
	s_mov_b32 s0, 0x1c000
	s_nop 0
	v_addc_co_u32_e32 v39, vcc, 0, v31, vcc
	v_mov_b32_e32 v43, v186
	s_nop 0
	v_mov_b32_e32 v38, v187
	v_lshlrev_b32_e32 v39, 16, v38
	v_max_f32_e32 v39, v39, v39
	v_and_b32_e32 v38, 0xffff0000, v38
	v_med3_f32 v39, v39, s89, v225
	v_max_f32_e32 v38, v38, v38
	v_med3_f32 v41, v38, s89, v225
	v_mul_f32_e32 v38, 0xbfb8aa3b, v39
	v_exp_f32_e32 v38, v38
	s_nop 0
	v_add_f32_e32 v39, 1.0, v38
	v_rcp_f32_e32 v40, v39
	v_mul_f32_e32 v39, 0xbfb8aa3b, v41
	v_exp_f32_e32 v39, v39
	v_fma_f32 v42, v26, v40, v28
	v_cmp_gt_f32_e32 vcc, s83, v42
	v_add_f32_e32 v41, 1.0, v39
	v_rcp_f32_e32 v41, v41
	v_cndmask_b32_e64 v45, 0, 32, vcc
	v_ldexp_f32 v42, v42, v45
	v_log_f32_e32 v42, v42
	v_fma_f32 v44, v27, v41, v29
	v_pk_mul_f32 v[38:39], v[38:39], v[40:41]
	v_mul_f32_e32 v45, 0x3f317217, v42
	v_fma_f32 v45, v42, s90, -v45
	v_fmac_f32_e32 v45, 0x3377d1cf, v42
	v_fmac_f32_e32 v45, 0x3f317217, v42
	v_cmp_lt_f32_e64 s[10:11], |v42|, s91
	v_pk_mul_f32 v[38:39], v[26:27], v[38:39]
	s_nop 0
	v_cndmask_b32_e64 v42, v42, v45, s[10:11]
	v_cndmask_b32_e32 v45, 0, v226, vcc
	v_sub_f32_e32 v42, v42, v45
	v_cmp_gt_f32_e32 vcc, s83, v44
	v_add_f32_e32 v103, v101, v42
	s_nop 0
	v_cndmask_b32_e64 v42, 0, 32, vcc
	v_ldexp_f32 v42, v44, v42
	v_log_f32_e32 v42, v42
	s_nop 0
	v_mul_f32_e32 v44, 0x3f317217, v42
	v_fma_f32 v44, v42, s90, -v44
	v_fmac_f32_e32 v44, 0x3377d1cf, v42
	v_fmac_f32_e32 v44, 0x3f317217, v42
	v_cmp_lt_f32_e64 s[10:11], |v42|, s91
	s_nop 1
	v_cndmask_b32_e64 v42, v42, v44, s[10:11]
	v_cndmask_b32_e32 v44, 0, v226, vcc
	v_sub_f32_e32 v42, v42, v44
	v_add_f32_e32 v102, v100, v42
	v_lshlrev_b32_e32 v42, 16, v43
	v_and_b32_e32 v43, 0xffff0000, v43
	v_mul_f32_e32 v46, 0xbfb8aa3b, v42
	v_mul_f32_e32 v47, 0xbfb8aa3b, v43
	v_exp_f32_e32 v46, v46
	v_exp_f32_e32 v47, v47
	v_mul_f32_e32 v44, 0x3fb8aa3b, v103
	v_mul_f32_e32 v45, 0x3fb8aa3b, v102
	v_add_f32_e32 v46, 1.0, v46
	v_add_f32_e32 v47, 1.0, v47
	v_rcp_f32_e32 v46, v46
	v_rcp_f32_e32 v47, v47
	v_exp_f32_e32 v44, v44
	v_exp_f32_e32 v45, v45
	v_pk_mul_f32 v[42:43], v[46:47], v[42:43]
	s_nop 0
	v_pk_mul_f32 v[42:43], v[42:43], v[44:45]
	s_nop 0
	v_cvt_pk_bf16_f32 v42, v42, v43
	global_store_dword v[62:63], v42, off offset:1024
	v_mul_f32_e32 v42, 0xbfb8aa3b, v103
	v_mul_f32_e32 v43, 0xbfb8aa3b, v102
	v_exp_f32_e32 v42, v42
	v_exp_f32_e32 v43, v43
	s_nop 0
	v_pk_mul_f32 v[40:41], v[38:39], v[42:43]
	s_nop 0
	v_cvt_pk_bf16_f32 v40, v40, v41
	global_store_dword v[64:65], v40, off offset:1024
	global_load_dword v186, v[210:211], off
	global_load_dword v187, v[210:211], off offset:1024
	v_lshl_add_u64 v[210:211], v[210:211], 0, v[230:231]
	v_add_co_u32_e32 v40, vcc, s0, v30
	s_mov_b32 s0, 0x21000
	s_nop 0
	v_addc_co_u32_e32 v41, vcc, 0, v31, vcc
	v_mov_b32_e32 v45, v188
	s_nop 0
	v_mov_b32_e32 v40, v189
	v_lshlrev_b32_e32 v41, 16, v40
	v_max_f32_e32 v41, v41, v41
	v_and_b32_e32 v40, 0xffff0000, v40
	v_med3_f32 v41, v41, s89, v225
	v_max_f32_e32 v40, v40, v40
; __device__ __forceinline__ float bflo(unsigned w) { return __uint_as_float(w << 16); }
; __device__ __forceinline__ float bfhi(unsigned w) { return __uint_as_float(w & 0xffff0000u); }
; __device__ __forceinline__ unsigned pk2(float lo, float hi) { return pg8::cvt_pk_bf16(lo, hi); }
; __device__ __forceinline__ float siluf(float x) { return x * __builtin_amdgcn_rcpf(1.0f + __expf(-x)); }
; __device__ __forceinline__ void hgrn_prep_phase(const bf16* z, const float* lbv, bf16* hq, float* dd, int tid, int G) {
;     ...
;             for (int tau = 0; tau < 32; ++tau) { const unsigned q2 = *(const unsigned*)(zq + (size_t)tau * ZP), f2 = *(const unsigned*)(zf + (size_t)tau * ZP);
;                 const float xf0 = fminf(fmaxf(bflo(f2), -30.f), 30.f), xf1 = fminf(fmaxf(bfhi(f2), -30.f), 30.f);
;                 const float e0 = __expf(-xf0), r0 = __builtin_amdgcn_rcpf(1.0f + e0), e1 = __expf(-xf1), r1 = __builtin_amdgcn_rcpf(1.0f + e1);
;                 const float f0 = lb0 + om0 * r0, f1 = lb1 + om1 * r1, k0v = om0 * (e0 * r0), k1v = om1 * (e1 * r1);
;                 bc0 += __logf(f0); bc1 += __logf(f1); kk0[tau] = k0v; kk1[tau] = k1v; bv0[tau] = bc0; bv1[tau] = bc1;
;                 *(unsigned*)(QT + tile + tau * 128 + kp) = pk2(siluf(bflo(q2)) * __expf(bc0), siluf(bfhi(q2)) * __expf(bc1));
;                 *(unsigned*)(KT + tile + tau * 128 + kp) = pk2(k0v * __expf(-bc0), k1v * __expf(-bc1)); }
	v_med3_f32 v43, v40, s89, v225
	v_mul_f32_e32 v40, 0xbfb8aa3b, v41
	v_exp_f32_e32 v40, v40
	s_nop 0
	v_add_f32_e32 v41, 1.0, v40
	v_rcp_f32_e32 v42, v41
	v_mul_f32_e32 v41, 0xbfb8aa3b, v43
	v_exp_f32_e32 v41, v41
	v_fma_f32 v44, v26, v42, v28
	v_cmp_gt_f32_e32 vcc, s83, v44
	v_add_f32_e32 v43, 1.0, v41
	v_rcp_f32_e32 v43, v43
	v_cndmask_b32_e64 v47, 0, 32, vcc
	v_ldexp_f32 v44, v44, v47
	v_log_f32_e32 v44, v44
	v_fma_f32 v46, v27, v43, v29
	v_pk_mul_f32 v[40:41], v[40:41], v[42:43]
	v_mul_f32_e32 v47, 0x3f317217, v44
	v_fma_f32 v47, v44, s90, -v47
	v_fmac_f32_e32 v47, 0x3377d1cf, v44
	v_fmac_f32_e32 v47, 0x3f317217, v44
	v_cmp_lt_f32_e64 s[10:11], |v44|, s91
	v_pk_mul_f32 v[40:41], v[26:27], v[40:41]
	s_nop 0
	v_cndmask_b32_e64 v44, v44, v47, s[10:11]
	v_cndmask_b32_e32 v47, 0, v226, vcc
	v_sub_f32_e32 v44, v44, v47
	v_cmp_gt_f32_e32 vcc, s83, v46
	v_add_f32_e32 v105, v103, v44
	s_nop 0
	v_cndmask_b32_e64 v44, 0, 32, vcc
	v_ldexp_f32 v44, v46, v44
	v_log_f32_e32 v44, v44
	s_nop 0
	v_mul_f32_e32 v46, 0x3f317217, v44
	v_fma_f32 v46, v44, s90, -v46
	v_fmac_f32_e32 v46, 0x3377d1cf, v44
	v_fmac_f32_e32 v46, 0x3f317217, v44
	v_cmp_lt_f32_e64 s[10:11], |v44|, s91
	s_nop 1
	v_cndmask_b32_e64 v44, v44, v46, s[10:11]
	v_cndmask_b32_e32 v46, 0, v226, vcc
	v_sub_f32_e32 v44, v44, v46
	v_add_f32_e32 v104, v102, v44
	v_lshlrev_b32_e32 v44, 16, v45
	v_and_b32_e32 v45, 0xffff0000, v45
	v_mul_f32_e32 v48, 0xbfb8aa3b, v44
	v_mul_f32_e32 v49, 0xbfb8aa3b, v45
	v_exp_f32_e32 v48, v48
	v_exp_f32_e32 v49, v49
	v_mul_f32_e32 v46, 0x3fb8aa3b, v105
	v_mul_f32_e32 v47, 0x3fb8aa3b, v104
	v_add_f32_e32 v48, 1.0, v48
	v_add_f32_e32 v49, 1.0, v49
	v_rcp_f32_e32 v48, v48
	v_rcp_f32_e32 v49, v49
	v_exp_f32_e32 v46, v46
	v_exp_f32_e32 v47, v47
	v_pk_mul_f32 v[44:45], v[48:49], v[44:45]
	s_nop 0
	v_pk_mul_f32 v[44:45], v[44:45], v[46:47]
	s_nop 0
	v_cvt_pk_bf16_f32 v44, v44, v45
	global_store_dword v[62:63], v44, off offset:1280
	v_mul_f32_e32 v44, 0xbfb8aa3b, v105
	v_mul_f32_e32 v45, 0xbfb8aa3b, v104
	v_exp_f32_e32 v44, v44
	v_exp_f32_e32 v45, v45
	s_nop 0
	v_pk_mul_f32 v[42:43], v[40:41], v[44:45]
	s_nop 0
	v_cvt_pk_bf16_f32 v42, v42, v43
	global_store_dword v[64:65], v42, off offset:1280
	global_load_dword v188, v[210:211], off
	global_load_dword v189, v[210:211], off offset:1024
	v_lshl_add_u64 v[210:211], v[210:211], 0, v[230:231]
	v_add_co_u32_e32 v42, vcc, s0, v30
	s_mov_b32 s0, 0x22000
	s_nop 0
	v_addc_co_u32_e32 v43, vcc, 0, v31, vcc
	v_add_co_u32_e32 v44, vcc, s0, v30
	v_mov_b32_e32 v42, v190
	s_nop 0
	v_addc_co_u32_e32 v45, vcc, 0, v31, vcc
	v_mov_b32_e32 v43, v191
	s_mov_b32 s0, 0x27000
	v_lshlrev_b32_e32 v44, 16, v43
	v_max_f32_e32 v44, v44, v44
	v_med3_f32 v44, v44, s89, v225
	v_mul_f32_e32 v44, 0xbfb8aa3b, v44
	v_exp_f32_e32 v44, v44
	v_and_b32_e32 v43, 0xffff0000, v43
	v_max_f32_e32 v43, v43, v43
	v_med3_f32 v43, v43, s89, v225
	v_add_f32_e32 v45, 1.0, v44
	v_mul_f32_e32 v43, 0xbfb8aa3b, v43
	v_rcp_f32_e32 v46, v45
	v_exp_f32_e32 v45, v43
	s_nop 0
	v_add_f32_e32 v43, 1.0, v45
	v_rcp_f32_e32 v47, v43
	v_fma_f32 v43, v26, v46, v28
	v_cmp_gt_f32_e32 vcc, s83, v43
	v_fma_f32 v48, v27, v47, v29
	s_nop 0
	v_cndmask_b32_e64 v49, 0, 32, vcc
	v_ldexp_f32 v43, v43, v49
	v_log_f32_e32 v43, v43
	s_nop 0
	v_mul_f32_e32 v49, 0x3f317217, v43
	v_fma_f32 v49, v43, s90, -v49
	v_fmac_f32_e32 v49, 0x3377d1cf, v43
	v_fmac_f32_e32 v49, 0x3f317217, v43
	v_cmp_lt_f32_e64 s[10:11], |v43|, s91
	s_nop 1
	v_cndmask_b32_e64 v43, v43, v49, s[10:11]
	v_cndmask_b32_e32 v49, 0, v226, vcc
	v_sub_f32_e32 v43, v43, v49
	v_cmp_gt_f32_e32 vcc, s83, v48
	v_add_f32_e32 v107, v105, v43
	v_and_b32_e32 v49, 0xffff0000, v42
	v_cndmask_b32_e64 v43, 0, 32, vcc
	v_ldexp_f32 v43, v48, v43
	v_log_f32_e32 v43, v43
	s_nop 0
	v_mul_f32_e32 v48, 0x3f317217, v43
	v_fma_f32 v48, v43, s90, -v48
	v_fmac_f32_e32 v48, 0x3377d1cf, v43
	v_fmac_f32_e32 v48, 0x3f317217, v43
	v_cmp_lt_f32_e64 s[10:11], |v43|, s91
	s_nop 1
	v_cndmask_b32_e64 v43, v43, v48, s[10:11]
	v_cndmask_b32_e32 v48, 0, v226, vcc
	v_sub_f32_e32 v43, v43, v48
	v_add_f32_e32 v106, v104, v43
	v_lshlrev_b32_e32 v48, 16, v42
	v_mul_f32_e32 v43, 0x3fb8aa3b, v107
	v_mul_f32_e32 v42, 0x3fb8aa3b, v106
	v_exp_f32_e32 v50, v43
	v_exp_f32_e32 v51, v42
	v_mul_f32_e32 v42, 0xbfb8aa3b, v48
	v_mul_f32_e32 v43, 0xbfb8aa3b, v49
	v_exp_f32_e32 v42, v42
	v_exp_f32_e32 v43, v43
	v_add_f32_e32 v42, 1.0, v42
	v_add_f32_e32 v43, 1.0, v43
	v_rcp_f32_e32 v42, v42
	v_rcp_f32_e32 v43, v43
	s_nop 0
	v_pk_mul_f32 v[42:43], v[42:43], v[48:49]
	s_nop 0
	v_pk_mul_f32 v[42:43], v[42:43], v[50:51]
	s_nop 0
	v_cvt_pk_bf16_f32 v42, v42, v43
	global_store_dword v[62:63], v42, off offset:1536
	v_mul_f32_e32 v42, 0xbfb8aa3b, v107
	v_exp_f32_e32 v48, v42
	v_mul_f32_e32 v42, 0xbfb8aa3b, v106
	v_exp_f32_e32 v49, v42
	v_pk_mul_f32 v[42:43], v[44:45], v[46:47]
	s_nop 0
	v_pk_mul_f32 v[42:43], v[26:27], v[42:43]
	s_nop 0
	v_pk_mul_f32 v[44:45], v[42:43], v[48:49]
	s_nop 0
	v_cvt_pk_bf16_f32 v44, v44, v45
	global_store_dword v[64:65], v44, off offset:1536
	global_load_dword v190, v[210:211], off
	global_load_dword v191, v[210:211], off offset:1024
	v_lshl_add_u64 v[210:211], v[210:211], 0, v[230:231]
	v_add_co_u32_e32 v44, vcc, s0, v30
	s_mov_b32 s0, 0x2d000
	s_nop 0
	v_addc_co_u32_e32 v45, vcc, 0, v31, vcc
	v_mov_b32_e32 v49, v192
	s_nop 0
	v_mov_b32_e32 v44, v193
	v_lshlrev_b32_e32 v45, 16, v44
	v_max_f32_e32 v45, v45, v45
	v_and_b32_e32 v44, 0xffff0000, v44
	v_med3_f32 v45, v45, s89, v225
	v_max_f32_e32 v44, v44, v44
	v_med3_f32 v47, v44, s89, v225
	v_mul_f32_e32 v44, 0xbfb8aa3b, v45
	v_exp_f32_e32 v44, v44
	s_nop 0
	v_add_f32_e32 v45, 1.0, v44
	v_rcp_f32_e32 v46, v45
	v_mul_f32_e32 v45, 0xbfb8aa3b, v47
; __device__ __forceinline__ float bflo(unsigned w) { return __uint_as_float(w << 16); }
; __device__ __forceinline__ float bfhi(unsigned w) { return __uint_as_float(w & 0xffff0000u); }
; __device__ __forceinline__ unsigned pk2(float lo, float hi) { return pg8::cvt_pk_bf16(lo, hi); }
; __device__ __forceinline__ float siluf(float x) { return x * __builtin_amdgcn_rcpf(1.0f + __expf(-x)); }
; __device__ __forceinline__ void hgrn_prep_phase(const bf16* z, const float* lbv, bf16* hq, float* dd, int tid, int G) {
;     ...
;             for (int tau = 0; tau < 32; ++tau) { const unsigned q2 = *(const unsigned*)(zq + (size_t)tau * ZP), f2 = *(const unsigned*)(zf + (size_t)tau * ZP);
;                 const float xf0 = fminf(fmaxf(bflo(f2), -30.f), 30.f), xf1 = fminf(fmaxf(bfhi(f2), -30.f), 30.f);
;                 const float e0 = __expf(-xf0), r0 = __builtin_amdgcn_rcpf(1.0f + e0), e1 = __expf(-xf1), r1 = __builtin_amdgcn_rcpf(1.0f + e1);
;                 const float f0 = lb0 + om0 * r0, f1 = lb1 + om1 * r1, k0v = om0 * (e0 * r0), k1v = om1 * (e1 * r1);
;                 bc0 += __logf(f0); bc1 += __logf(f1); kk0[tau] = k0v; kk1[tau] = k1v; bv0[tau] = bc0; bv1[tau] = bc1;
;                 *(unsigned*)(QT + tile + tau * 128 + kp) = pk2(siluf(bflo(q2)) * __expf(bc0), siluf(bfhi(q2)) * __expf(bc1));
;                 *(unsigned*)(KT + tile + tau * 128 + kp) = pk2(k0v * __expf(-bc0), k1v * __expf(-bc1)); }
	v_exp_f32_e32 v45, v45
	v_fma_f32 v48, v26, v46, v28
	v_cmp_gt_f32_e32 vcc, s83, v48
	v_add_f32_e32 v47, 1.0, v45
	v_rcp_f32_e32 v47, v47
	v_cndmask_b32_e64 v51, 0, 32, vcc
	v_ldexp_f32 v48, v48, v51
	v_log_f32_e32 v48, v48
	v_fma_f32 v50, v27, v47, v29
	v_pk_mul_f32 v[44:45], v[44:45], v[46:47]
	v_mul_f32_e32 v51, 0x3f317217, v48
	v_fma_f32 v51, v48, s90, -v51
	v_fmac_f32_e32 v51, 0x3377d1cf, v48
	v_fmac_f32_e32 v51, 0x3f317217, v48
	v_cmp_lt_f32_e64 s[10:11], |v48|, s91
	v_pk_mul_f32 v[44:45], v[26:27], v[44:45]
	s_nop 0
	v_cndmask_b32_e64 v48, v48, v51, s[10:11]
	v_cndmask_b32_e32 v51, 0, v226, vcc
	v_sub_f32_e32 v48, v48, v51
	v_cmp_gt_f32_e32 vcc, s83, v50
	v_add_f32_e32 v109, v107, v48
	s_nop 0
	v_cndmask_b32_e64 v48, 0, 32, vcc
	v_ldexp_f32 v48, v50, v48
	v_log_f32_e32 v48, v48
	s_nop 0
	v_mul_f32_e32 v50, 0x3f317217, v48
	v_fma_f32 v50, v48, s90, -v50
	v_fmac_f32_e32 v50, 0x3377d1cf, v48
	v_fmac_f32_e32 v50, 0x3f317217, v48
	v_cmp_lt_f32_e64 s[10:11], |v48|, s91
	s_nop 1
	v_cndmask_b32_e64 v48, v48, v50, s[10:11]
	v_cndmask_b32_e32 v50, 0, v226, vcc
	v_sub_f32_e32 v48, v48, v50
	v_add_f32_e32 v108, v106, v48
	v_lshlrev_b32_e32 v48, 16, v49
	v_and_b32_e32 v49, 0xffff0000, v49
	v_mul_f32_e32 v52, 0xbfb8aa3b, v48
	v_mul_f32_e32 v53, 0xbfb8aa3b, v49
	v_exp_f32_e32 v52, v52
	v_exp_f32_e32 v53, v53
	v_mul_f32_e32 v50, 0x3fb8aa3b, v109
	v_mul_f32_e32 v51, 0x3fb8aa3b, v108
	v_add_f32_e32 v52, 1.0, v52
	v_add_f32_e32 v53, 1.0, v53
	v_rcp_f32_e32 v52, v52
	v_rcp_f32_e32 v53, v53
	v_exp_f32_e32 v50, v50
	v_exp_f32_e32 v51, v51
	v_pk_mul_f32 v[48:49], v[52:53], v[48:49]
	s_nop 0
	v_pk_mul_f32 v[48:49], v[48:49], v[50:51]
	s_nop 0
	v_cvt_pk_bf16_f32 v48, v48, v49
	global_store_dword v[62:63], v48, off offset:1792
	v_mul_f32_e32 v48, 0xbfb8aa3b, v109
	v_mul_f32_e32 v49, 0xbfb8aa3b, v108
	v_exp_f32_e32 v48, v48
	v_exp_f32_e32 v49, v49
	s_nop 0
	v_pk_mul_f32 v[46:47], v[44:45], v[48:49]
	s_nop 0
	v_cvt_pk_bf16_f32 v46, v46, v47
	global_store_dword v[64:65], v46, off offset:1792
	global_load_dword v192, v[210:211], off
	global_load_dword v193, v[210:211], off offset:1024
	v_lshl_add_u64 v[210:211], v[210:211], 0, v[230:231]
	v_add_co_u32_e32 v46, vcc, s0, v30
	s_mov_b32 s0, 0x32000
	s_nop 0
	v_addc_co_u32_e32 v47, vcc, 0, v31, vcc
	v_mov_b32_e32 v51, v194
	s_nop 0
	v_mov_b32_e32 v46, v195
	v_lshlrev_b32_e32 v47, 16, v46
	v_max_f32_e32 v47, v47, v47
	v_and_b32_e32 v46, 0xffff0000, v46
	v_med3_f32 v47, v47, s89, v225
	v_max_f32_e32 v46, v46, v46
	v_med3_f32 v49, v46, s89, v225
	v_mul_f32_e32 v46, 0xbfb8aa3b, v47
	v_exp_f32_e32 v46, v46
	s_nop 0
	v_add_f32_e32 v47, 1.0, v46
	v_rcp_f32_e32 v48, v47
	v_mul_f32_e32 v47, 0xbfb8aa3b, v49
	v_exp_f32_e32 v47, v47
	v_fma_f32 v50, v26, v48, v28
	v_cmp_gt_f32_e32 vcc, s83, v50
	v_add_f32_e32 v49, 1.0, v47
	v_rcp_f32_e32 v49, v49
	v_cndmask_b32_e64 v53, 0, 32, vcc
	v_ldexp_f32 v50, v50, v53
	v_log_f32_e32 v50, v50
	v_fma_f32 v52, v27, v49, v29
	v_pk_mul_f32 v[46:47], v[46:47], v[48:49]
	v_mul_f32_e32 v53, 0x3f317217, v50
	v_fma_f32 v53, v50, s90, -v53
	v_fmac_f32_e32 v53, 0x3377d1cf, v50
	v_fmac_f32_e32 v53, 0x3f317217, v50
	v_cmp_lt_f32_e64 s[10:11], |v50|, s91
	v_pk_mul_f32 v[46:47], v[26:27], v[46:47]
	s_nop 0
	v_cndmask_b32_e64 v50, v50, v53, s[10:11]
	v_cndmask_b32_e32 v53, 0, v226, vcc
	v_sub_f32_e32 v50, v50, v53
	v_cmp_gt_f32_e32 vcc, s83, v52
	v_add_f32_e32 v111, v109, v50
	s_nop 0
	v_cndmask_b32_e64 v50, 0, 32, vcc
	v_ldexp_f32 v50, v52, v50
	v_log_f32_e32 v50, v50
	s_nop 0
	v_mul_f32_e32 v52, 0x3f317217, v50
	v_fma_f32 v52, v50, s90, -v52
	v_fmac_f32_e32 v52, 0x3377d1cf, v50
	v_fmac_f32_e32 v52, 0x3f317217, v50
	v_cmp_lt_f32_e64 s[10:11], |v50|, s91
	s_nop 1
	v_cndmask_b32_e64 v50, v50, v52, s[10:11]
	v_cndmask_b32_e32 v52, 0, v226, vcc
	v_sub_f32_e32 v50, v50, v52
	v_add_f32_e32 v110, v108, v50
	v_lshlrev_b32_e32 v50, 16, v51
	v_and_b32_e32 v51, 0xffff0000, v51
	v_mul_f32_e32 v54, 0xbfb8aa3b, v50
	v_mul_f32_e32 v55, 0xbfb8aa3b, v51
	v_exp_f32_e32 v54, v54
	v_exp_f32_e32 v55, v55
	v_mul_f32_e32 v52, 0x3fb8aa3b, v111
	v_mul_f32_e32 v53, 0x3fb8aa3b, v110
	v_add_f32_e32 v54, 1.0, v54
	v_add_f32_e32 v55, 1.0, v55
	v_rcp_f32_e32 v54, v54
	v_rcp_f32_e32 v55, v55
	v_exp_f32_e32 v52, v52
	v_exp_f32_e32 v53, v53
	v_pk_mul_f32 v[50:51], v[54:55], v[50:51]
	s_nop 0
	v_pk_mul_f32 v[50:51], v[50:51], v[52:53]
	s_nop 0
	v_cvt_pk_bf16_f32 v50, v50, v51
	global_store_dword v[62:63], v50, off offset:2048
	v_mul_f32_e32 v50, 0xbfb8aa3b, v111
	v_mul_f32_e32 v51, 0xbfb8aa3b, v110
	v_exp_f32_e32 v50, v50
	v_exp_f32_e32 v51, v51
	s_nop 0
	v_pk_mul_f32 v[48:49], v[46:47], v[50:51]
	s_nop 0
	v_cvt_pk_bf16_f32 v48, v48, v49
	global_store_dword v[64:65], v48, off offset:2048
	global_load_dword v194, v[210:211], off
	global_load_dword v195, v[210:211], off offset:1024
	v_lshl_add_u64 v[210:211], v[210:211], 0, v[230:231]
	v_add_co_u32_e32 v48, vcc, s0, v30
	s_mov_b32 s0, 0x38000
	s_nop 0
	v_addc_co_u32_e32 v49, vcc, 0, v31, vcc
	v_mov_b32_e32 v53, v196
	s_nop 0
	v_mov_b32_e32 v48, v197
	v_lshlrev_b32_e32 v49, 16, v48
	v_max_f32_e32 v49, v49, v49
	v_and_b32_e32 v48, 0xffff0000, v48
	v_med3_f32 v49, v49, s89, v225
	v_max_f32_e32 v48, v48, v48
	v_med3_f32 v51, v48, s89, v225
	v_mul_f32_e32 v48, 0xbfb8aa3b, v49
	v_exp_f32_e32 v48, v48
	s_nop 0
	v_add_f32_e32 v49, 1.0, v48
	v_rcp_f32_e32 v50, v49
	v_mul_f32_e32 v49, 0xbfb8aa3b, v51
	v_exp_f32_e32 v49, v49
	v_fma_f32 v52, v26, v50, v28
	v_cmp_gt_f32_e32 vcc, s83, v52
	v_add_f32_e32 v51, 1.0, v49
	v_rcp_f32_e32 v51, v51
	v_cndmask_b32_e64 v55, 0, 32, vcc
	v_ldexp_f32 v52, v52, v55
	v_log_f32_e32 v52, v52
	v_fma_f32 v54, v27, v51, v29
	v_pk_mul_f32 v[48:49], v[48:49], v[50:51]
; __device__ __forceinline__ float bflo(unsigned w) { return __uint_as_float(w << 16); }
; __device__ __forceinline__ float bfhi(unsigned w) { return __uint_as_float(w & 0xffff0000u); }
; __device__ __forceinline__ unsigned pk2(float lo, float hi) { return pg8::cvt_pk_bf16(lo, hi); }
; __device__ __forceinline__ float siluf(float x) { return x * __builtin_amdgcn_rcpf(1.0f + __expf(-x)); }
; __device__ __forceinline__ void hgrn_prep_phase(const bf16* z, const float* lbv, bf16* hq, float* dd, int tid, int G) {
;     ...
;             for (int tau = 0; tau < 32; ++tau) { const unsigned q2 = *(const unsigned*)(zq + (size_t)tau * ZP), f2 = *(const unsigned*)(zf + (size_t)tau * ZP);
;                 const float xf0 = fminf(fmaxf(bflo(f2), -30.f), 30.f), xf1 = fminf(fmaxf(bfhi(f2), -30.f), 30.f);
;                 const float e0 = __expf(-xf0), r0 = __builtin_amdgcn_rcpf(1.0f + e0), e1 = __expf(-xf1), r1 = __builtin_amdgcn_rcpf(1.0f + e1);
;                 const float f0 = lb0 + om0 * r0, f1 = lb1 + om1 * r1, k0v = om0 * (e0 * r0), k1v = om1 * (e1 * r1);
;                 bc0 += __logf(f0); bc1 += __logf(f1); kk0[tau] = k0v; kk1[tau] = k1v; bv0[tau] = bc0; bv1[tau] = bc1;
;                 *(unsigned*)(QT + tile + tau * 128 + kp) = pk2(siluf(bflo(q2)) * __expf(bc0), siluf(bfhi(q2)) * __expf(bc1));
;                 *(unsigned*)(KT + tile + tau * 128 + kp) = pk2(k0v * __expf(-bc0), k1v * __expf(-bc1)); }
	v_mul_f32_e32 v55, 0x3f317217, v52
	v_fma_f32 v55, v52, s90, -v55
	v_fmac_f32_e32 v55, 0x3377d1cf, v52
	v_fmac_f32_e32 v55, 0x3f317217, v52
	v_cmp_lt_f32_e64 s[10:11], |v52|, s91
	v_pk_mul_f32 v[48:49], v[26:27], v[48:49]
	s_nop 0
	v_cndmask_b32_e64 v52, v52, v55, s[10:11]
	v_cndmask_b32_e32 v55, 0, v226, vcc
	v_sub_f32_e32 v52, v52, v55
	v_cmp_gt_f32_e32 vcc, s83, v54
	v_add_f32_e32 v113, v111, v52
	s_nop 0
	v_cndmask_b32_e64 v52, 0, 32, vcc
	v_ldexp_f32 v52, v54, v52
	v_log_f32_e32 v52, v52
	s_nop 0
	v_mul_f32_e32 v54, 0x3f317217, v52
	v_fma_f32 v54, v52, s90, -v54
	v_fmac_f32_e32 v54, 0x3377d1cf, v52
	v_fmac_f32_e32 v54, 0x3f317217, v52
	v_cmp_lt_f32_e64 s[10:11], |v52|, s91
	s_nop 1
	v_cndmask_b32_e64 v52, v52, v54, s[10:11]
	v_cndmask_b32_e32 v54, 0, v226, vcc
	v_sub_f32_e32 v52, v52, v54
	v_add_f32_e32 v112, v110, v52
	v_lshlrev_b32_e32 v52, 16, v53
	v_and_b32_e32 v53, 0xffff0000, v53
	v_mul_f32_e32 v56, 0xbfb8aa3b, v52
	v_mul_f32_e32 v57, 0xbfb8aa3b, v53
	v_exp_f32_e32 v56, v56
	v_exp_f32_e32 v57, v57
	v_mul_f32_e32 v54, 0x3fb8aa3b, v113
	v_mul_f32_e32 v55, 0x3fb8aa3b, v112
	v_add_f32_e32 v56, 1.0, v56
	v_add_f32_e32 v57, 1.0, v57
	v_rcp_f32_e32 v56, v56
	v_rcp_f32_e32 v57, v57
	v_exp_f32_e32 v54, v54
	v_exp_f32_e32 v55, v55
	v_pk_mul_f32 v[52:53], v[56:57], v[52:53]
	s_nop 0
	v_pk_mul_f32 v[52:53], v[52:53], v[54:55]
	s_nop 0
	v_cvt_pk_bf16_f32 v52, v52, v53
	global_store_dword v[62:63], v52, off offset:2304
	v_mul_f32_e32 v52, 0xbfb8aa3b, v113
	v_mul_f32_e32 v53, 0xbfb8aa3b, v112
	v_exp_f32_e32 v52, v52
	v_exp_f32_e32 v53, v53
	s_nop 0
	v_pk_mul_f32 v[50:51], v[48:49], v[52:53]
	s_nop 0
	v_cvt_pk_bf16_f32 v50, v50, v51
	global_store_dword v[64:65], v50, off offset:2304
	global_load_dword v196, v[210:211], off
	global_load_dword v197, v[210:211], off offset:1024
	v_lshl_add_u64 v[210:211], v[210:211], 0, v[230:231]
	v_add_co_u32_e32 v50, vcc, s0, v30
	s_mov_b32 s0, 0x3d000
	s_nop 0
	v_addc_co_u32_e32 v51, vcc, 0, v31, vcc
	v_mov_b32_e32 v55, v198
	s_nop 0
	v_mov_b32_e32 v50, v199
	v_lshlrev_b32_e32 v51, 16, v50
	v_max_f32_e32 v51, v51, v51
	v_and_b32_e32 v50, 0xffff0000, v50
	v_med3_f32 v51, v51, s89, v225
	v_max_f32_e32 v50, v50, v50
	v_med3_f32 v53, v50, s89, v225
	v_mul_f32_e32 v50, 0xbfb8aa3b, v51
	v_exp_f32_e32 v50, v50
	s_nop 0
	v_add_f32_e32 v51, 1.0, v50
	v_rcp_f32_e32 v52, v51
	v_mul_f32_e32 v51, 0xbfb8aa3b, v53
	v_exp_f32_e32 v51, v51
	v_fma_f32 v54, v26, v52, v28
	v_cmp_gt_f32_e32 vcc, s83, v54
	v_add_f32_e32 v53, 1.0, v51
	v_rcp_f32_e32 v53, v53
	v_cndmask_b32_e64 v57, 0, 32, vcc
	v_ldexp_f32 v54, v54, v57
	v_log_f32_e32 v54, v54
	v_fma_f32 v56, v27, v53, v29
	v_pk_mul_f32 v[50:51], v[50:51], v[52:53]
	v_mul_f32_e32 v57, 0x3f317217, v54
	v_fma_f32 v57, v54, s90, -v57
	v_fmac_f32_e32 v57, 0x3377d1cf, v54
	v_fmac_f32_e32 v57, 0x3f317217, v54
	v_cmp_lt_f32_e64 s[10:11], |v54|, s91
	v_pk_mul_f32 v[50:51], v[26:27], v[50:51]
	s_nop 0
	v_cndmask_b32_e64 v54, v54, v57, s[10:11]
	v_cndmask_b32_e32 v57, 0, v226, vcc
	v_sub_f32_e32 v54, v54, v57
	v_cmp_gt_f32_e32 vcc, s83, v56
	v_add_f32_e32 v115, v113, v54
	s_nop 0
	v_cndmask_b32_e64 v54, 0, 32, vcc
	v_ldexp_f32 v54, v56, v54
	v_log_f32_e32 v54, v54
	s_nop 0
	v_mul_f32_e32 v56, 0x3f317217, v54
	v_fma_f32 v56, v54, s90, -v56
	v_fmac_f32_e32 v56, 0x3377d1cf, v54
	v_fmac_f32_e32 v56, 0x3f317217, v54
	v_cmp_lt_f32_e64 s[10:11], |v54|, s91
	s_nop 1
	v_cndmask_b32_e64 v54, v54, v56, s[10:11]
	v_cndmask_b32_e32 v56, 0, v226, vcc
	v_sub_f32_e32 v54, v54, v56
	v_add_f32_e32 v114, v112, v54
	v_lshlrev_b32_e32 v54, 16, v55
	v_and_b32_e32 v55, 0xffff0000, v55
	v_mul_f32_e32 v58, 0xbfb8aa3b, v54
	v_mul_f32_e32 v59, 0xbfb8aa3b, v55
	v_exp_f32_e32 v58, v58
	v_exp_f32_e32 v59, v59
	v_mul_f32_e32 v56, 0x3fb8aa3b, v115
	v_mul_f32_e32 v57, 0x3fb8aa3b, v114
	v_add_f32_e32 v58, 1.0, v58
	v_add_f32_e32 v59, 1.0, v59
	v_rcp_f32_e32 v58, v58
	v_rcp_f32_e32 v59, v59
	v_exp_f32_e32 v56, v56
	v_exp_f32_e32 v57, v57
	v_pk_mul_f32 v[54:55], v[58:59], v[54:55]
	s_nop 0
	v_pk_mul_f32 v[54:55], v[54:55], v[56:57]
	s_nop 0
	v_cvt_pk_bf16_f32 v54, v54, v55
	global_store_dword v[62:63], v54, off offset:2560
	v_mul_f32_e32 v54, 0xbfb8aa3b, v115
	v_mul_f32_e32 v55, 0xbfb8aa3b, v114
	v_exp_f32_e32 v54, v54
	v_exp_f32_e32 v55, v55
	s_nop 0
	v_pk_mul_f32 v[52:53], v[50:51], v[54:55]
	s_nop 0
	v_cvt_pk_bf16_f32 v52, v52, v53
	global_store_dword v[64:65], v52, off offset:2560
	global_load_dword v198, v[210:211], off
	global_load_dword v199, v[210:211], off offset:1024
	v_lshl_add_u64 v[210:211], v[210:211], 0, v[230:231]
	v_add_co_u32_e32 v52, vcc, s0, v30
	s_mov_b32 s0, 0x3e000
	s_nop 0
	v_addc_co_u32_e32 v53, vcc, 0, v31, vcc
	v_mov_b32_e32 v57, v200
	v_add_co_u32_e32 v52, vcc, s0, v30
	s_mov_b32 s0, 0x43000
	s_nop 0
	v_addc_co_u32_e32 v53, vcc, 0, v31, vcc
	v_mov_b32_e32 v52, v201
	v_lshlrev_b32_e32 v53, 16, v52
	v_max_f32_e32 v53, v53, v53
	v_and_b32_e32 v52, 0xffff0000, v52
	v_med3_f32 v53, v53, s89, v225
	v_max_f32_e32 v52, v52, v52
	v_med3_f32 v55, v52, s89, v225
	v_mul_f32_e32 v52, 0xbfb8aa3b, v53
	v_exp_f32_e32 v52, v52
	s_nop 0
	v_add_f32_e32 v53, 1.0, v52
	v_rcp_f32_e32 v54, v53
	v_mul_f32_e32 v53, 0xbfb8aa3b, v55
	v_exp_f32_e32 v53, v53
	v_fma_f32 v56, v26, v54, v28
	v_cmp_gt_f32_e32 vcc, s83, v56
	v_add_f32_e32 v55, 1.0, v53
	v_rcp_f32_e32 v55, v55
	v_cndmask_b32_e64 v59, 0, 32, vcc
	v_ldexp_f32 v56, v56, v59
	v_log_f32_e32 v56, v56
	v_fma_f32 v58, v27, v55, v29
	v_pk_mul_f32 v[52:53], v[52:53], v[54:55]
	v_mul_f32_e32 v59, 0x3f317217, v56
	v_fma_f32 v59, v56, s90, -v59
	v_fmac_f32_e32 v59, 0x3377d1cf, v56
	v_fmac_f32_e32 v59, 0x3f317217, v56
	v_cmp_lt_f32_e64 s[10:11], |v56|, s91
; __device__ __forceinline__ float bflo(unsigned w) { return __uint_as_float(w << 16); }
; __device__ __forceinline__ float bfhi(unsigned w) { return __uint_as_float(w & 0xffff0000u); }
; __device__ __forceinline__ unsigned pk2(float lo, float hi) { return pg8::cvt_pk_bf16(lo, hi); }
; __device__ __forceinline__ float siluf(float x) { return x * __builtin_amdgcn_rcpf(1.0f + __expf(-x)); }
; __device__ __forceinline__ void hgrn_prep_phase(const bf16* z, const float* lbv, bf16* hq, float* dd, int tid, int G) {
;     ...
;             for (int tau = 0; tau < 32; ++tau) { const unsigned q2 = *(const unsigned*)(zq + (size_t)tau * ZP), f2 = *(const unsigned*)(zf + (size_t)tau * ZP);
;                 const float xf0 = fminf(fmaxf(bflo(f2), -30.f), 30.f), xf1 = fminf(fmaxf(bfhi(f2), -30.f), 30.f);
;                 const float e0 = __expf(-xf0), r0 = __builtin_amdgcn_rcpf(1.0f + e0), e1 = __expf(-xf1), r1 = __builtin_amdgcn_rcpf(1.0f + e1);
;                 const float f0 = lb0 + om0 * r0, f1 = lb1 + om1 * r1, k0v = om0 * (e0 * r0), k1v = om1 * (e1 * r1);
;                 bc0 += __logf(f0); bc1 += __logf(f1); kk0[tau] = k0v; kk1[tau] = k1v; bv0[tau] = bc0; bv1[tau] = bc1;
;                 *(unsigned*)(QT + tile + tau * 128 + kp) = pk2(siluf(bflo(q2)) * __expf(bc0), siluf(bfhi(q2)) * __expf(bc1));
;                 *(unsigned*)(KT + tile + tau * 128 + kp) = pk2(k0v * __expf(-bc0), k1v * __expf(-bc1)); }
	v_pk_mul_f32 v[52:53], v[26:27], v[52:53]
	s_nop 0
	v_cndmask_b32_e64 v56, v56, v59, s[10:11]
	v_cndmask_b32_e32 v59, 0, v226, vcc
	v_sub_f32_e32 v56, v56, v59
	v_cmp_gt_f32_e32 vcc, s83, v58
	v_add_f32_e32 v117, v115, v56
	s_nop 0
	v_cndmask_b32_e64 v56, 0, 32, vcc
	v_ldexp_f32 v56, v58, v56
	v_log_f32_e32 v56, v56
	s_nop 0
	v_mul_f32_e32 v58, 0x3f317217, v56
	v_fma_f32 v58, v56, s90, -v58
	v_fmac_f32_e32 v58, 0x3377d1cf, v56
	v_fmac_f32_e32 v58, 0x3f317217, v56
	v_cmp_lt_f32_e64 s[10:11], |v56|, s91
	s_nop 1
	v_cndmask_b32_e64 v56, v56, v58, s[10:11]
	v_cndmask_b32_e32 v58, 0, v226, vcc
	v_sub_f32_e32 v56, v56, v58
	v_add_f32_e32 v116, v114, v56
	v_lshlrev_b32_e32 v56, 16, v57
	v_and_b32_e32 v57, 0xffff0000, v57
	v_mul_f32_e32 v60, 0xbfb8aa3b, v56
	v_mul_f32_e32 v61, 0xbfb8aa3b, v57
	v_exp_f32_e32 v60, v60
	v_exp_f32_e32 v61, v61
	v_mul_f32_e32 v58, 0x3fb8aa3b, v117
	v_mul_f32_e32 v59, 0x3fb8aa3b, v116
	v_add_f32_e32 v60, 1.0, v60
	v_add_f32_e32 v61, 1.0, v61
	v_rcp_f32_e32 v60, v60
	v_rcp_f32_e32 v61, v61
	v_exp_f32_e32 v58, v58
	v_exp_f32_e32 v59, v59
	v_pk_mul_f32 v[56:57], v[60:61], v[56:57]
	s_nop 0
	v_pk_mul_f32 v[56:57], v[56:57], v[58:59]
	s_nop 0
	v_cvt_pk_bf16_f32 v56, v56, v57
	global_store_dword v[62:63], v56, off offset:2816
	v_mul_f32_e32 v56, 0xbfb8aa3b, v117
	v_mul_f32_e32 v57, 0xbfb8aa3b, v116
	v_exp_f32_e32 v56, v56
	v_exp_f32_e32 v57, v57
	s_nop 0
	v_pk_mul_f32 v[54:55], v[52:53], v[56:57]
	s_nop 0
	v_cvt_pk_bf16_f32 v54, v54, v55
	global_store_dword v[64:65], v54, off offset:2816
	global_load_dword v200, v[210:211], off
	global_load_dword v201, v[210:211], off offset:1024
	v_lshl_add_u64 v[210:211], v[210:211], 0, v[230:231]
	v_add_co_u32_e32 v54, vcc, s0, v30
	s_mov_b32 s0, 0x49000
	s_nop 0
	v_addc_co_u32_e32 v55, vcc, 0, v31, vcc
	v_mov_b32_e32 v59, v202
	s_nop 0
	v_mov_b32_e32 v54, v203
	v_lshlrev_b32_e32 v55, 16, v54
	v_max_f32_e32 v55, v55, v55
	v_and_b32_e32 v54, 0xffff0000, v54
	v_med3_f32 v55, v55, s89, v225
	v_max_f32_e32 v54, v54, v54
	v_med3_f32 v57, v54, s89, v225
	v_mul_f32_e32 v54, 0xbfb8aa3b, v55
	v_exp_f32_e32 v54, v54
	s_nop 0
	v_add_f32_e32 v55, 1.0, v54
	v_rcp_f32_e32 v56, v55
	v_mul_f32_e32 v55, 0xbfb8aa3b, v57
	v_exp_f32_e32 v55, v55
	v_fma_f32 v58, v26, v56, v28
	v_cmp_gt_f32_e32 vcc, s83, v58
	v_add_f32_e32 v57, 1.0, v55
	v_rcp_f32_e32 v57, v57
	v_cndmask_b32_e64 v61, 0, 32, vcc
	v_ldexp_f32 v58, v58, v61
	v_log_f32_e32 v58, v58
	v_fma_f32 v60, v27, v57, v29
	v_pk_mul_f32 v[54:55], v[54:55], v[56:57]
	v_mul_f32_e32 v61, 0x3f317217, v58
	v_fma_f32 v61, v58, s90, -v61
	v_fmac_f32_e32 v61, 0x3377d1cf, v58
	v_fmac_f32_e32 v61, 0x3f317217, v58
	v_cmp_lt_f32_e64 s[10:11], |v58|, s91
	v_pk_mul_f32 v[54:55], v[26:27], v[54:55]
	s_nop 0
	v_cndmask_b32_e64 v58, v58, v61, s[10:11]
	v_cndmask_b32_e32 v61, 0, v226, vcc
	v_sub_f32_e32 v58, v58, v61
	v_cmp_gt_f32_e32 vcc, s83, v60
	v_add_f32_e32 v119, v117, v58
	s_nop 0
	v_cndmask_b32_e64 v58, 0, 32, vcc
	v_ldexp_f32 v58, v60, v58
	v_log_f32_e32 v58, v58
	s_nop 0
	v_mul_f32_e32 v60, 0x3f317217, v58
	v_fma_f32 v60, v58, s90, -v60
	v_fmac_f32_e32 v60, 0x3377d1cf, v58
	v_fmac_f32_e32 v60, 0x3f317217, v58
	v_cmp_lt_f32_e64 s[10:11], |v58|, s91
	s_nop 1
	v_cndmask_b32_e64 v58, v58, v60, s[10:11]
	v_cndmask_b32_e32 v60, 0, v226, vcc
	v_sub_f32_e32 v58, v58, v60
	v_add_f32_e32 v118, v116, v58
	v_lshlrev_b32_e32 v58, 16, v59
	v_and_b32_e32 v59, 0xffff0000, v59
	v_mul_f32_e32 v66, 0xbfb8aa3b, v58
	v_mul_f32_e32 v67, 0xbfb8aa3b, v59
	v_exp_f32_e32 v66, v66
	v_exp_f32_e32 v67, v67
	v_mul_f32_e32 v60, 0x3fb8aa3b, v119
	v_mul_f32_e32 v61, 0x3fb8aa3b, v118
	v_add_f32_e32 v66, 1.0, v66
	v_add_f32_e32 v67, 1.0, v67
	v_rcp_f32_e32 v66, v66
	v_rcp_f32_e32 v67, v67
	v_exp_f32_e32 v60, v60
	v_exp_f32_e32 v61, v61
	v_pk_mul_f32 v[58:59], v[66:67], v[58:59]
	s_nop 0
	v_pk_mul_f32 v[58:59], v[58:59], v[60:61]
	s_nop 0
	v_cvt_pk_bf16_f32 v58, v58, v59
	global_store_dword v[62:63], v58, off offset:3072
	v_mul_f32_e32 v58, 0xbfb8aa3b, v119
	v_mul_f32_e32 v59, 0xbfb8aa3b, v118
	v_exp_f32_e32 v58, v58
	v_exp_f32_e32 v59, v59
	s_nop 0
	v_pk_mul_f32 v[56:57], v[54:55], v[58:59]
	s_nop 0
	v_cvt_pk_bf16_f32 v56, v56, v57
	global_store_dword v[64:65], v56, off offset:3072
	global_load_dword v202, v[210:211], off
	global_load_dword v203, v[210:211], off offset:1024
	v_lshl_add_u64 v[210:211], v[210:211], 0, v[230:231]
	v_add_co_u32_e32 v56, vcc, s0, v30
	s_mov_b32 s0, 0x4e000
	s_nop 0
	v_addc_co_u32_e32 v57, vcc, 0, v31, vcc
	v_mov_b32_e32 v61, v204
	s_nop 0
	v_mov_b32_e32 v56, v205
	v_lshlrev_b32_e32 v57, 16, v56
	v_max_f32_e32 v57, v57, v57
	v_and_b32_e32 v56, 0xffff0000, v56
	v_med3_f32 v57, v57, s89, v225
	v_max_f32_e32 v56, v56, v56
	v_med3_f32 v59, v56, s89, v225
	v_mul_f32_e32 v56, 0xbfb8aa3b, v57
	v_exp_f32_e32 v56, v56
	s_nop 0
	v_add_f32_e32 v57, 1.0, v56
	v_rcp_f32_e32 v58, v57
	v_mul_f32_e32 v57, 0xbfb8aa3b, v59
	v_exp_f32_e32 v57, v57
	v_fma_f32 v60, v26, v58, v28
	v_cmp_gt_f32_e32 vcc, s83, v60
	v_add_f32_e32 v59, 1.0, v57
	v_rcp_f32_e32 v59, v59
	v_cndmask_b32_e64 v67, 0, 32, vcc
	v_ldexp_f32 v60, v60, v67
	v_log_f32_e32 v60, v60
	v_fma_f32 v66, v27, v59, v29
	v_pk_mul_f32 v[56:57], v[56:57], v[58:59]
	v_mul_f32_e32 v67, 0x3f317217, v60
	v_fma_f32 v67, v60, s90, -v67
	v_fmac_f32_e32 v67, 0x3377d1cf, v60
	v_fmac_f32_e32 v67, 0x3f317217, v60
	v_cmp_lt_f32_e64 s[10:11], |v60|, s91
	v_pk_mul_f32 v[56:57], v[26:27], v[56:57]
	s_nop 0
	v_cndmask_b32_e64 v60, v60, v67, s[10:11]
	v_cndmask_b32_e32 v67, 0, v226, vcc
	v_sub_f32_e32 v60, v60, v67
	v_cmp_gt_f32_e32 vcc, s83, v66
	v_add_f32_e32 v121, v119, v60
	s_nop 0
	v_cndmask_b32_e64 v60, 0, 32, vcc
	v_ldexp_f32 v60, v66, v60
; __device__ __forceinline__ float bflo(unsigned w) { return __uint_as_float(w << 16); }
; __device__ __forceinline__ float bfhi(unsigned w) { return __uint_as_float(w & 0xffff0000u); }
; __device__ __forceinline__ unsigned pk2(float lo, float hi) { return pg8::cvt_pk_bf16(lo, hi); }
; __device__ __forceinline__ float siluf(float x) { return x * __builtin_amdgcn_rcpf(1.0f + __expf(-x)); }
; __device__ __forceinline__ void hgrn_prep_phase(const bf16* z, const float* lbv, bf16* hq, float* dd, int tid, int G) {
;     ...
;             for (int tau = 0; tau < 32; ++tau) { const unsigned q2 = *(const unsigned*)(zq + (size_t)tau * ZP), f2 = *(const unsigned*)(zf + (size_t)tau * ZP);
;                 const float xf0 = fminf(fmaxf(bflo(f2), -30.f), 30.f), xf1 = fminf(fmaxf(bfhi(f2), -30.f), 30.f);
;                 const float e0 = __expf(-xf0), r0 = __builtin_amdgcn_rcpf(1.0f + e0), e1 = __expf(-xf1), r1 = __builtin_amdgcn_rcpf(1.0f + e1);
;                 const float f0 = lb0 + om0 * r0, f1 = lb1 + om1 * r1, k0v = om0 * (e0 * r0), k1v = om1 * (e1 * r1);
;                 bc0 += __logf(f0); bc1 += __logf(f1); kk0[tau] = k0v; kk1[tau] = k1v; bv0[tau] = bc0; bv1[tau] = bc1;
;                 *(unsigned*)(QT + tile + tau * 128 + kp) = pk2(siluf(bflo(q2)) * __expf(bc0), siluf(bfhi(q2)) * __expf(bc1));
;                 *(unsigned*)(KT + tile + tau * 128 + kp) = pk2(k0v * __expf(-bc0), k1v * __expf(-bc1)); }
	v_log_f32_e32 v60, v60
	s_nop 0
	v_mul_f32_e32 v66, 0x3f317217, v60
	v_fma_f32 v66, v60, s90, -v66
	v_fmac_f32_e32 v66, 0x3377d1cf, v60
	v_fmac_f32_e32 v66, 0x3f317217, v60
	v_cmp_lt_f32_e64 s[10:11], |v60|, s91
	s_nop 1
	v_cndmask_b32_e64 v60, v60, v66, s[10:11]
	v_cndmask_b32_e32 v66, 0, v226, vcc
	v_sub_f32_e32 v60, v60, v66
	v_add_f32_e32 v120, v118, v60
	v_lshlrev_b32_e32 v60, 16, v61
	v_and_b32_e32 v61, 0xffff0000, v61
	v_mul_f32_e32 v68, 0xbfb8aa3b, v60
	v_mul_f32_e32 v69, 0xbfb8aa3b, v61
	v_exp_f32_e32 v68, v68
	v_exp_f32_e32 v69, v69
	v_mul_f32_e32 v66, 0x3fb8aa3b, v121
	v_mul_f32_e32 v67, 0x3fb8aa3b, v120
	v_add_f32_e32 v68, 1.0, v68
	v_add_f32_e32 v69, 1.0, v69
	v_rcp_f32_e32 v68, v68
	v_rcp_f32_e32 v69, v69
	v_exp_f32_e32 v66, v66
	v_exp_f32_e32 v67, v67
	v_pk_mul_f32 v[60:61], v[68:69], v[60:61]
	s_nop 0
	v_pk_mul_f32 v[60:61], v[60:61], v[66:67]
	s_nop 0
	v_cvt_pk_bf16_f32 v60, v60, v61
	global_store_dword v[62:63], v60, off offset:3328
	v_mul_f32_e32 v60, 0xbfb8aa3b, v121
	v_mul_f32_e32 v61, 0xbfb8aa3b, v120
	v_exp_f32_e32 v60, v60
	v_exp_f32_e32 v61, v61
	s_nop 0
	v_pk_mul_f32 v[58:59], v[56:57], v[60:61]
	s_nop 0
	v_cvt_pk_bf16_f32 v58, v58, v59
	global_store_dword v[64:65], v58, off offset:3328
	global_load_dword v204, v[210:211], off
	global_load_dword v205, v[210:211], off offset:1024
	v_lshl_add_u64 v[210:211], v[210:211], 0, v[230:231]
	v_add_co_u32_e32 v58, vcc, s0, v30
	s_mov_b32 s0, 0x4f000
	s_nop 0
	v_addc_co_u32_e32 v59, vcc, 0, v31, vcc
	v_add_co_u32_e32 v60, vcc, s0, v30
	v_mov_b32_e32 v58, v206
	s_nop 0
	v_addc_co_u32_e32 v61, vcc, 0, v31, vcc
	v_mov_b32_e32 v59, v207
	s_mov_b32 s0, 0x54000
	v_lshlrev_b32_e32 v60, 16, v59
	v_max_f32_e32 v60, v60, v60
	v_med3_f32 v60, v60, s89, v225
	v_mul_f32_e32 v60, 0xbfb8aa3b, v60
	v_exp_f32_e32 v60, v60
	v_and_b32_e32 v59, 0xffff0000, v59
	v_max_f32_e32 v59, v59, v59
	v_med3_f32 v59, v59, s89, v225
	v_add_f32_e32 v61, 1.0, v60
	v_mul_f32_e32 v59, 0xbfb8aa3b, v59
	v_rcp_f32_e32 v66, v61
	v_exp_f32_e32 v61, v59
	s_nop 0
	v_add_f32_e32 v59, 1.0, v61
	v_rcp_f32_e32 v67, v59
	v_fma_f32 v59, v26, v66, v28
	v_cmp_gt_f32_e32 vcc, s83, v59
	v_fma_f32 v68, v27, v67, v29
	s_nop 0
	v_cndmask_b32_e64 v69, 0, 32, vcc
	v_ldexp_f32 v59, v59, v69
	v_log_f32_e32 v59, v59
	s_nop 0
	v_mul_f32_e32 v69, 0x3f317217, v59
	v_fma_f32 v69, v59, s90, -v69
	v_fmac_f32_e32 v69, 0x3377d1cf, v59
	v_fmac_f32_e32 v69, 0x3f317217, v59
	v_cmp_lt_f32_e64 s[10:11], |v59|, s91
	s_nop 1
	v_cndmask_b32_e64 v59, v59, v69, s[10:11]
	v_cndmask_b32_e32 v69, 0, v226, vcc
	v_sub_f32_e32 v59, v59, v69
	v_cmp_gt_f32_e32 vcc, s83, v68
	v_add_f32_e32 v123, v121, v59
	v_and_b32_e32 v69, 0xffff0000, v58
	v_cndmask_b32_e64 v59, 0, 32, vcc
	v_ldexp_f32 v59, v68, v59
	v_log_f32_e32 v59, v59
	s_nop 0
	v_mul_f32_e32 v68, 0x3f317217, v59
	v_fma_f32 v68, v59, s90, -v68
	v_fmac_f32_e32 v68, 0x3377d1cf, v59
	v_fmac_f32_e32 v68, 0x3f317217, v59
	v_cmp_lt_f32_e64 s[10:11], |v59|, s91
	s_nop 1
	v_cndmask_b32_e64 v59, v59, v68, s[10:11]
	v_cndmask_b32_e32 v68, 0, v226, vcc
	v_sub_f32_e32 v59, v59, v68
	v_add_f32_e32 v122, v120, v59
	v_lshlrev_b32_e32 v68, 16, v58
	v_mul_f32_e32 v59, 0x3fb8aa3b, v123
	v_mul_f32_e32 v58, 0x3fb8aa3b, v122
	v_exp_f32_e32 v70, v59
	v_exp_f32_e32 v71, v58
	v_mul_f32_e32 v58, 0xbfb8aa3b, v68
	v_mul_f32_e32 v59, 0xbfb8aa3b, v69
	v_exp_f32_e32 v58, v58
	v_exp_f32_e32 v59, v59
	v_add_f32_e32 v58, 1.0, v58
	v_add_f32_e32 v59, 1.0, v59
	v_rcp_f32_e32 v58, v58
	v_rcp_f32_e32 v59, v59
	s_nop 0
	v_pk_mul_f32 v[58:59], v[58:59], v[68:69]
	s_nop 0
	v_pk_mul_f32 v[58:59], v[58:59], v[70:71]
	s_nop 0
	v_cvt_pk_bf16_f32 v58, v58, v59
	global_store_dword v[62:63], v58, off offset:3584
	v_mul_f32_e32 v58, 0xbfb8aa3b, v123
	v_exp_f32_e32 v68, v58
	v_mul_f32_e32 v58, 0xbfb8aa3b, v122
	v_exp_f32_e32 v69, v58
	v_pk_mul_f32 v[58:59], v[60:61], v[66:67]
	s_nop 0
	v_pk_mul_f32 v[58:59], v[26:27], v[58:59]
	s_nop 0
	v_pk_mul_f32 v[60:61], v[58:59], v[68:69]
	s_nop 0
	v_cvt_pk_bf16_f32 v60, v60, v61
	global_store_dword v[64:65], v60, off offset:3584
	global_load_dword v206, v[210:211], off
	global_load_dword v207, v[210:211], off offset:1024
	v_lshl_add_u64 v[210:211], v[210:211], 0, v[230:231]
	v_add_co_u32_e32 v60, vcc, s0, v30
	s_mov_b32 s0, 0x5a000
	s_nop 0
	v_addc_co_u32_e32 v61, vcc, 0, v31, vcc
	v_mov_b32_e32 v69, v208
	s_nop 0
	v_mov_b32_e32 v60, v209
	v_lshlrev_b32_e32 v61, 16, v60
	v_max_f32_e32 v61, v61, v61
	v_and_b32_e32 v60, 0xffff0000, v60
	v_med3_f32 v61, v61, s89, v225
	v_max_f32_e32 v60, v60, v60
	v_med3_f32 v67, v60, s89, v225
	v_mul_f32_e32 v60, 0xbfb8aa3b, v61
	v_exp_f32_e32 v60, v60
	s_nop 0
	v_add_f32_e32 v61, 1.0, v60
	v_rcp_f32_e32 v66, v61
	v_mul_f32_e32 v61, 0xbfb8aa3b, v67
	v_exp_f32_e32 v61, v61
	v_fma_f32 v68, v26, v66, v28
	v_cmp_gt_f32_e32 vcc, s83, v68
	v_add_f32_e32 v67, 1.0, v61
	v_rcp_f32_e32 v67, v67
	v_cndmask_b32_e64 v71, 0, 32, vcc
	v_ldexp_f32 v68, v68, v71
	v_log_f32_e32 v68, v68
	v_fma_f32 v70, v27, v67, v29
	v_pk_mul_f32 v[60:61], v[60:61], v[66:67]
	v_mul_f32_e32 v71, 0x3f317217, v68
	v_fma_f32 v71, v68, s90, -v71
	v_fmac_f32_e32 v71, 0x3377d1cf, v68
	v_fmac_f32_e32 v71, 0x3f317217, v68
	v_cmp_lt_f32_e64 s[10:11], |v68|, s91
	v_pk_mul_f32 v[60:61], v[26:27], v[60:61]
	s_nop 0
	v_cndmask_b32_e64 v68, v68, v71, s[10:11]
	v_cndmask_b32_e32 v71, 0, v226, vcc
	v_sub_f32_e32 v68, v68, v71
	v_cmp_gt_f32_e32 vcc, s83, v70
	v_add_f32_e32 v125, v123, v68
	s_nop 0
	v_cndmask_b32_e64 v68, 0, 32, vcc
	v_ldexp_f32 v68, v70, v68
	v_log_f32_e32 v68, v68
	s_nop 0
	v_mul_f32_e32 v70, 0x3f317217, v68
	v_fma_f32 v70, v68, s90, -v70
	v_fmac_f32_e32 v70, 0x3377d1cf, v68
	v_fmac_f32_e32 v70, 0x3f317217, v68
	v_cmp_lt_f32_e64 s[10:11], |v68|, s91
	s_nop 1
	v_cndmask_b32_e64 v68, v68, v70, s[10:11]
	v_cndmask_b32_e32 v70, 0, v226, vcc
	v_sub_f32_e32 v68, v68, v70
	v_add_f32_e32 v124, v122, v68
	v_lshlrev_b32_e32 v68, 16, v69
	v_and_b32_e32 v69, 0xffff0000, v69
	v_mul_f32_e32 v72, 0xbfb8aa3b, v68
	v_mul_f32_e32 v73, 0xbfb8aa3b, v69
	v_exp_f32_e32 v72, v72
	v_exp_f32_e32 v73, v73
	v_mul_f32_e32 v70, 0x3fb8aa3b, v125
	v_mul_f32_e32 v71, 0x3fb8aa3b, v124
	v_add_f32_e32 v72, 1.0, v72
	v_add_f32_e32 v73, 1.0, v73
	v_rcp_f32_e32 v72, v72
	v_rcp_f32_e32 v73, v73
	v_exp_f32_e32 v70, v70
	v_exp_f32_e32 v71, v71
	v_pk_mul_f32 v[68:69], v[72:73], v[68:69]
	s_nop 0
	v_pk_mul_f32 v[68:69], v[68:69], v[70:71]
	s_nop 0
	v_cvt_pk_bf16_f32 v68, v68, v69
	global_store_dword v[62:63], v68, off offset:3840
	v_mul_f32_e32 v68, 0xbfb8aa3b, v125
	v_mul_f32_e32 v69, 0xbfb8aa3b, v124
	v_exp_f32_e32 v68, v68
	v_exp_f32_e32 v69, v69
	s_nop 0
	v_pk_mul_f32 v[66:67], v[60:61], v[68:69]
	s_nop 0
	v_cvt_pk_bf16_f32 v66, v66, v67
	global_store_dword v[64:65], v66, off offset:3840
	global_load_dword v208, v[210:211], off
	global_load_dword v209, v[210:211], off offset:1024
	v_lshl_add_u64 v[210:211], v[210:211], 0, v[230:231]
	v_add_co_u32_e32 v66, vcc, s0, v30
	s_mov_b32 s0, 0x5f000
	s_nop 0
	v_addc_co_u32_e32 v67, vcc, 0, v31, vcc
	s_waitcnt vmcnt(60)
; __device__ __forceinline__ float bflo(unsigned w) { return __uint_as_float(w << 16); }
; __device__ __forceinline__ float bfhi(unsigned w) { return __uint_as_float(w & 0xffff0000u); }
; __device__ __forceinline__ unsigned pk2(float lo, float hi) { return pg8::cvt_pk_bf16(lo, hi); }
; __device__ __forceinline__ float siluf(float x) { return x * __builtin_amdgcn_rcpf(1.0f + __expf(-x)); }
; __device__ __forceinline__ void hgrn_prep_phase(const bf16* z, const float* lbv, bf16* hq, float* dd, int tid, int G) {
;     ...
;             for (int tau = 0; tau < 32; ++tau) { const unsigned q2 = *(const unsigned*)(zq + (size_t)tau * ZP), f2 = *(const unsigned*)(zf + (size_t)tau * ZP);
;                 const float xf0 = fminf(fmaxf(bflo(f2), -30.f), 30.f), xf1 = fminf(fmaxf(bfhi(f2), -30.f), 30.f);
;                 const float e0 = __expf(-xf0), r0 = __builtin_amdgcn_rcpf(1.0f + e0), e1 = __expf(-xf1), r1 = __builtin_amdgcn_rcpf(1.0f + e1);
;                 const float f0 = lb0 + om0 * r0, f1 = lb1 + om1 * r1, k0v = om0 * (e0 * r0), k1v = om1 * (e1 * r1);
;                 bc0 += __logf(f0); bc1 += __logf(f1); kk0[tau] = k0v; kk1[tau] = k1v; bv0[tau] = bc0; bv1[tau] = bc1;
;                 *(unsigned*)(QT + tile + tau * 128 + kp) = pk2(siluf(bflo(q2)) * __expf(bc0), siluf(bfhi(q2)) * __expf(bc1));
;                 *(unsigned*)(KT + tile + tau * 128 + kp) = pk2(k0v * __expf(-bc0), k1v * __expf(-bc1)); }
	v_mov_b32_e32 v69, v164
	s_nop 0
	v_mov_b32_e32 v66, v165
	v_lshlrev_b32_e32 v67, 16, v66
	v_max_f32_e32 v67, v67, v67
	v_and_b32_e32 v66, 0xffff0000, v66
	v_med3_f32 v67, v67, s89, v225
	v_max_f32_e32 v66, v66, v66
	v_med3_f32 v68, v66, s89, v225
	v_mul_f32_e32 v66, 0xbfb8aa3b, v67
	v_exp_f32_e32 v66, v66
	s_nop 0
	v_add_f32_e32 v67, 1.0, v66
	v_rcp_f32_e32 v70, v67
	v_mul_f32_e32 v67, 0xbfb8aa3b, v68
	v_exp_f32_e32 v67, v67
	s_nop 0
	v_add_f32_e32 v68, 1.0, v67
	v_rcp_f32_e32 v71, v68
	v_fma_f32 v68, v26, v70, v28
	v_cmp_gt_f32_e32 vcc, s83, v68
	v_fma_f32 v72, v27, v71, v29
	s_nop 0
	v_cndmask_b32_e64 v73, 0, 32, vcc
	v_ldexp_f32 v68, v68, v73
	v_log_f32_e32 v68, v68
	s_nop 0
	v_mul_f32_e32 v73, 0x3f317217, v68
	v_fma_f32 v73, v68, s90, -v73
	v_fmac_f32_e32 v73, 0x3377d1cf, v68
	v_fmac_f32_e32 v73, 0x3f317217, v68
	v_cmp_lt_f32_e64 s[10:11], |v68|, s91
	s_nop 1
	v_cndmask_b32_e64 v68, v68, v73, s[10:11]
	v_cndmask_b32_e32 v73, 0, v226, vcc
	v_sub_f32_e32 v68, v68, v73
	v_cmp_gt_f32_e32 vcc, s83, v72
	v_add_f32_e32 v127, v125, v68
	s_nop 0
	v_cndmask_b32_e64 v68, 0, 32, vcc
	v_ldexp_f32 v68, v72, v68
	v_log_f32_e32 v68, v68
	s_nop 0
	v_mul_f32_e32 v72, 0x3f317217, v68
	v_fma_f32 v72, v68, s90, -v72
	v_fmac_f32_e32 v72, 0x3377d1cf, v68
	v_fmac_f32_e32 v72, 0x3f317217, v68
	v_cmp_lt_f32_e64 s[10:11], |v68|, s91
	s_nop 1
	v_cndmask_b32_e64 v68, v68, v72, s[10:11]
	v_cndmask_b32_e32 v72, 0, v226, vcc
	v_sub_f32_e32 v68, v68, v72
	v_add_f32_e32 v126, v124, v68
	v_lshlrev_b32_e32 v68, 16, v69
	v_and_b32_e32 v69, 0xffff0000, v69
	v_mul_f32_e32 v74, 0xbfb8aa3b, v68
	v_mul_f32_e32 v75, 0xbfb8aa3b, v69
	v_exp_f32_e32 v74, v74
	v_exp_f32_e32 v75, v75
	v_mul_f32_e32 v72, 0x3fb8aa3b, v127
	v_mul_f32_e32 v73, 0x3fb8aa3b, v126
	v_add_f32_e32 v74, 1.0, v74
	v_add_f32_e32 v75, 1.0, v75
	v_rcp_f32_e32 v74, v74
	v_rcp_f32_e32 v75, v75
	v_exp_f32_e32 v72, v72
	v_exp_f32_e32 v73, v73
	v_pk_mul_f32 v[68:69], v[74:75], v[68:69]
	s_nop 0
	v_pk_mul_f32 v[68:69], v[68:69], v[72:73]
	s_nop 0
	v_cvt_pk_bf16_f32 v72, v68, v69
	v_add_co_u32_e32 v68, vcc, s75, v62
	v_mul_f32_e32 v62, 0xbfb8aa3b, v127
	s_nop 0
	v_addc_co_u32_e32 v69, vcc, 0, v63, vcc
	global_store_dword v[68:69], v72, off
	v_exp_f32_e32 v72, v62
	v_mul_f32_e32 v62, 0xbfb8aa3b, v126
	v_exp_f32_e32 v73, v62
	v_pk_mul_f32 v[62:63], v[66:67], v[70:71]
	v_add_co_u32_e32 v70, vcc, s75, v64
	v_pk_mul_f32 v[62:63], v[26:27], v[62:63]
	s_nop 0
	v_addc_co_u32_e32 v71, vcc, 0, v65, vcc
	v_pk_mul_f32 v[66:67], v[62:63], v[72:73]
	v_add_co_u32_e32 v64, vcc, s0, v30
	v_cvt_pk_bf16_f32 v66, v66, v67
	global_store_dword v[70:71], v66, off
	v_addc_co_u32_e32 v65, vcc, 0, v31, vcc
	s_waitcnt vmcnt(58)
	v_mov_b32_e32 v73, v166
	s_nop 0
	v_mov_b32_e32 v64, v167
	s_mov_b32 s0, 0x65000
	v_lshlrev_b32_e32 v65, 16, v64
	v_max_f32_e32 v65, v65, v65
	v_and_b32_e32 v64, 0xffff0000, v64
	v_med3_f32 v65, v65, s89, v225
	v_max_f32_e32 v64, v64, v64
	v_med3_f32 v67, v64, s89, v225
	v_mul_f32_e32 v64, 0xbfb8aa3b, v65
	v_exp_f32_e32 v64, v64
	s_nop 0
	v_add_f32_e32 v65, 1.0, v64
	v_rcp_f32_e32 v66, v65
	v_mul_f32_e32 v65, 0xbfb8aa3b, v67
	v_exp_f32_e32 v65, v65
	v_fma_f32 v72, v26, v66, v28
	v_cmp_gt_f32_e32 vcc, s83, v72
	v_add_f32_e32 v67, 1.0, v65
	v_rcp_f32_e32 v67, v67
	v_cndmask_b32_e64 v75, 0, 32, vcc
	v_ldexp_f32 v72, v72, v75
	v_log_f32_e32 v72, v72
	v_fma_f32 v74, v27, v67, v29
	v_pk_mul_f32 v[64:65], v[64:65], v[66:67]
	v_mul_f32_e32 v75, 0x3f317217, v72
	v_fma_f32 v75, v72, s90, -v75
	v_fmac_f32_e32 v75, 0x3377d1cf, v72
	v_fmac_f32_e32 v75, 0x3f317217, v72
	v_cmp_lt_f32_e64 s[10:11], |v72|, s91
	v_pk_mul_f32 v[64:65], v[26:27], v[64:65]
	s_nop 0
	v_cndmask_b32_e64 v72, v72, v75, s[10:11]
	v_cndmask_b32_e32 v75, 0, v226, vcc
	v_sub_f32_e32 v72, v72, v75
	v_cmp_gt_f32_e32 vcc, s83, v74
	v_add_f32_e32 v129, v127, v72
	s_nop 0
	v_cndmask_b32_e64 v72, 0, 32, vcc
	v_ldexp_f32 v72, v74, v72
	v_log_f32_e32 v72, v72
	s_nop 0
	v_mul_f32_e32 v74, 0x3f317217, v72
	v_fma_f32 v74, v72, s90, -v74
	v_fmac_f32_e32 v74, 0x3377d1cf, v72
	v_fmac_f32_e32 v74, 0x3f317217, v72
	v_cmp_lt_f32_e64 s[10:11], |v72|, s91
	s_nop 1
	v_cndmask_b32_e64 v72, v72, v74, s[10:11]
	v_cndmask_b32_e32 v74, 0, v226, vcc
	v_sub_f32_e32 v72, v72, v74
	v_add_f32_e32 v128, v126, v72
	v_lshlrev_b32_e32 v72, 16, v73
	v_and_b32_e32 v73, 0xffff0000, v73
	v_mul_f32_e32 v76, 0xbfb8aa3b, v72
	v_mul_f32_e32 v77, 0xbfb8aa3b, v73
	v_exp_f32_e32 v76, v76
	v_exp_f32_e32 v77, v77
	v_mul_f32_e32 v74, 0x3fb8aa3b, v129
	v_mul_f32_e32 v75, 0x3fb8aa3b, v128
	v_add_f32_e32 v76, 1.0, v76
	v_add_f32_e32 v77, 1.0, v77
	v_rcp_f32_e32 v76, v76
	v_rcp_f32_e32 v77, v77
	v_exp_f32_e32 v74, v74
	v_exp_f32_e32 v75, v75
	v_pk_mul_f32 v[72:73], v[76:77], v[72:73]
	s_nop 0
	v_pk_mul_f32 v[72:73], v[72:73], v[74:75]
	s_nop 0
	v_cvt_pk_bf16_f32 v72, v72, v73
	global_store_dword v[68:69], v72, off offset:256
	v_mul_f32_e32 v72, 0xbfb8aa3b, v129
	v_mul_f32_e32 v73, 0xbfb8aa3b, v128
	v_exp_f32_e32 v72, v72
	v_exp_f32_e32 v73, v73
	s_nop 0
	v_pk_mul_f32 v[66:67], v[64:65], v[72:73]
	s_nop 0
	v_cvt_pk_bf16_f32 v66, v66, v67
	global_store_dword v[70:71], v66, off offset:256
	v_add_co_u32_e32 v66, vcc, s0, v30
	s_mov_b32 s0, 0x6a000
	s_nop 0
	v_addc_co_u32_e32 v67, vcc, 0, v31, vcc
	s_waitcnt vmcnt(56)
; __device__ __forceinline__ float bflo(unsigned w) { return __uint_as_float(w << 16); }
; __device__ __forceinline__ float bfhi(unsigned w) { return __uint_as_float(w & 0xffff0000u); }
; __device__ __forceinline__ unsigned pk2(float lo, float hi) { return pg8::cvt_pk_bf16(lo, hi); }
; __device__ __forceinline__ float siluf(float x) { return x * __builtin_amdgcn_rcpf(1.0f + __expf(-x)); }
; __device__ __forceinline__ void hgrn_prep_phase(const bf16* z, const float* lbv, bf16* hq, float* dd, int tid, int G) {
;     ...
;             for (int tau = 0; tau < 32; ++tau) { const unsigned q2 = *(const unsigned*)(zq + (size_t)tau * ZP), f2 = *(const unsigned*)(zf + (size_t)tau * ZP);
;                 const float xf0 = fminf(fmaxf(bflo(f2), -30.f), 30.f), xf1 = fminf(fmaxf(bfhi(f2), -30.f), 30.f);
;                 const float e0 = __expf(-xf0), r0 = __builtin_amdgcn_rcpf(1.0f + e0), e1 = __expf(-xf1), r1 = __builtin_amdgcn_rcpf(1.0f + e1);
;                 const float f0 = lb0 + om0 * r0, f1 = lb1 + om1 * r1, k0v = om0 * (e0 * r0), k1v = om1 * (e1 * r1);
;                 bc0 += __logf(f0); bc1 += __logf(f1); kk0[tau] = k0v; kk1[tau] = k1v; bv0[tau] = bc0; bv1[tau] = bc1;
;                 *(unsigned*)(QT + tile + tau * 128 + kp) = pk2(siluf(bflo(q2)) * __expf(bc0), siluf(bfhi(q2)) * __expf(bc1));
;                 *(unsigned*)(KT + tile + tau * 128 + kp) = pk2(k0v * __expf(-bc0), k1v * __expf(-bc1)); }
	v_mov_b32_e32 v75, v168
	s_nop 0
	v_mov_b32_e32 v66, v169
	v_lshlrev_b32_e32 v67, 16, v66
	v_max_f32_e32 v67, v67, v67
	v_and_b32_e32 v66, 0xffff0000, v66
	v_med3_f32 v67, v67, s89, v225
	v_max_f32_e32 v66, v66, v66
	v_med3_f32 v73, v66, s89, v225
	v_mul_f32_e32 v66, 0xbfb8aa3b, v67
	v_exp_f32_e32 v66, v66
	s_nop 0
	v_add_f32_e32 v67, 1.0, v66
	v_rcp_f32_e32 v72, v67
	v_mul_f32_e32 v67, 0xbfb8aa3b, v73
	v_exp_f32_e32 v67, v67
	v_fma_f32 v74, v26, v72, v28
	v_cmp_gt_f32_e32 vcc, s83, v74
	v_add_f32_e32 v73, 1.0, v67
	v_rcp_f32_e32 v73, v73
	v_cndmask_b32_e64 v77, 0, 32, vcc
	v_ldexp_f32 v74, v74, v77
	v_log_f32_e32 v74, v74
	v_fma_f32 v76, v27, v73, v29
	v_pk_mul_f32 v[66:67], v[66:67], v[72:73]
	v_mul_f32_e32 v77, 0x3f317217, v74
	v_fma_f32 v77, v74, s90, -v77
	v_fmac_f32_e32 v77, 0x3377d1cf, v74
	v_fmac_f32_e32 v77, 0x3f317217, v74
	v_cmp_lt_f32_e64 s[10:11], |v74|, s91
	v_pk_mul_f32 v[66:67], v[26:27], v[66:67]
	s_nop 0
	v_cndmask_b32_e64 v74, v74, v77, s[10:11]
	v_cndmask_b32_e32 v77, 0, v226, vcc
	v_sub_f32_e32 v74, v74, v77
	v_cmp_gt_f32_e32 vcc, s83, v76
	v_add_f32_e32 v131, v129, v74
	s_nop 0
	v_cndmask_b32_e64 v74, 0, 32, vcc
	v_ldexp_f32 v74, v76, v74
	v_log_f32_e32 v74, v74
	s_nop 0
	v_mul_f32_e32 v76, 0x3f317217, v74
	v_fma_f32 v76, v74, s90, -v76
	v_fmac_f32_e32 v76, 0x3377d1cf, v74
	v_fmac_f32_e32 v76, 0x3f317217, v74
	v_cmp_lt_f32_e64 s[10:11], |v74|, s91
	s_nop 1
	v_cndmask_b32_e64 v74, v74, v76, s[10:11]
	v_cndmask_b32_e32 v76, 0, v226, vcc
	v_sub_f32_e32 v74, v74, v76
	v_add_f32_e32 v130, v128, v74
	v_lshlrev_b32_e32 v74, 16, v75
	v_and_b32_e32 v75, 0xffff0000, v75
	v_mul_f32_e32 v78, 0xbfb8aa3b, v74
	v_mul_f32_e32 v79, 0xbfb8aa3b, v75
	v_exp_f32_e32 v78, v78
	v_exp_f32_e32 v79, v79
	v_mul_f32_e32 v76, 0x3fb8aa3b, v131
	v_mul_f32_e32 v77, 0x3fb8aa3b, v130
	v_add_f32_e32 v78, 1.0, v78
	v_add_f32_e32 v79, 1.0, v79
	v_rcp_f32_e32 v78, v78
	v_rcp_f32_e32 v79, v79
	v_exp_f32_e32 v76, v76
	v_exp_f32_e32 v77, v77
	v_pk_mul_f32 v[74:75], v[78:79], v[74:75]
	s_nop 0
	v_pk_mul_f32 v[74:75], v[74:75], v[76:77]
	s_nop 0
	v_cvt_pk_bf16_f32 v74, v74, v75
	global_store_dword v[68:69], v74, off offset:512
	v_mul_f32_e32 v74, 0xbfb8aa3b, v131
	v_mul_f32_e32 v75, 0xbfb8aa3b, v130
	v_exp_f32_e32 v74, v74
	v_exp_f32_e32 v75, v75
	s_nop 0
	v_pk_mul_f32 v[72:73], v[66:67], v[74:75]
	s_nop 0
	v_cvt_pk_bf16_f32 v72, v72, v73
	global_store_dword v[70:71], v72, off offset:512
	v_add_co_u32_e32 v72, vcc, s0, v30
	s_mov_b32 s0, 0x6b000
	s_nop 0
	v_addc_co_u32_e32 v73, vcc, 0, v31, vcc
	s_waitcnt vmcnt(54)
	v_mov_b32_e32 v77, v170
	v_add_co_u32_e32 v72, vcc, s0, v30
	s_mov_b32 s0, 0x70000
	s_nop 0
	v_addc_co_u32_e32 v73, vcc, 0, v31, vcc
	v_mov_b32_e32 v72, v171
	v_lshlrev_b32_e32 v73, 16, v72
	v_max_f32_e32 v73, v73, v73
	v_and_b32_e32 v72, 0xffff0000, v72
	v_med3_f32 v73, v73, s89, v225
	v_max_f32_e32 v72, v72, v72
	v_med3_f32 v75, v72, s89, v225
	v_mul_f32_e32 v72, 0xbfb8aa3b, v73
	v_exp_f32_e32 v72, v72
	s_nop 0
	v_add_f32_e32 v73, 1.0, v72
	v_rcp_f32_e32 v74, v73
	v_mul_f32_e32 v73, 0xbfb8aa3b, v75
	v_exp_f32_e32 v73, v73
	v_fma_f32 v76, v26, v74, v28
	v_cmp_gt_f32_e32 vcc, s83, v76
	v_add_f32_e32 v75, 1.0, v73
	v_rcp_f32_e32 v75, v75
	v_cndmask_b32_e64 v79, 0, 32, vcc
	v_ldexp_f32 v76, v76, v79
	v_log_f32_e32 v76, v76
	v_fma_f32 v78, v27, v75, v29
	v_pk_mul_f32 v[72:73], v[72:73], v[74:75]
	v_mul_f32_e32 v79, 0x3f317217, v76
	v_fma_f32 v79, v76, s90, -v79
	v_fmac_f32_e32 v79, 0x3377d1cf, v76
	v_fmac_f32_e32 v79, 0x3f317217, v76
	v_cmp_lt_f32_e64 s[10:11], |v76|, s91
	v_pk_mul_f32 v[72:73], v[26:27], v[72:73]
	s_nop 0
	v_cndmask_b32_e64 v76, v76, v79, s[10:11]
	v_cndmask_b32_e32 v79, 0, v226, vcc
	v_sub_f32_e32 v76, v76, v79
	v_cmp_gt_f32_e32 vcc, s83, v78
	v_add_f32_e32 v133, v131, v76
	s_nop 0
	v_cndmask_b32_e64 v76, 0, 32, vcc
	v_ldexp_f32 v76, v78, v76
	v_log_f32_e32 v76, v76
	s_nop 0
	v_mul_f32_e32 v78, 0x3f317217, v76
	v_fma_f32 v78, v76, s90, -v78
	v_fmac_f32_e32 v78, 0x3377d1cf, v76
	v_fmac_f32_e32 v78, 0x3f317217, v76
	v_cmp_lt_f32_e64 s[10:11], |v76|, s91
	s_nop 1
	v_cndmask_b32_e64 v76, v76, v78, s[10:11]
	v_cndmask_b32_e32 v78, 0, v226, vcc
	v_sub_f32_e32 v76, v76, v78
	v_add_f32_e32 v132, v130, v76
	v_lshlrev_b32_e32 v76, 16, v77
	v_and_b32_e32 v77, 0xffff0000, v77
	v_mul_f32_e32 v80, 0xbfb8aa3b, v76
	v_mul_f32_e32 v81, 0xbfb8aa3b, v77
	v_exp_f32_e32 v80, v80
	v_exp_f32_e32 v81, v81
	v_mul_f32_e32 v78, 0x3fb8aa3b, v133
	v_mul_f32_e32 v79, 0x3fb8aa3b, v132
	v_add_f32_e32 v80, 1.0, v80
	v_add_f32_e32 v81, 1.0, v81
	v_rcp_f32_e32 v80, v80
	v_rcp_f32_e32 v81, v81
	v_exp_f32_e32 v78, v78
	v_exp_f32_e32 v79, v79
	v_pk_mul_f32 v[76:77], v[80:81], v[76:77]
	s_nop 0
	v_pk_mul_f32 v[76:77], v[76:77], v[78:79]
	s_nop 0
	v_cvt_pk_bf16_f32 v76, v76, v77
	global_store_dword v[68:69], v76, off offset:768
	v_mul_f32_e32 v76, 0xbfb8aa3b, v133
	v_mul_f32_e32 v77, 0xbfb8aa3b, v132
	v_exp_f32_e32 v76, v76
	v_exp_f32_e32 v77, v77
	s_nop 0
	v_pk_mul_f32 v[74:75], v[72:73], v[76:77]
	s_nop 0
	v_cvt_pk_bf16_f32 v74, v74, v75
	global_store_dword v[70:71], v74, off offset:768
	v_add_co_u32_e32 v74, vcc, s0, v30
	s_mov_b32 s0, 0x76000
	s_nop 0
	v_addc_co_u32_e32 v75, vcc, 0, v31, vcc
	s_waitcnt vmcnt(52)
; __device__ __forceinline__ float bflo(unsigned w) { return __uint_as_float(w << 16); }
; __device__ __forceinline__ float bfhi(unsigned w) { return __uint_as_float(w & 0xffff0000u); }
; __device__ __forceinline__ unsigned pk2(float lo, float hi) { return pg8::cvt_pk_bf16(lo, hi); }
; __device__ __forceinline__ float siluf(float x) { return x * __builtin_amdgcn_rcpf(1.0f + __expf(-x)); }
; __device__ __forceinline__ void hgrn_prep_phase(const bf16* z, const float* lbv, bf16* hq, float* dd, int tid, int G) {
;     ...
;             for (int tau = 0; tau < 32; ++tau) { const unsigned q2 = *(const unsigned*)(zq + (size_t)tau * ZP), f2 = *(const unsigned*)(zf + (size_t)tau * ZP);
;                 const float xf0 = fminf(fmaxf(bflo(f2), -30.f), 30.f), xf1 = fminf(fmaxf(bfhi(f2), -30.f), 30.f);
;                 const float e0 = __expf(-xf0), r0 = __builtin_amdgcn_rcpf(1.0f + e0), e1 = __expf(-xf1), r1 = __builtin_amdgcn_rcpf(1.0f + e1);
;                 const float f0 = lb0 + om0 * r0, f1 = lb1 + om1 * r1, k0v = om0 * (e0 * r0), k1v = om1 * (e1 * r1);
;                 bc0 += __logf(f0); bc1 += __logf(f1); kk0[tau] = k0v; kk1[tau] = k1v; bv0[tau] = bc0; bv1[tau] = bc1;
;                 *(unsigned*)(QT + tile + tau * 128 + kp) = pk2(siluf(bflo(q2)) * __expf(bc0), siluf(bfhi(q2)) * __expf(bc1));
;                 *(unsigned*)(KT + tile + tau * 128 + kp) = pk2(k0v * __expf(-bc0), k1v * __expf(-bc1)); }
	v_mov_b32_e32 v79, v186
	s_nop 0
	v_mov_b32_e32 v74, v187
	v_lshlrev_b32_e32 v75, 16, v74
	v_max_f32_e32 v75, v75, v75
	v_and_b32_e32 v74, 0xffff0000, v74
	v_med3_f32 v75, v75, s89, v225
	v_max_f32_e32 v74, v74, v74
	v_med3_f32 v77, v74, s89, v225
	v_mul_f32_e32 v74, 0xbfb8aa3b, v75
	v_exp_f32_e32 v74, v74
	s_nop 0
	v_add_f32_e32 v75, 1.0, v74
	v_rcp_f32_e32 v76, v75
	v_mul_f32_e32 v75, 0xbfb8aa3b, v77
	v_exp_f32_e32 v75, v75
	v_fma_f32 v78, v26, v76, v28
	v_cmp_gt_f32_e32 vcc, s83, v78
	v_add_f32_e32 v77, 1.0, v75
	v_rcp_f32_e32 v77, v77
	v_cndmask_b32_e64 v81, 0, 32, vcc
	v_ldexp_f32 v78, v78, v81
	v_log_f32_e32 v78, v78
	v_fma_f32 v80, v27, v77, v29
	v_pk_mul_f32 v[74:75], v[74:75], v[76:77]
	v_mul_f32_e32 v81, 0x3f317217, v78
	v_fma_f32 v81, v78, s90, -v81
	v_fmac_f32_e32 v81, 0x3377d1cf, v78
	v_fmac_f32_e32 v81, 0x3f317217, v78
	v_cmp_lt_f32_e64 s[10:11], |v78|, s91
	v_pk_mul_f32 v[74:75], v[26:27], v[74:75]
	s_nop 0
	v_cndmask_b32_e64 v78, v78, v81, s[10:11]
	v_cndmask_b32_e32 v81, 0, v226, vcc
	v_sub_f32_e32 v78, v78, v81
	v_cmp_gt_f32_e32 vcc, s83, v80
	v_add_f32_e32 v135, v133, v78
	s_nop 0
	v_cndmask_b32_e64 v78, 0, 32, vcc
	v_ldexp_f32 v78, v80, v78
	v_log_f32_e32 v78, v78
	s_nop 0
	v_mul_f32_e32 v80, 0x3f317217, v78
	v_fma_f32 v80, v78, s90, -v80
	v_fmac_f32_e32 v80, 0x3377d1cf, v78
	v_fmac_f32_e32 v80, 0x3f317217, v78
	v_cmp_lt_f32_e64 s[10:11], |v78|, s91
	s_nop 1
	v_cndmask_b32_e64 v78, v78, v80, s[10:11]
	v_cndmask_b32_e32 v80, 0, v226, vcc
	v_sub_f32_e32 v78, v78, v80
	v_add_f32_e32 v134, v132, v78
	v_lshlrev_b32_e32 v78, 16, v79
	v_and_b32_e32 v79, 0xffff0000, v79
	v_mul_f32_e32 v82, 0xbfb8aa3b, v78
	v_mul_f32_e32 v83, 0xbfb8aa3b, v79
	v_exp_f32_e32 v82, v82
	v_exp_f32_e32 v83, v83
	v_mul_f32_e32 v80, 0x3fb8aa3b, v135
	v_mul_f32_e32 v81, 0x3fb8aa3b, v134
	v_add_f32_e32 v82, 1.0, v82
	v_add_f32_e32 v83, 1.0, v83
	v_rcp_f32_e32 v82, v82
	v_rcp_f32_e32 v83, v83
	v_exp_f32_e32 v80, v80
	v_exp_f32_e32 v81, v81
	v_pk_mul_f32 v[78:79], v[82:83], v[78:79]
	s_nop 0
	v_pk_mul_f32 v[78:79], v[78:79], v[80:81]
	s_nop 0
	v_cvt_pk_bf16_f32 v78, v78, v79
	global_store_dword v[68:69], v78, off offset:1024
	v_mul_f32_e32 v78, 0xbfb8aa3b, v135
	v_mul_f32_e32 v79, 0xbfb8aa3b, v134
	v_exp_f32_e32 v78, v78
	v_exp_f32_e32 v79, v79
	s_nop 0
	v_pk_mul_f32 v[76:77], v[74:75], v[78:79]
	s_nop 0
	v_cvt_pk_bf16_f32 v76, v76, v77
	global_store_dword v[70:71], v76, off offset:1024
	v_add_co_u32_e32 v76, vcc, s0, v30
	s_mov_b32 s0, 0x7b000
	s_nop 0
	v_addc_co_u32_e32 v77, vcc, 0, v31, vcc
	s_waitcnt vmcnt(50)
	v_mov_b32_e32 v81, v188
	s_nop 0
	v_mov_b32_e32 v76, v189
	v_lshlrev_b32_e32 v77, 16, v76
	v_max_f32_e32 v77, v77, v77
	v_and_b32_e32 v76, 0xffff0000, v76
	v_med3_f32 v77, v77, s89, v225
	v_max_f32_e32 v76, v76, v76
	v_med3_f32 v79, v76, s89, v225
	v_mul_f32_e32 v76, 0xbfb8aa3b, v77
	v_exp_f32_e32 v76, v76
	s_nop 0
	v_add_f32_e32 v77, 1.0, v76
	v_rcp_f32_e32 v78, v77
	v_mul_f32_e32 v77, 0xbfb8aa3b, v79
	v_exp_f32_e32 v77, v77
	v_fma_f32 v80, v26, v78, v28
	v_cmp_gt_f32_e32 vcc, s83, v80
	v_add_f32_e32 v79, 1.0, v77
	v_rcp_f32_e32 v79, v79
	v_cndmask_b32_e64 v83, 0, 32, vcc
	v_ldexp_f32 v80, v80, v83
	v_log_f32_e32 v80, v80
	v_fma_f32 v82, v27, v79, v29
	v_pk_mul_f32 v[76:77], v[76:77], v[78:79]
	v_mul_f32_e32 v83, 0x3f317217, v80
	v_fma_f32 v83, v80, s90, -v83
	v_fmac_f32_e32 v83, 0x3377d1cf, v80
	v_fmac_f32_e32 v83, 0x3f317217, v80
	v_cmp_lt_f32_e64 s[10:11], |v80|, s91
	v_pk_mul_f32 v[76:77], v[26:27], v[76:77]
	s_nop 0
	v_cndmask_b32_e64 v80, v80, v83, s[10:11]
	v_cndmask_b32_e32 v83, 0, v226, vcc
	v_sub_f32_e32 v80, v80, v83
	v_cmp_gt_f32_e32 vcc, s83, v82
	v_add_f32_e32 v137, v135, v80
	s_nop 0
	v_cndmask_b32_e64 v80, 0, 32, vcc
	v_ldexp_f32 v80, v82, v80
	v_log_f32_e32 v80, v80
	s_nop 0
	v_mul_f32_e32 v82, 0x3f317217, v80
	v_fma_f32 v82, v80, s90, -v82
	v_fmac_f32_e32 v82, 0x3377d1cf, v80
	v_fmac_f32_e32 v82, 0x3f317217, v80
	v_cmp_lt_f32_e64 s[10:11], |v80|, s91
	s_nop 1
	v_cndmask_b32_e64 v80, v80, v82, s[10:11]
	v_cndmask_b32_e32 v82, 0, v226, vcc
	v_sub_f32_e32 v80, v80, v82
	v_add_f32_e32 v136, v134, v80
	v_lshlrev_b32_e32 v80, 16, v81
	v_and_b32_e32 v81, 0xffff0000, v81
	v_mul_f32_e32 v84, 0xbfb8aa3b, v80
	v_mul_f32_e32 v85, 0xbfb8aa3b, v81
	v_exp_f32_e32 v84, v84
	v_exp_f32_e32 v85, v85
	v_mul_f32_e32 v82, 0x3fb8aa3b, v137
	v_mul_f32_e32 v83, 0x3fb8aa3b, v136
	v_add_f32_e32 v84, 1.0, v84
	v_add_f32_e32 v85, 1.0, v85
	v_rcp_f32_e32 v84, v84
	v_rcp_f32_e32 v85, v85
	v_exp_f32_e32 v82, v82
	v_exp_f32_e32 v83, v83
	v_pk_mul_f32 v[80:81], v[84:85], v[80:81]
	s_nop 0
	v_pk_mul_f32 v[80:81], v[80:81], v[82:83]
	s_nop 0
	v_cvt_pk_bf16_f32 v80, v80, v81
	global_store_dword v[68:69], v80, off offset:1280
	v_mul_f32_e32 v80, 0xbfb8aa3b, v137
	v_mul_f32_e32 v81, 0xbfb8aa3b, v136
	v_exp_f32_e32 v80, v80
	v_exp_f32_e32 v81, v81
	s_nop 0
	v_pk_mul_f32 v[78:79], v[76:77], v[80:81]
	s_nop 0
	v_cvt_pk_bf16_f32 v78, v78, v79
	global_store_dword v[70:71], v78, off offset:1280
	v_add_co_u32_e32 v78, vcc, s0, v30
	s_mov_b32 s0, 0x7c000
	s_nop 0
	v_addc_co_u32_e32 v79, vcc, 0, v31, vcc
	v_add_co_u32_e32 v80, vcc, s0, v30
	s_waitcnt vmcnt(48)
; __device__ __forceinline__ float bflo(unsigned w) { return __uint_as_float(w << 16); }
; __device__ __forceinline__ float bfhi(unsigned w) { return __uint_as_float(w & 0xffff0000u); }
; __device__ __forceinline__ unsigned pk2(float lo, float hi) { return pg8::cvt_pk_bf16(lo, hi); }
; __device__ __forceinline__ float siluf(float x) { return x * __builtin_amdgcn_rcpf(1.0f + __expf(-x)); }
; __device__ __forceinline__ void hgrn_prep_phase(const bf16* z, const float* lbv, bf16* hq, float* dd, int tid, int G) {
;     ...
;             for (int tau = 0; tau < 32; ++tau) { const unsigned q2 = *(const unsigned*)(zq + (size_t)tau * ZP), f2 = *(const unsigned*)(zf + (size_t)tau * ZP);
;                 const float xf0 = fminf(fmaxf(bflo(f2), -30.f), 30.f), xf1 = fminf(fmaxf(bfhi(f2), -30.f), 30.f);
;                 const float e0 = __expf(-xf0), r0 = __builtin_amdgcn_rcpf(1.0f + e0), e1 = __expf(-xf1), r1 = __builtin_amdgcn_rcpf(1.0f + e1);
;                 const float f0 = lb0 + om0 * r0, f1 = lb1 + om1 * r1, k0v = om0 * (e0 * r0), k1v = om1 * (e1 * r1);
;                 bc0 += __logf(f0); bc1 += __logf(f1); kk0[tau] = k0v; kk1[tau] = k1v; bv0[tau] = bc0; bv1[tau] = bc1;
;                 *(unsigned*)(QT + tile + tau * 128 + kp) = pk2(siluf(bflo(q2)) * __expf(bc0), siluf(bfhi(q2)) * __expf(bc1));
;                 *(unsigned*)(KT + tile + tau * 128 + kp) = pk2(k0v * __expf(-bc0), k1v * __expf(-bc1)); }
	v_mov_b32_e32 v78, v190
	s_nop 0
	v_addc_co_u32_e32 v81, vcc, 0, v31, vcc
	v_mov_b32_e32 v79, v191
	s_mov_b32 s0, 0x81000
	v_lshlrev_b32_e32 v80, 16, v79
	v_max_f32_e32 v80, v80, v80
	v_med3_f32 v80, v80, s89, v225
	v_mul_f32_e32 v80, 0xbfb8aa3b, v80
	v_exp_f32_e32 v80, v80
	v_and_b32_e32 v79, 0xffff0000, v79
	v_max_f32_e32 v79, v79, v79
	v_med3_f32 v79, v79, s89, v225
	v_add_f32_e32 v81, 1.0, v80
	v_mul_f32_e32 v79, 0xbfb8aa3b, v79
	v_rcp_f32_e32 v82, v81
	v_exp_f32_e32 v81, v79
	s_nop 0
	v_add_f32_e32 v79, 1.0, v81
	v_rcp_f32_e32 v83, v79
	v_fma_f32 v79, v26, v82, v28
	v_cmp_gt_f32_e32 vcc, s83, v79
	v_fma_f32 v84, v27, v83, v29
	s_nop 0
	v_cndmask_b32_e64 v85, 0, 32, vcc
	v_ldexp_f32 v79, v79, v85
	v_log_f32_e32 v79, v79
	s_nop 0
	v_mul_f32_e32 v85, 0x3f317217, v79
	v_fma_f32 v85, v79, s90, -v85
	v_fmac_f32_e32 v85, 0x3377d1cf, v79
	v_fmac_f32_e32 v85, 0x3f317217, v79
	v_cmp_lt_f32_e64 s[10:11], |v79|, s91
	s_nop 1
	v_cndmask_b32_e64 v79, v79, v85, s[10:11]
	v_cndmask_b32_e32 v85, 0, v226, vcc
	v_sub_f32_e32 v79, v79, v85
	v_cmp_gt_f32_e32 vcc, s83, v84
	v_add_f32_e32 v139, v137, v79
	v_and_b32_e32 v85, 0xffff0000, v78
	v_cndmask_b32_e64 v79, 0, 32, vcc
	v_ldexp_f32 v79, v84, v79
	v_log_f32_e32 v79, v79
	s_nop 0
	v_mul_f32_e32 v84, 0x3f317217, v79
	v_fma_f32 v84, v79, s90, -v84
	v_fmac_f32_e32 v84, 0x3377d1cf, v79
	v_fmac_f32_e32 v84, 0x3f317217, v79
	v_cmp_lt_f32_e64 s[10:11], |v79|, s91
	s_nop 1
	v_cndmask_b32_e64 v79, v79, v84, s[10:11]
	v_cndmask_b32_e32 v84, 0, v226, vcc
	v_sub_f32_e32 v79, v79, v84
	v_add_f32_e32 v138, v136, v79
	v_lshlrev_b32_e32 v84, 16, v78
	v_mul_f32_e32 v79, 0x3fb8aa3b, v139
	v_mul_f32_e32 v78, 0x3fb8aa3b, v138
	v_exp_f32_e32 v86, v79
	v_exp_f32_e32 v87, v78
	v_mul_f32_e32 v78, 0xbfb8aa3b, v84
	v_mul_f32_e32 v79, 0xbfb8aa3b, v85
	v_exp_f32_e32 v78, v78
	v_exp_f32_e32 v79, v79
	v_add_f32_e32 v78, 1.0, v78
	v_add_f32_e32 v79, 1.0, v79
	v_rcp_f32_e32 v78, v78
	v_rcp_f32_e32 v79, v79
	s_nop 0
	v_pk_mul_f32 v[78:79], v[78:79], v[84:85]
	s_nop 0
	v_pk_mul_f32 v[78:79], v[78:79], v[86:87]
	s_nop 0
	v_cvt_pk_bf16_f32 v78, v78, v79
	global_store_dword v[68:69], v78, off offset:1536
	v_mul_f32_e32 v78, 0xbfb8aa3b, v139
	v_exp_f32_e32 v84, v78
	v_mul_f32_e32 v78, 0xbfb8aa3b, v138
	v_exp_f32_e32 v85, v78
	v_pk_mul_f32 v[78:79], v[80:81], v[82:83]
	s_nop 0
	v_pk_mul_f32 v[78:79], v[26:27], v[78:79]
	s_nop 0
	v_pk_mul_f32 v[80:81], v[78:79], v[84:85]
	s_nop 0
	v_cvt_pk_bf16_f32 v80, v80, v81
	global_store_dword v[70:71], v80, off offset:1536
	v_add_co_u32_e32 v80, vcc, s0, v30
	s_mov_b32 s0, 0x87000
	s_nop 0
	v_addc_co_u32_e32 v81, vcc, 0, v31, vcc
	s_waitcnt vmcnt(46)
	v_mov_b32_e32 v85, v192
	s_nop 0
	v_mov_b32_e32 v80, v193
	v_lshlrev_b32_e32 v81, 16, v80
	v_max_f32_e32 v81, v81, v81
	v_and_b32_e32 v80, 0xffff0000, v80
	v_med3_f32 v81, v81, s89, v225
	v_max_f32_e32 v80, v80, v80
	v_med3_f32 v83, v80, s89, v225
	v_mul_f32_e32 v80, 0xbfb8aa3b, v81
	v_exp_f32_e32 v80, v80
	s_nop 0
	v_add_f32_e32 v81, 1.0, v80
	v_rcp_f32_e32 v82, v81
	v_mul_f32_e32 v81, 0xbfb8aa3b, v83
	v_exp_f32_e32 v81, v81
	v_fma_f32 v84, v26, v82, v28
	v_cmp_gt_f32_e32 vcc, s83, v84
	v_add_f32_e32 v83, 1.0, v81
	v_rcp_f32_e32 v83, v83
	v_cndmask_b32_e64 v87, 0, 32, vcc
	v_ldexp_f32 v84, v84, v87
	v_log_f32_e32 v84, v84
	v_fma_f32 v86, v27, v83, v29
	v_pk_mul_f32 v[80:81], v[80:81], v[82:83]
	v_mul_f32_e32 v87, 0x3f317217, v84
	v_fma_f32 v87, v84, s90, -v87
	v_fmac_f32_e32 v87, 0x3377d1cf, v84
	v_fmac_f32_e32 v87, 0x3f317217, v84
	v_cmp_lt_f32_e64 s[10:11], |v84|, s91
	v_pk_mul_f32 v[80:81], v[26:27], v[80:81]
	s_nop 0
	v_cndmask_b32_e64 v84, v84, v87, s[10:11]
	v_cndmask_b32_e32 v87, 0, v226, vcc
	v_sub_f32_e32 v84, v84, v87
	v_cmp_gt_f32_e32 vcc, s83, v86
	v_add_f32_e32 v141, v139, v84
	s_nop 0
	v_cndmask_b32_e64 v84, 0, 32, vcc
	v_ldexp_f32 v84, v86, v84
	v_log_f32_e32 v84, v84
	s_nop 0
	v_mul_f32_e32 v86, 0x3f317217, v84
	v_fma_f32 v86, v84, s90, -v86
	v_fmac_f32_e32 v86, 0x3377d1cf, v84
	v_fmac_f32_e32 v86, 0x3f317217, v84
	v_cmp_lt_f32_e64 s[10:11], |v84|, s91
	s_nop 1
	v_cndmask_b32_e64 v84, v84, v86, s[10:11]
	v_cndmask_b32_e32 v86, 0, v226, vcc
	v_sub_f32_e32 v84, v84, v86
	v_add_f32_e32 v140, v138, v84
	v_lshlrev_b32_e32 v84, 16, v85
	v_and_b32_e32 v85, 0xffff0000, v85
	v_mul_f32_e32 v88, 0xbfb8aa3b, v84
	v_mul_f32_e32 v89, 0xbfb8aa3b, v85
	v_exp_f32_e32 v88, v88
	v_exp_f32_e32 v89, v89
	v_mul_f32_e32 v86, 0x3fb8aa3b, v141
	v_mul_f32_e32 v87, 0x3fb8aa3b, v140
	v_add_f32_e32 v88, 1.0, v88
	v_add_f32_e32 v89, 1.0, v89
	v_rcp_f32_e32 v88, v88
	v_rcp_f32_e32 v89, v89
	v_exp_f32_e32 v86, v86
	v_exp_f32_e32 v87, v87
	v_pk_mul_f32 v[84:85], v[88:89], v[84:85]
	s_nop 0
	v_pk_mul_f32 v[84:85], v[84:85], v[86:87]
	s_nop 0
	v_cvt_pk_bf16_f32 v84, v84, v85
	global_store_dword v[68:69], v84, off offset:1792
	v_mul_f32_e32 v84, 0xbfb8aa3b, v141
	v_mul_f32_e32 v85, 0xbfb8aa3b, v140
	v_exp_f32_e32 v84, v84
	v_exp_f32_e32 v85, v85
	s_nop 0
	v_pk_mul_f32 v[82:83], v[80:81], v[84:85]
	s_nop 0
	v_cvt_pk_bf16_f32 v82, v82, v83
	global_store_dword v[70:71], v82, off offset:1792
	v_add_co_u32_e32 v82, vcc, s0, v30
	s_mov_b32 s0, 0x8c000
	s_nop 0
	v_addc_co_u32_e32 v83, vcc, 0, v31, vcc
	s_waitcnt vmcnt(44)
; __device__ __forceinline__ float bflo(unsigned w) { return __uint_as_float(w << 16); }
; __device__ __forceinline__ float bfhi(unsigned w) { return __uint_as_float(w & 0xffff0000u); }
; __device__ __forceinline__ unsigned pk2(float lo, float hi) { return pg8::cvt_pk_bf16(lo, hi); }
; __device__ __forceinline__ float siluf(float x) { return x * __builtin_amdgcn_rcpf(1.0f + __expf(-x)); }
; __device__ __forceinline__ void hgrn_prep_phase(const bf16* z, const float* lbv, bf16* hq, float* dd, int tid, int G) {
;     ...
;             for (int tau = 0; tau < 32; ++tau) { const unsigned q2 = *(const unsigned*)(zq + (size_t)tau * ZP), f2 = *(const unsigned*)(zf + (size_t)tau * ZP);
;                 const float xf0 = fminf(fmaxf(bflo(f2), -30.f), 30.f), xf1 = fminf(fmaxf(bfhi(f2), -30.f), 30.f);
;                 const float e0 = __expf(-xf0), r0 = __builtin_amdgcn_rcpf(1.0f + e0), e1 = __expf(-xf1), r1 = __builtin_amdgcn_rcpf(1.0f + e1);
;                 const float f0 = lb0 + om0 * r0, f1 = lb1 + om1 * r1, k0v = om0 * (e0 * r0), k1v = om1 * (e1 * r1);
;                 bc0 += __logf(f0); bc1 += __logf(f1); kk0[tau] = k0v; kk1[tau] = k1v; bv0[tau] = bc0; bv1[tau] = bc1;
;                 *(unsigned*)(QT + tile + tau * 128 + kp) = pk2(siluf(bflo(q2)) * __expf(bc0), siluf(bfhi(q2)) * __expf(bc1));
;                 *(unsigned*)(KT + tile + tau * 128 + kp) = pk2(k0v * __expf(-bc0), k1v * __expf(-bc1)); }
	v_mov_b32_e32 v87, v194
	s_nop 0
	v_mov_b32_e32 v82, v195
	v_lshlrev_b32_e32 v83, 16, v82
	v_max_f32_e32 v83, v83, v83
	v_and_b32_e32 v82, 0xffff0000, v82
	v_med3_f32 v83, v83, s89, v225
	v_max_f32_e32 v82, v82, v82
	v_med3_f32 v85, v82, s89, v225
	v_mul_f32_e32 v82, 0xbfb8aa3b, v83
	v_exp_f32_e32 v82, v82
	s_nop 0
	v_add_f32_e32 v83, 1.0, v82
	v_rcp_f32_e32 v84, v83
	v_mul_f32_e32 v83, 0xbfb8aa3b, v85
	v_exp_f32_e32 v83, v83
	v_fma_f32 v86, v26, v84, v28
	v_cmp_gt_f32_e32 vcc, s83, v86
	v_add_f32_e32 v85, 1.0, v83
	v_rcp_f32_e32 v85, v85
	v_cndmask_b32_e64 v89, 0, 32, vcc
	v_ldexp_f32 v86, v86, v89
	v_log_f32_e32 v86, v86
	v_fma_f32 v88, v27, v85, v29
	v_pk_mul_f32 v[82:83], v[82:83], v[84:85]
	v_mul_f32_e32 v89, 0x3f317217, v86
	v_fma_f32 v89, v86, s90, -v89
	v_fmac_f32_e32 v89, 0x3377d1cf, v86
	v_fmac_f32_e32 v89, 0x3f317217, v86
	v_cmp_lt_f32_e64 s[10:11], |v86|, s91
	v_pk_mul_f32 v[82:83], v[26:27], v[82:83]
	s_nop 0
	v_cndmask_b32_e64 v86, v86, v89, s[10:11]
	v_cndmask_b32_e32 v89, 0, v226, vcc
	v_sub_f32_e32 v86, v86, v89
	v_cmp_gt_f32_e32 vcc, s83, v88
	v_add_f32_e32 v143, v141, v86
	s_nop 0
	v_cndmask_b32_e64 v86, 0, 32, vcc
	v_ldexp_f32 v86, v88, v86
	v_log_f32_e32 v86, v86
	s_nop 0
	v_mul_f32_e32 v88, 0x3f317217, v86
	v_fma_f32 v88, v86, s90, -v88
	v_fmac_f32_e32 v88, 0x3377d1cf, v86
	v_fmac_f32_e32 v88, 0x3f317217, v86
	v_cmp_lt_f32_e64 s[10:11], |v86|, s91
	s_nop 1
	v_cndmask_b32_e64 v86, v86, v88, s[10:11]
	v_cndmask_b32_e32 v88, 0, v226, vcc
	v_sub_f32_e32 v86, v86, v88
	v_add_f32_e32 v142, v140, v86
	v_lshlrev_b32_e32 v86, 16, v87
	v_and_b32_e32 v87, 0xffff0000, v87
	v_mul_f32_e32 v90, 0xbfb8aa3b, v86
	v_mul_f32_e32 v91, 0xbfb8aa3b, v87
	v_exp_f32_e32 v90, v90
	v_exp_f32_e32 v91, v91
	v_mul_f32_e32 v88, 0x3fb8aa3b, v143
	v_mul_f32_e32 v89, 0x3fb8aa3b, v142
	v_add_f32_e32 v90, 1.0, v90
	v_add_f32_e32 v91, 1.0, v91
	v_rcp_f32_e32 v90, v90
	v_rcp_f32_e32 v91, v91
	v_exp_f32_e32 v88, v88
	v_exp_f32_e32 v89, v89
	v_pk_mul_f32 v[86:87], v[90:91], v[86:87]
	s_nop 0
	v_pk_mul_f32 v[86:87], v[86:87], v[88:89]
	s_nop 0
	v_cvt_pk_bf16_f32 v86, v86, v87
	global_store_dword v[68:69], v86, off offset:2048
	v_mul_f32_e32 v86, 0xbfb8aa3b, v143
	v_mul_f32_e32 v87, 0xbfb8aa3b, v142
	v_exp_f32_e32 v86, v86
	v_exp_f32_e32 v87, v87
	s_nop 0
	v_pk_mul_f32 v[84:85], v[82:83], v[86:87]
	s_nop 0
	v_cvt_pk_bf16_f32 v84, v84, v85
	global_store_dword v[70:71], v84, off offset:2048
	v_add_co_u32_e32 v84, vcc, s0, v30
	s_mov_b32 s0, 0x92000
	s_nop 0
	v_addc_co_u32_e32 v85, vcc, 0, v31, vcc
	s_waitcnt vmcnt(42)
	v_mov_b32_e32 v89, v196
	s_nop 0
	v_mov_b32_e32 v84, v197
	v_lshlrev_b32_e32 v85, 16, v84
	v_max_f32_e32 v85, v85, v85
	v_and_b32_e32 v84, 0xffff0000, v84
	v_med3_f32 v85, v85, s89, v225
	v_max_f32_e32 v84, v84, v84
	v_med3_f32 v87, v84, s89, v225
	v_mul_f32_e32 v84, 0xbfb8aa3b, v85
	v_exp_f32_e32 v84, v84
	s_nop 0
	v_add_f32_e32 v85, 1.0, v84
	v_rcp_f32_e32 v86, v85
	v_mul_f32_e32 v85, 0xbfb8aa3b, v87
	v_exp_f32_e32 v85, v85
	v_fma_f32 v88, v26, v86, v28
	v_cmp_gt_f32_e32 vcc, s83, v88
	v_add_f32_e32 v87, 1.0, v85
	v_rcp_f32_e32 v87, v87
	v_cndmask_b32_e64 v91, 0, 32, vcc
	v_ldexp_f32 v88, v88, v91
	v_log_f32_e32 v88, v88
	v_fma_f32 v90, v27, v87, v29
	v_pk_mul_f32 v[84:85], v[84:85], v[86:87]
	v_mul_f32_e32 v91, 0x3f317217, v88
	v_fma_f32 v91, v88, s90, -v91
	v_fmac_f32_e32 v91, 0x3377d1cf, v88
	v_fmac_f32_e32 v91, 0x3f317217, v88
	v_cmp_lt_f32_e64 s[10:11], |v88|, s91
	v_pk_mul_f32 v[84:85], v[26:27], v[84:85]
	s_nop 0
	v_cndmask_b32_e64 v88, v88, v91, s[10:11]
	v_cndmask_b32_e32 v91, 0, v226, vcc
	v_sub_f32_e32 v88, v88, v91
	v_cmp_gt_f32_e32 vcc, s83, v90
	v_add_f32_e32 v145, v143, v88
	s_nop 0
	v_cndmask_b32_e64 v88, 0, 32, vcc
	v_ldexp_f32 v88, v90, v88
	v_log_f32_e32 v88, v88
	s_nop 0
	v_mul_f32_e32 v90, 0x3f317217, v88
	v_fma_f32 v90, v88, s90, -v90
	v_fmac_f32_e32 v90, 0x3377d1cf, v88
	v_fmac_f32_e32 v90, 0x3f317217, v88
	v_cmp_lt_f32_e64 s[10:11], |v88|, s91
	s_nop 1
	v_cndmask_b32_e64 v88, v88, v90, s[10:11]
	v_cndmask_b32_e32 v90, 0, v226, vcc
	v_sub_f32_e32 v88, v88, v90
	v_add_f32_e32 v144, v142, v88
	v_lshlrev_b32_e32 v88, 16, v89
	v_and_b32_e32 v89, 0xffff0000, v89
	v_mul_f32_e32 v92, 0xbfb8aa3b, v88
	v_mul_f32_e32 v93, 0xbfb8aa3b, v89
	v_exp_f32_e32 v92, v92
	v_exp_f32_e32 v93, v93
	v_mul_f32_e32 v90, 0x3fb8aa3b, v145
	v_mul_f32_e32 v91, 0x3fb8aa3b, v144
	v_add_f32_e32 v92, 1.0, v92
	v_add_f32_e32 v93, 1.0, v93
	v_rcp_f32_e32 v92, v92
	v_rcp_f32_e32 v93, v93
	v_exp_f32_e32 v90, v90
	v_exp_f32_e32 v91, v91
	v_pk_mul_f32 v[88:89], v[92:93], v[88:89]
	s_nop 0
	v_pk_mul_f32 v[88:89], v[88:89], v[90:91]
	s_nop 0
	v_cvt_pk_bf16_f32 v88, v88, v89
	global_store_dword v[68:69], v88, off offset:2304
	v_mul_f32_e32 v88, 0xbfb8aa3b, v145
	v_mul_f32_e32 v89, 0xbfb8aa3b, v144
	v_exp_f32_e32 v88, v88
	v_exp_f32_e32 v89, v89
	s_nop 0
	v_pk_mul_f32 v[86:87], v[84:85], v[88:89]
	s_nop 0
	v_cvt_pk_bf16_f32 v86, v86, v87
	global_store_dword v[70:71], v86, off offset:2304
	v_add_co_u32_e32 v86, vcc, s0, v30
	s_mov_b32 s0, 0x97000
	s_nop 0
	v_addc_co_u32_e32 v87, vcc, 0, v31, vcc
	s_waitcnt vmcnt(40)
; __device__ __forceinline__ float bflo(unsigned w) { return __uint_as_float(w << 16); }
; __device__ __forceinline__ float bfhi(unsigned w) { return __uint_as_float(w & 0xffff0000u); }
; __device__ __forceinline__ unsigned pk2(float lo, float hi) { return pg8::cvt_pk_bf16(lo, hi); }
; __device__ __forceinline__ float siluf(float x) { return x * __builtin_amdgcn_rcpf(1.0f + __expf(-x)); }
; __device__ __forceinline__ void hgrn_prep_phase(const bf16* z, const float* lbv, bf16* hq, float* dd, int tid, int G) {
;     ...
;             for (int tau = 0; tau < 32; ++tau) { const unsigned q2 = *(const unsigned*)(zq + (size_t)tau * ZP), f2 = *(const unsigned*)(zf + (size_t)tau * ZP);
;                 const float xf0 = fminf(fmaxf(bflo(f2), -30.f), 30.f), xf1 = fminf(fmaxf(bfhi(f2), -30.f), 30.f);
;                 const float e0 = __expf(-xf0), r0 = __builtin_amdgcn_rcpf(1.0f + e0), e1 = __expf(-xf1), r1 = __builtin_amdgcn_rcpf(1.0f + e1);
;                 const float f0 = lb0 + om0 * r0, f1 = lb1 + om1 * r1, k0v = om0 * (e0 * r0), k1v = om1 * (e1 * r1);
;                 bc0 += __logf(f0); bc1 += __logf(f1); kk0[tau] = k0v; kk1[tau] = k1v; bv0[tau] = bc0; bv1[tau] = bc1;
;                 *(unsigned*)(QT + tile + tau * 128 + kp) = pk2(siluf(bflo(q2)) * __expf(bc0), siluf(bfhi(q2)) * __expf(bc1));
;                 *(unsigned*)(KT + tile + tau * 128 + kp) = pk2(k0v * __expf(-bc0), k1v * __expf(-bc1)); }
	v_mov_b32_e32 v91, v198
	s_nop 0
	v_mov_b32_e32 v86, v199
	v_lshlrev_b32_e32 v87, 16, v86
	v_max_f32_e32 v87, v87, v87
	v_and_b32_e32 v86, 0xffff0000, v86
	v_med3_f32 v87, v87, s89, v225
	v_max_f32_e32 v86, v86, v86
	v_med3_f32 v89, v86, s89, v225
	v_mul_f32_e32 v86, 0xbfb8aa3b, v87
	v_exp_f32_e32 v86, v86
	s_nop 0
	v_add_f32_e32 v87, 1.0, v86
	v_rcp_f32_e32 v88, v87
	v_mul_f32_e32 v87, 0xbfb8aa3b, v89
	v_exp_f32_e32 v87, v87
	v_fma_f32 v90, v26, v88, v28
	v_cmp_gt_f32_e32 vcc, s83, v90
	v_add_f32_e32 v89, 1.0, v87
	v_rcp_f32_e32 v89, v89
	v_cndmask_b32_e64 v93, 0, 32, vcc
	v_ldexp_f32 v90, v90, v93
	v_log_f32_e32 v90, v90
	v_fma_f32 v92, v27, v89, v29
	v_pk_mul_f32 v[86:87], v[86:87], v[88:89]
	v_mul_f32_e32 v93, 0x3f317217, v90
	v_fma_f32 v93, v90, s90, -v93
	v_fmac_f32_e32 v93, 0x3377d1cf, v90
	v_fmac_f32_e32 v93, 0x3f317217, v90
	v_cmp_lt_f32_e64 s[10:11], |v90|, s91
	v_pk_mul_f32 v[86:87], v[26:27], v[86:87]
	s_nop 0
	v_cndmask_b32_e64 v90, v90, v93, s[10:11]
	v_cndmask_b32_e32 v93, 0, v226, vcc
	v_sub_f32_e32 v90, v90, v93
	v_cmp_gt_f32_e32 vcc, s83, v92
	v_add_f32_e32 v147, v145, v90
	s_nop 0
	v_cndmask_b32_e64 v90, 0, 32, vcc
	v_ldexp_f32 v90, v92, v90
	v_log_f32_e32 v90, v90
	s_nop 0
	v_mul_f32_e32 v92, 0x3f317217, v90
	v_fma_f32 v92, v90, s90, -v92
	v_fmac_f32_e32 v92, 0x3377d1cf, v90
	v_fmac_f32_e32 v92, 0x3f317217, v90
	v_cmp_lt_f32_e64 s[10:11], |v90|, s91
	s_nop 1
	v_cndmask_b32_e64 v90, v90, v92, s[10:11]
	v_cndmask_b32_e32 v92, 0, v226, vcc
	v_sub_f32_e32 v90, v90, v92
	v_add_f32_e32 v146, v144, v90
	v_lshlrev_b32_e32 v90, 16, v91
	v_and_b32_e32 v91, 0xffff0000, v91
	v_mul_f32_e32 v94, 0xbfb8aa3b, v90
	v_mul_f32_e32 v95, 0xbfb8aa3b, v91
	v_exp_f32_e32 v94, v94
	v_exp_f32_e32 v95, v95
	v_mul_f32_e32 v92, 0x3fb8aa3b, v147
	v_mul_f32_e32 v93, 0x3fb8aa3b, v146
	v_add_f32_e32 v94, 1.0, v94
	v_add_f32_e32 v95, 1.0, v95
	v_rcp_f32_e32 v94, v94
	v_rcp_f32_e32 v95, v95
	v_exp_f32_e32 v92, v92
	v_exp_f32_e32 v93, v93
	v_pk_mul_f32 v[90:91], v[94:95], v[90:91]
	s_nop 0
	v_pk_mul_f32 v[90:91], v[90:91], v[92:93]
	s_nop 0
	v_cvt_pk_bf16_f32 v90, v90, v91
	global_store_dword v[68:69], v90, off offset:2560
	v_mul_f32_e32 v90, 0xbfb8aa3b, v147
	v_mul_f32_e32 v91, 0xbfb8aa3b, v146
	v_exp_f32_e32 v90, v90
	v_exp_f32_e32 v91, v91
	s_nop 0
	v_pk_mul_f32 v[88:89], v[86:87], v[90:91]
	s_nop 0
	v_cvt_pk_bf16_f32 v88, v88, v89
	global_store_dword v[70:71], v88, off offset:2560
	v_add_co_u32_e32 v88, vcc, s0, v30
	s_mov_b32 s0, 0x98000
	s_nop 0
	v_addc_co_u32_e32 v89, vcc, 0, v31, vcc
	s_waitcnt vmcnt(38)
	v_mov_b32_e32 v93, v200
	v_add_co_u32_e32 v88, vcc, s0, v30
	s_mov_b32 s0, 0x9d000
	s_nop 0
	v_addc_co_u32_e32 v89, vcc, 0, v31, vcc
	v_mov_b32_e32 v88, v201
	v_lshlrev_b32_e32 v89, 16, v88
	v_max_f32_e32 v89, v89, v89
	v_and_b32_e32 v88, 0xffff0000, v88
	v_med3_f32 v89, v89, s89, v225
	v_max_f32_e32 v88, v88, v88
	v_med3_f32 v91, v88, s89, v225
	v_mul_f32_e32 v88, 0xbfb8aa3b, v89
	v_exp_f32_e32 v88, v88
	s_nop 0
	v_add_f32_e32 v89, 1.0, v88
	v_rcp_f32_e32 v90, v89
	v_mul_f32_e32 v89, 0xbfb8aa3b, v91
	v_exp_f32_e32 v89, v89
	v_fma_f32 v92, v26, v90, v28
	v_cmp_gt_f32_e32 vcc, s83, v92
	v_add_f32_e32 v91, 1.0, v89
	v_rcp_f32_e32 v91, v91
	v_cndmask_b32_e64 v95, 0, 32, vcc
	v_ldexp_f32 v92, v92, v95
	v_log_f32_e32 v92, v92
	v_fma_f32 v94, v27, v91, v29
	v_pk_mul_f32 v[88:89], v[88:89], v[90:91]
	v_mul_f32_e32 v95, 0x3f317217, v92
	v_fma_f32 v95, v92, s90, -v95
	v_fmac_f32_e32 v95, 0x3377d1cf, v92
	v_fmac_f32_e32 v95, 0x3f317217, v92
	v_cmp_lt_f32_e64 s[10:11], |v92|, s91
	v_pk_mul_f32 v[88:89], v[26:27], v[88:89]
	s_nop 0
	v_cndmask_b32_e64 v92, v92, v95, s[10:11]
	v_cndmask_b32_e32 v95, 0, v226, vcc
	v_sub_f32_e32 v92, v92, v95
	v_cmp_gt_f32_e32 vcc, s83, v94
	v_add_f32_e32 v149, v147, v92
	s_nop 0
	v_cndmask_b32_e64 v92, 0, 32, vcc
	v_ldexp_f32 v92, v94, v92
	v_log_f32_e32 v92, v92
	s_nop 0
	v_mul_f32_e32 v94, 0x3f317217, v92
	v_fma_f32 v94, v92, s90, -v94
	v_fmac_f32_e32 v94, 0x3377d1cf, v92
	v_fmac_f32_e32 v94, 0x3f317217, v92
	v_cmp_lt_f32_e64 s[10:11], |v92|, s91
	s_nop 1
	v_cndmask_b32_e64 v92, v92, v94, s[10:11]
	v_cndmask_b32_e32 v94, 0, v226, vcc
	v_sub_f32_e32 v92, v92, v94
	v_add_f32_e32 v148, v146, v92
	v_lshlrev_b32_e32 v92, 16, v93
	v_and_b32_e32 v93, 0xffff0000, v93
	v_mul_f32_e32 v150, 0xbfb8aa3b, v92
	v_mul_f32_e32 v151, 0xbfb8aa3b, v93
	v_exp_f32_e32 v150, v150
	v_exp_f32_e32 v151, v151
	v_mul_f32_e32 v94, 0x3fb8aa3b, v149
	v_mul_f32_e32 v95, 0x3fb8aa3b, v148
	v_add_f32_e32 v150, 1.0, v150
	v_add_f32_e32 v151, 1.0, v151
	v_rcp_f32_e32 v150, v150
	v_rcp_f32_e32 v151, v151
	v_exp_f32_e32 v94, v94
	v_exp_f32_e32 v95, v95
	v_pk_mul_f32 v[92:93], v[150:151], v[92:93]
	s_nop 0
	v_pk_mul_f32 v[92:93], v[92:93], v[94:95]
	s_nop 0
	v_cvt_pk_bf16_f32 v92, v92, v93
	global_store_dword v[68:69], v92, off offset:2816
	v_mul_f32_e32 v92, 0xbfb8aa3b, v149
	v_mul_f32_e32 v93, 0xbfb8aa3b, v148
	v_exp_f32_e32 v92, v92
	v_exp_f32_e32 v93, v93
	s_nop 0
	v_pk_mul_f32 v[90:91], v[88:89], v[92:93]
	s_nop 0
	v_cvt_pk_bf16_f32 v90, v90, v91
	global_store_dword v[70:71], v90, off offset:2816
	v_add_co_u32_e32 v90, vcc, s0, v30
	s_mov_b32 s0, 0xa3000
	s_nop 0
	v_addc_co_u32_e32 v91, vcc, 0, v31, vcc
	s_waitcnt vmcnt(36)
; __device__ __forceinline__ float bflo(unsigned w) { return __uint_as_float(w << 16); }
; __device__ __forceinline__ float bfhi(unsigned w) { return __uint_as_float(w & 0xffff0000u); }
; __device__ __forceinline__ unsigned pk2(float lo, float hi) { return pg8::cvt_pk_bf16(lo, hi); }
; __device__ __forceinline__ float siluf(float x) { return x * __builtin_amdgcn_rcpf(1.0f + __expf(-x)); }
; __device__ __forceinline__ void hgrn_prep_phase(const bf16* z, const float* lbv, bf16* hq, float* dd, int tid, int G) {
;     ...
;             for (int tau = 0; tau < 32; ++tau) { const unsigned q2 = *(const unsigned*)(zq + (size_t)tau * ZP), f2 = *(const unsigned*)(zf + (size_t)tau * ZP);
;                 const float xf0 = fminf(fmaxf(bflo(f2), -30.f), 30.f), xf1 = fminf(fmaxf(bfhi(f2), -30.f), 30.f);
;                 const float e0 = __expf(-xf0), r0 = __builtin_amdgcn_rcpf(1.0f + e0), e1 = __expf(-xf1), r1 = __builtin_amdgcn_rcpf(1.0f + e1);
;                 const float f0 = lb0 + om0 * r0, f1 = lb1 + om1 * r1, k0v = om0 * (e0 * r0), k1v = om1 * (e1 * r1);
;                 bc0 += __logf(f0); bc1 += __logf(f1); kk0[tau] = k0v; kk1[tau] = k1v; bv0[tau] = bc0; bv1[tau] = bc1;
;                 *(unsigned*)(QT + tile + tau * 128 + kp) = pk2(siluf(bflo(q2)) * __expf(bc0), siluf(bfhi(q2)) * __expf(bc1));
;                 *(unsigned*)(KT + tile + tau * 128 + kp) = pk2(k0v * __expf(-bc0), k1v * __expf(-bc1)); }
	v_mov_b32_e32 v95, v202
	s_nop 0
	v_mov_b32_e32 v90, v203
	v_lshlrev_b32_e32 v91, 16, v90
	v_max_f32_e32 v91, v91, v91
	v_and_b32_e32 v90, 0xffff0000, v90
	v_med3_f32 v91, v91, s89, v225
	v_max_f32_e32 v90, v90, v90
	v_med3_f32 v93, v90, s89, v225
	v_mul_f32_e32 v90, 0xbfb8aa3b, v91
	v_exp_f32_e32 v90, v90
	s_nop 0
	v_add_f32_e32 v91, 1.0, v90
	v_rcp_f32_e32 v92, v91
	v_mul_f32_e32 v91, 0xbfb8aa3b, v93
	v_exp_f32_e32 v91, v91
	v_fma_f32 v94, v26, v92, v28
	v_cmp_gt_f32_e32 vcc, s83, v94
	v_add_f32_e32 v93, 1.0, v91
	v_rcp_f32_e32 v93, v93
	v_cndmask_b32_e64 v151, 0, 32, vcc
	v_ldexp_f32 v94, v94, v151
	v_log_f32_e32 v94, v94
	v_fma_f32 v150, v27, v93, v29
	v_pk_mul_f32 v[90:91], v[90:91], v[92:93]
	v_mul_f32_e32 v151, 0x3f317217, v94
	v_fma_f32 v151, v94, s90, -v151
	v_fmac_f32_e32 v151, 0x3377d1cf, v94
	v_fmac_f32_e32 v151, 0x3f317217, v94
	v_cmp_lt_f32_e64 s[10:11], |v94|, s91
	v_pk_mul_f32 v[90:91], v[26:27], v[90:91]
	s_nop 0
	v_cndmask_b32_e64 v94, v94, v151, s[10:11]
	v_cndmask_b32_e32 v151, 0, v226, vcc
	v_sub_f32_e32 v94, v94, v151
	v_cmp_gt_f32_e32 vcc, s83, v150
	v_add_f32_e32 v151, v149, v94
	v_mul_f32_e32 v152, 0x3fb8aa3b, v151
	v_cndmask_b32_e64 v94, 0, 32, vcc
	v_ldexp_f32 v94, v150, v94
	v_log_f32_e32 v94, v94
	v_exp_f32_e32 v152, v152
	v_mul_f32_e32 v150, 0x3f317217, v94
	v_fma_f32 v150, v94, s90, -v150
	v_fmac_f32_e32 v150, 0x3377d1cf, v94
	v_fmac_f32_e32 v150, 0x3f317217, v94
	v_cmp_lt_f32_e64 s[10:11], |v94|, s91
	s_nop 1
	v_cndmask_b32_e64 v94, v94, v150, s[10:11]
	v_cndmask_b32_e32 v150, 0, v226, vcc
	v_sub_f32_e32 v94, v94, v150
	v_add_f32_e32 v150, v148, v94
	v_lshlrev_b32_e32 v94, 16, v95
	v_and_b32_e32 v95, 0xffff0000, v95
	v_mul_f32_e32 v154, 0xbfb8aa3b, v94
	v_mul_f32_e32 v155, 0xbfb8aa3b, v95
	v_exp_f32_e32 v154, v154
	v_exp_f32_e32 v155, v155
	v_mul_f32_e32 v153, 0x3fb8aa3b, v150
	v_exp_f32_e32 v153, v153
	v_add_f32_e32 v154, 1.0, v154
	v_add_f32_e32 v155, 1.0, v155
	v_rcp_f32_e32 v154, v154
	v_rcp_f32_e32 v155, v155
	s_nop 0
	v_pk_mul_f32 v[94:95], v[154:155], v[94:95]
	s_nop 0
	v_pk_mul_f32 v[94:95], v[94:95], v[152:153]
	s_nop 0
	v_cvt_pk_bf16_f32 v94, v94, v95
	global_store_dword v[68:69], v94, off offset:3072
	v_mul_f32_e32 v94, 0xbfb8aa3b, v151
	v_mul_f32_e32 v95, 0xbfb8aa3b, v150
	v_exp_f32_e32 v94, v94
	v_exp_f32_e32 v95, v95
	s_nop 0
	v_pk_mul_f32 v[92:93], v[90:91], v[94:95]
	s_nop 0
	v_cvt_pk_bf16_f32 v92, v92, v93
	global_store_dword v[70:71], v92, off offset:3072
	v_add_co_u32_e32 v92, vcc, s0, v30
	s_mov_b32 s0, 0xa8000
	s_nop 0
	v_addc_co_u32_e32 v93, vcc, 0, v31, vcc
	s_waitcnt vmcnt(34)
	v_mov_b32_e32 v153, v204
	s_nop 0
	v_mov_b32_e32 v92, v205
	v_lshlrev_b32_e32 v156, 16, v153
	v_lshlrev_b32_e32 v93, 16, v92
	v_max_f32_e32 v93, v93, v93
	v_and_b32_e32 v92, 0xffff0000, v92
	v_med3_f32 v93, v93, s89, v225
	v_max_f32_e32 v92, v92, v92
	v_med3_f32 v95, v92, s89, v225
	v_mul_f32_e32 v92, 0xbfb8aa3b, v93
	v_exp_f32_e32 v92, v92
	v_and_b32_e32 v157, 0xffff0000, v153
	v_add_f32_e32 v93, 1.0, v92
	v_rcp_f32_e32 v94, v93
	v_mul_f32_e32 v93, 0xbfb8aa3b, v95
	v_exp_f32_e32 v93, v93
	v_fma_f32 v152, v26, v94, v28
	v_cmp_gt_f32_e32 vcc, s83, v152
	v_add_f32_e32 v95, 1.0, v93
	v_rcp_f32_e32 v95, v95
	v_cndmask_b32_e64 v154, 0, 32, vcc
	v_ldexp_f32 v152, v152, v154
	v_log_f32_e32 v152, v152
	v_fma_f32 v155, v27, v95, v29
	v_pk_mul_f32 v[92:93], v[92:93], v[94:95]
	v_mul_f32_e32 v154, 0x3f317217, v152
	v_fma_f32 v154, v152, s90, -v154
	v_fmac_f32_e32 v154, 0x3377d1cf, v152
	v_fmac_f32_e32 v154, 0x3f317217, v152
	v_cmp_lt_f32_e64 s[10:11], |v152|, s91
	v_pk_mul_f32 v[94:95], v[26:27], v[92:93]
	s_nop 0
	v_cndmask_b32_e64 v152, v152, v154, s[10:11]
	v_cndmask_b32_e32 v154, 0, v226, vcc
	v_sub_f32_e32 v152, v152, v154
	v_cmp_gt_f32_e32 vcc, s83, v155
	v_add_f32_e32 v154, v151, v152
	s_nop 0
	v_cndmask_b32_e64 v152, 0, 32, vcc
	v_ldexp_f32 v152, v155, v152
	v_log_f32_e32 v152, v152
	s_nop 0
	v_mul_f32_e32 v155, 0x3f317217, v152
	v_fma_f32 v155, v152, s90, -v155
	v_fmac_f32_e32 v155, 0x3377d1cf, v152
	v_fmac_f32_e32 v155, 0x3f317217, v152
	v_cmp_lt_f32_e64 s[10:11], |v152|, s91
	s_nop 1
	v_cndmask_b32_e64 v152, v152, v155, s[10:11]
	v_cndmask_b32_e32 v155, 0, v226, vcc
	v_sub_f32_e32 v152, v152, v155
	v_add_f32_e32 v152, v150, v152
	v_mul_f32_e32 v153, 0x3fb8aa3b, v152
	v_exp_f32_e32 v159, v153
	v_mul_f32_e32 v153, 0xbfb8aa3b, v156
	v_exp_f32_e32 v153, v153
	v_mul_f32_e32 v155, 0x3fb8aa3b, v154
	v_exp_f32_e32 v158, v155
	v_add_f32_e32 v153, 1.0, v153
	v_rcp_f32_e32 v160, v153
	v_mul_f32_e32 v153, 0xbfb8aa3b, v157
	v_exp_f32_e32 v153, v153
	s_nop 0
	v_add_f32_e32 v153, 1.0, v153
	v_rcp_f32_e32 v161, v153
	s_nop 0
	v_pk_mul_f32 v[156:157], v[160:161], v[156:157]
	s_nop 0
	v_pk_mul_f32 v[156:157], v[156:157], v[158:159]
	s_nop 0
	v_cvt_pk_bf16_f32 v153, v156, v157
	global_store_dword v[68:69], v153, off offset:3328
	v_mul_f32_e32 v153, 0xbfb8aa3b, v154
	v_exp_f32_e32 v156, v153
	v_mul_f32_e32 v153, 0xbfb8aa3b, v152
	v_exp_f32_e32 v157, v153
	s_nop 0
	v_pk_mul_f32 v[92:93], v[94:95], v[156:157]
	s_nop 0
	v_cvt_pk_bf16_f32 v92, v92, v93
	global_store_dword v[70:71], v92, off offset:3328
	v_add_co_u32_e32 v92, vcc, s0, v30
	s_mov_b32 s0, 0xa9000
	s_nop 0
	v_addc_co_u32_e32 v93, vcc, 0, v31, vcc
	v_add_co_u32_e32 v156, vcc, s0, v30
	s_waitcnt vmcnt(32)
; __device__ __forceinline__ float bflo(unsigned w) { return __uint_as_float(w << 16); }
; __device__ __forceinline__ float bfhi(unsigned w) { return __uint_as_float(w & 0xffff0000u); }
; __device__ __forceinline__ unsigned pk2(float lo, float hi) { return pg8::cvt_pk_bf16(lo, hi); }
; __device__ __forceinline__ float siluf(float x) { return x * __builtin_amdgcn_rcpf(1.0f + __expf(-x)); }
; __device__ __forceinline__ void hgrn_prep_phase(const bf16* z, const float* lbv, bf16* hq, float* dd, int tid, int G) {
;     ...
;             for (int tau = 0; tau < 32; ++tau) { const unsigned q2 = *(const unsigned*)(zq + (size_t)tau * ZP), f2 = *(const unsigned*)(zf + (size_t)tau * ZP);
;                 const float xf0 = fminf(fmaxf(bflo(f2), -30.f), 30.f), xf1 = fminf(fmaxf(bfhi(f2), -30.f), 30.f);
;                 const float e0 = __expf(-xf0), r0 = __builtin_amdgcn_rcpf(1.0f + e0), e1 = __expf(-xf1), r1 = __builtin_amdgcn_rcpf(1.0f + e1);
;                 const float f0 = lb0 + om0 * r0, f1 = lb1 + om1 * r1, k0v = om0 * (e0 * r0), k1v = om1 * (e1 * r1);
;                 bc0 += __logf(f0); bc1 += __logf(f1); kk0[tau] = k0v; kk1[tau] = k1v; bv0[tau] = bc0; bv1[tau] = bc1;
;                 *(unsigned*)(QT + tile + tau * 128 + kp) = pk2(siluf(bflo(q2)) * __expf(bc0), siluf(bfhi(q2)) * __expf(bc1));
;                 *(unsigned*)(KT + tile + tau * 128 + kp) = pk2(k0v * __expf(-bc0), k1v * __expf(-bc1)); }
;             *(float2*)(dd + ((size_t)bh * 64 + c) * 128 + k) = make_float2(__expf(bc0), __expf(bc1));
; #pragma unroll
;             for (int g4 = 0; g4 < 4; ++g4) { float v[8]; u32x4 o;
; #pragma unroll
;                 for (int i = 0; i < 8; ++i) v[i] = kk0[8 * g4 + i] * __expf(bc0 - bv0[8 * g4 + i]);
;                 o.x = pk2(v[0], v[1]); o.y = pk2(v[2], v[3]); o.z = pk2(v[4], v[5]); o.w = pk2(v[6], v[7]); *(u32x4*)(KHT + tile + k * 32 + 8 * g4) = o;
; #pragma unroll
;                 for (int i = 0; i < 8; ++i) v[i] = kk1[8 * g4 + i] * __expf(bc1 - bv1[8 * g4 + i]);
;                 o.x = pk2(v[0], v[1]); o.y = pk2(v[2], v[3]); o.z = pk2(v[4], v[5]); o.w = pk2(v[6], v[7]); *(u32x4*)(KHT + tile + (k + 1) * 32 + 8 * g4) = o; }
	v_mov_b32_e32 v92, v206
	s_nop 0
	v_addc_co_u32_e32 v157, vcc, 0, v31, vcc
	v_mov_b32_e32 v93, v207
	s_mov_b32 s0, 0xae000
	v_lshlrev_b32_e32 v160, 16, v92
	v_and_b32_e32 v161, 0xffff0000, v92
	v_lshlrev_b32_e32 v153, 16, v93
	v_max_f32_e32 v153, v153, v153
	v_med3_f32 v153, v153, s89, v225
	v_mul_f32_e32 v153, 0xbfb8aa3b, v153
	v_and_b32_e32 v93, 0xffff0000, v93
	v_exp_f32_e32 v156, v153
	v_max_f32_e32 v93, v93, v93
	v_med3_f32 v93, v93, s89, v225
	v_mul_f32_e32 v93, 0xbfb8aa3b, v93
	v_add_f32_e32 v153, 1.0, v156
	v_exp_f32_e32 v157, v93
	v_rcp_f32_e32 v158, v153
	v_add_f32_e32 v93, 1.0, v157
	v_rcp_f32_e32 v159, v93
	v_fma_f32 v93, v26, v158, v28
	v_cmp_gt_f32_e32 vcc, s83, v93
	v_fma_f32 v153, v27, v159, v29
	s_nop 0
	v_cndmask_b32_e64 v155, 0, 32, vcc
	v_ldexp_f32 v93, v93, v155
	v_log_f32_e32 v93, v93
	s_nop 0
	v_mul_f32_e32 v155, 0x3f317217, v93
	v_fma_f32 v155, v93, s90, -v155
	v_fmac_f32_e32 v155, 0x3377d1cf, v93
	v_fmac_f32_e32 v155, 0x3f317217, v93
	v_cmp_lt_f32_e64 s[10:11], |v93|, s91
	s_nop 1
	v_cndmask_b32_e64 v93, v93, v155, s[10:11]
	v_cndmask_b32_e32 v155, 0, v226, vcc
	v_sub_f32_e32 v93, v93, v155
	v_cmp_gt_f32_e32 vcc, s83, v153
	v_add_f32_e32 v155, v154, v93
	s_nop 0
	v_cndmask_b32_e64 v93, 0, 32, vcc
	v_ldexp_f32 v93, v153, v93
	v_log_f32_e32 v93, v93
	s_nop 0
	v_mul_f32_e32 v153, 0x3f317217, v93
	v_fma_f32 v153, v93, s90, -v153
	v_fmac_f32_e32 v153, 0x3377d1cf, v93
	v_fmac_f32_e32 v153, 0x3f317217, v93
	v_cmp_lt_f32_e64 s[10:11], |v93|, s91
	s_nop 1
	v_cndmask_b32_e64 v93, v93, v153, s[10:11]
	v_cndmask_b32_e32 v153, 0, v226, vcc
	v_sub_f32_e32 v93, v93, v153
	v_add_f32_e32 v153, v152, v93
	v_mul_f32_e32 v93, 0x3fb8aa3b, v155
	v_mul_f32_e32 v92, 0x3fb8aa3b, v153
	v_exp_f32_e32 v162, v93
	v_exp_f32_e32 v163, v92
	v_mul_f32_e32 v92, 0xbfb8aa3b, v160
	v_mul_f32_e32 v93, 0xbfb8aa3b, v161
	v_exp_f32_e32 v92, v92
	v_exp_f32_e32 v93, v93
	v_add_co_u32_e32 v30, vcc, s0, v30
	v_add_f32_e32 v92, 1.0, v92
	v_add_f32_e32 v93, 1.0, v93
	v_rcp_f32_e32 v92, v92
	v_rcp_f32_e32 v93, v93
	v_addc_co_u32_e32 v31, vcc, 0, v31, vcc
	v_pk_mul_f32 v[92:93], v[92:93], v[160:161]
	s_nop 0
	v_pk_mul_f32 v[92:93], v[92:93], v[162:163]
	s_nop 0
	v_cvt_pk_bf16_f32 v92, v92, v93
	global_store_dword v[68:69], v92, off offset:3584
	v_mul_f32_e32 v92, 0xbfb8aa3b, v155
	v_exp_f32_e32 v160, v92
	v_mul_f32_e32 v92, 0xbfb8aa3b, v153
	v_exp_f32_e32 v161, v92
	v_pk_mul_f32 v[92:93], v[156:157], v[158:159]
	s_nop 0
	v_pk_mul_f32 v[92:93], v[26:27], v[92:93]
	s_nop 0
	v_pk_mul_f32 v[156:157], v[92:93], v[160:161]
	s_nop 0
	v_cvt_pk_bf16_f32 v156, v156, v157
	global_store_dword v[70:71], v156, off offset:3584
	s_waitcnt vmcnt(30)
	v_mov_b32_e32 v161, v208
	s_nop 0
	v_mov_b32_e32 v30, v209
	v_lshlrev_b32_e32 v160, 16, v161
	v_lshlrev_b32_e32 v31, 16, v30
	v_max_f32_e32 v31, v31, v31
	v_med3_f32 v31, v31, s89, v225
	v_mul_f32_e32 v31, 0xbfb8aa3b, v31
	v_exp_f32_e32 v156, v31
	v_and_b32_e32 v30, 0xffff0000, v30
	v_max_f32_e32 v30, v30, v30
	v_med3_f32 v30, v30, s89, v225
	v_add_f32_e32 v31, 1.0, v156
	v_rcp_f32_e32 v158, v31
	v_mul_f32_e32 v30, 0xbfb8aa3b, v30
	v_exp_f32_e32 v157, v30
	v_and_b32_e32 v161, 0xffff0000, v161
	v_fma_f32 v28, v26, v158, v28
	v_cmp_gt_f32_e32 vcc, s83, v28
	v_add_f32_e32 v30, 1.0, v157
	v_rcp_f32_e32 v159, v30
	v_cndmask_b32_e64 v30, 0, 32, vcc
	v_ldexp_f32 v28, v28, v30
	v_log_f32_e32 v28, v28
	v_fmac_f32_e32 v29, v27, v159
	v_mul_f32_e32 v162, 0xbfb8aa3b, v160
	v_mul_f32_e32 v163, 0xbfb8aa3b, v161
	v_mul_f32_e32 v30, 0x3f317217, v28
	v_fma_f32 v30, v28, s90, -v30
	v_fmac_f32_e32 v30, 0x3377d1cf, v28
	v_fmac_f32_e32 v30, 0x3f317217, v28
	v_cmp_lt_f32_e64 s[10:11], |v28|, s91
	v_exp_f32_e32 v162, v162
	v_exp_f32_e32 v163, v163
	v_cndmask_b32_e64 v28, v28, v30, s[10:11]
	v_cndmask_b32_e32 v30, 0, v226, vcc
	v_sub_f32_e32 v28, v28, v30
	v_cmp_gt_f32_e32 vcc, s83, v29
	v_add_f32_e32 v31, v155, v28
	v_add_f32_e32 v162, 1.0, v162
	v_cndmask_b32_e64 v28, 0, 32, vcc
	v_ldexp_f32 v28, v29, v28
	v_log_f32_e32 v28, v28
	v_add_f32_e32 v163, 1.0, v163
	v_rcp_f32_e32 v162, v162
	v_rcp_f32_e32 v163, v163
	v_mul_f32_e32 v29, 0x3f317217, v28
	v_fma_f32 v29, v28, s90, -v29
	v_fmac_f32_e32 v29, 0x3377d1cf, v28
	v_fmac_f32_e32 v29, 0x3f317217, v28
	v_cmp_lt_f32_e64 s[10:11], |v28|, s91
	v_pk_mul_f32 v[160:161], v[162:163], v[160:161]
	v_pk_mul_f32 v[156:157], v[156:157], v[158:159]
	v_cndmask_b32_e64 v28, v28, v29, s[10:11]
	v_cndmask_b32_e32 v29, 0, v226, vcc
	v_sub_f32_e32 v28, v28, v29
	v_add_f32_e32 v30, v153, v28
	v_mul_f32_e32 v28, 0x3fb8aa3b, v31
	v_mul_f32_e32 v29, 0x3fb8aa3b, v30
	v_exp_f32_e32 v28, v28
	v_exp_f32_e32 v29, v29
	v_pk_mul_f32 v[26:27], v[26:27], v[156:157]
	v_sub_f32_e32 v9, v31, v9
	v_mul_f32_e32 v9, 0x3fb8aa3b, v9
	v_pk_mul_f32 v[160:161], v[160:161], v[28:29]
	v_sub_f32_e32 v2, v30, v2
	v_cvt_pk_bf16_f32 v160, v160, v161
	global_store_dword v[68:69], v160, off offset:3840
	v_mul_f32_e32 v68, 0xbfb8aa3b, v31
	v_mul_f32_e32 v69, 0xbfb8aa3b, v30
	v_exp_f32_e32 v68, v68
	v_exp_f32_e32 v69, v69
	v_mov_b32_e32 v156, v42
	v_mov_b32_e32 v157, v44
	v_mul_f32_e32 v2, 0x3fb8aa3b, v2
	v_pk_mul_f32 v[68:69], v[26:27], v[68:69]
	v_mov_b32_e32 v44, v43
	v_cvt_pk_bf16_f32 v68, v68, v69
	global_store_dword v[70:71], v68, off offset:3840
	global_store_dwordx2 v[24:25], v[28:29], off
	v_exp_f32_e32 v24, v9
	v_sub_f32_e32 v9, v31, v97
	v_mul_f32_e32 v9, 0x3fb8aa3b, v9
	v_exp_f32_e32 v25, v9
	v_mov_b32_e32 v28, v4
	v_sub_f32_e32 v4, v31, v99
	v_mov_b32_e32 v29, v32
	v_mul_f32_e32 v4, 0x3fb8aa3b, v4
	v_pk_mul_f32 v[24:25], v[28:29], v[24:25]
	v_exp_f32_e32 v28, v4
	v_sub_f32_e32 v4, v31, v101
	v_mul_f32_e32 v4, 0x3fb8aa3b, v4
	v_exp_f32_e32 v29, v4
; __device__ __forceinline__ unsigned pk2(float lo, float hi) { return pg8::cvt_pk_bf16(lo, hi); }
; __device__ __forceinline__ void hgrn_prep_phase(const bf16* z, const float* lbv, bf16* hq, float* dd, int tid, int G) {
;     ...
; #pragma unroll
;             for (int g4 = 0; g4 < 4; ++g4) { float v[8]; u32x4 o;
; #pragma unroll
;                 for (int i = 0; i < 8; ++i) v[i] = kk0[8 * g4 + i] * __expf(bc0 - bv0[8 * g4 + i]);
;                 o.x = pk2(v[0], v[1]); o.y = pk2(v[2], v[3]); o.z = pk2(v[4], v[5]); o.w = pk2(v[6], v[7]); *(u32x4*)(KHT + tile + k * 32 + 8 * g4) = o;
; #pragma unroll
;                 for (int i = 0; i < 8; ++i) v[i] = kk1[8 * g4 + i] * __expf(bc1 - bv1[8 * g4 + i]);
;                 o.x = pk2(v[0], v[1]); o.y = pk2(v[2], v[3]); o.z = pk2(v[4], v[5]); o.w = pk2(v[6], v[7]); *(u32x4*)(KHT + tile + (k + 1) * 32 + 8 * g4) = o; }
	v_sub_f32_e32 v4, v31, v103
	v_mov_b32_e32 v68, v34
	v_mov_b32_e32 v69, v36
	v_mul_f32_e32 v4, 0x3fb8aa3b, v4
	v_pk_mul_f32 v[28:29], v[68:69], v[28:29]
	v_exp_f32_e32 v68, v4
	v_sub_f32_e32 v4, v31, v105
	v_mul_f32_e32 v4, 0x3fb8aa3b, v4
	v_exp_f32_e32 v69, v4
	v_sub_f32_e32 v4, v31, v107
	v_mov_b32_e32 v70, v38
	v_mov_b32_e32 v71, v40
	v_mul_f32_e32 v4, 0x3fb8aa3b, v4
	v_pk_mul_f32 v[70:71], v[70:71], v[68:69]
	v_exp_f32_e32 v68, v4
	v_sub_f32_e32 v4, v31, v109
	v_mul_f32_e32 v4, 0x3fb8aa3b, v4
	v_exp_f32_e32 v69, v4
	v_mov_b32_e32 v32, v5
	v_mov_b32_e32 v36, v35
	v_mov_b32_e32 v40, v39
	v_pk_mul_f32 v[156:157], v[156:157], v[68:69]
	v_cvt_pk_bf16_f32 v68, v24, v25
	v_exp_f32_e32 v24, v2
	v_sub_f32_e32 v2, v30, v96
	v_mul_f32_e32 v2, 0x3fb8aa3b, v2
	v_exp_f32_e32 v25, v2
	v_sub_f32_e32 v2, v30, v98
	v_mul_f32_e32 v2, 0x3fb8aa3b, v2
	v_cvt_pk_bf16_f32 v69, v28, v29
	v_pk_mul_f32 v[4:5], v[32:33], v[24:25]
	v_exp_f32_e32 v24, v2
	v_sub_f32_e32 v2, v30, v100
	v_mul_f32_e32 v2, 0x3fb8aa3b, v2
	v_exp_f32_e32 v25, v2
	v_sub_f32_e32 v2, v30, v102
	v_mul_f32_e32 v2, 0x3fb8aa3b, v2
	v_exp_f32_e32 v28, v2
	v_sub_f32_e32 v2, v30, v104
	v_mul_f32_e32 v2, 0x3fb8aa3b, v2
	v_exp_f32_e32 v29, v2
	v_sub_f32_e32 v2, v30, v106
	v_mul_f32_e32 v2, 0x3fb8aa3b, v2
	v_exp_f32_e32 v32, v2
	v_sub_f32_e32 v2, v30, v108
	v_mul_f32_e32 v2, 0x3fb8aa3b, v2
	v_exp_f32_e32 v33, v2
	v_sub_f32_e32 v2, v31, v111
	v_mul_f32_e32 v2, 0x3fb8aa3b, v2
	v_pk_mul_f32 v[24:25], v[36:37], v[24:25]
	v_pk_mul_f32 v[36:37], v[44:45], v[32:33]
	v_cvt_pk_bf16_f32 v32, v4, v5
	v_exp_f32_e32 v4, v2
	v_sub_f32_e32 v2, v31, v113
	v_mul_f32_e32 v2, 0x3fb8aa3b, v2
	v_exp_f32_e32 v5, v2
	v_sub_f32_e32 v2, v31, v115
	v_cvt_pk_bf16_f32 v33, v24, v25
	v_mov_b32_e32 v24, v46
	v_mov_b32_e32 v25, v48
	v_mul_f32_e32 v2, 0x3fb8aa3b, v2
	v_pk_mul_f32 v[4:5], v[24:25], v[4:5]
	v_exp_f32_e32 v24, v2
	v_sub_f32_e32 v2, v31, v117
	v_mul_f32_e32 v2, 0x3fb8aa3b, v2
	v_exp_f32_e32 v25, v2
	v_pk_mul_f32 v[28:29], v[40:41], v[28:29]
	v_sub_f32_e32 v2, v31, v119
	v_cvt_pk_bf16_f32 v34, v28, v29
	v_mov_b32_e32 v28, v50
	v_mov_b32_e32 v29, v52
	v_mul_f32_e32 v2, 0x3fb8aa3b, v2
	v_pk_mul_f32 v[24:25], v[28:29], v[24:25]
	v_exp_f32_e32 v28, v2
	v_sub_f32_e32 v2, v31, v121
	v_mul_f32_e32 v2, 0x3fb8aa3b, v2
	v_exp_f32_e32 v29, v2
	v_cvt_pk_bf16_f32 v35, v36, v37
	v_sub_f32_e32 v2, v31, v123
	global_store_dwordx4 v[6:7], v[32:35], off offset:64
	v_mul_f32_e32 v2, 0x3fb8aa3b, v2
	v_mov_b32_e32 v48, v47
	v_mov_b32_e32 v32, v54
	v_mov_b32_e32 v33, v56
	v_pk_mul_f32 v[28:29], v[32:33], v[28:29]
	v_exp_f32_e32 v32, v2
	v_sub_f32_e32 v2, v31, v125
	v_mul_f32_e32 v2, 0x3fb8aa3b, v2
	v_exp_f32_e32 v33, v2
	v_sub_f32_e32 v2, v30, v110
	v_mov_b32_e32 v34, v58
	v_mov_b32_e32 v35, v60
	v_mul_f32_e32 v2, 0x3fb8aa3b, v2
	v_pk_mul_f32 v[36:37], v[34:35], v[32:33]
	v_cvt_pk_bf16_f32 v32, v4, v5
	v_exp_f32_e32 v4, v2
	v_sub_f32_e32 v2, v30, v112
	v_mul_f32_e32 v2, 0x3fb8aa3b, v2
	v_exp_f32_e32 v5, v2
	v_sub_f32_e32 v2, v30, v114
	v_mul_f32_e32 v2, 0x3fb8aa3b, v2
	v_cvt_pk_bf16_f32 v33, v24, v25
	v_exp_f32_e32 v24, v2
	v_sub_f32_e32 v2, v30, v116
	v_mul_f32_e32 v2, 0x3fb8aa3b, v2
	v_exp_f32_e32 v25, v2
	v_sub_f32_e32 v2, v30, v118
	v_mul_f32_e32 v2, 0x3fb8aa3b, v2
	v_cvt_pk_bf16_f32 v34, v28, v29
	v_exp_f32_e32 v28, v2
	v_sub_f32_e32 v2, v30, v120
	v_mul_f32_e32 v2, 0x3fb8aa3b, v2
	v_exp_f32_e32 v29, v2
	v_sub_f32_e32 v2, v30, v122
	v_cvt_pk_bf16_f32 v35, v36, v37
	v_mul_f32_e32 v2, 0x3fb8aa3b, v2
	global_store_dwordx4 v[6:7], v[32:35], off offset:16
	v_pk_mul_f32 v[4:5], v[48:49], v[4:5]
	v_mov_b32_e32 v60, v59
	v_exp_f32_e32 v32, v2
	v_sub_f32_e32 v2, v30, v124
	v_mul_f32_e32 v2, 0x3fb8aa3b, v2
	v_exp_f32_e32 v33, v2
	v_sub_f32_e32 v2, v31, v127
	v_mul_f32_e32 v2, 0x3fb8aa3b, v2
	v_mov_b32_e32 v52, v51
	v_pk_mul_f32 v[36:37], v[60:61], v[32:33]
	v_cvt_pk_bf16_f32 v32, v4, v5
	v_exp_f32_e32 v4, v2
	v_sub_f32_e32 v2, v31, v129
	v_mul_f32_e32 v2, 0x3fb8aa3b, v2
	v_exp_f32_e32 v5, v2
	v_pk_mul_f32 v[24:25], v[52:53], v[24:25]
	v_sub_f32_e32 v2, v31, v131
	v_cvt_pk_bf16_f32 v33, v24, v25
	v_mov_b32_e32 v24, v62
	v_mov_b32_e32 v25, v64
	v_mul_f32_e32 v2, 0x3fb8aa3b, v2
	v_pk_mul_f32 v[4:5], v[24:25], v[4:5]
	v_exp_f32_e32 v24, v2
	v_sub_f32_e32 v2, v31, v133
	v_mul_f32_e32 v2, 0x3fb8aa3b, v2
	v_exp_f32_e32 v25, v2
	v_mov_b32_e32 v56, v55
	v_pk_mul_f32 v[28:29], v[56:57], v[28:29]
	v_sub_f32_e32 v2, v31, v135
	v_cvt_pk_bf16_f32 v34, v28, v29
	v_mov_b32_e32 v28, v66
; __device__ __forceinline__ unsigned pk2(float lo, float hi) { return pg8::cvt_pk_bf16(lo, hi); }
; __device__ __forceinline__ void hgrn_prep_phase(const bf16* z, const float* lbv, bf16* hq, float* dd, int tid, int G) {
;     ...
; #pragma unroll
;             for (int g4 = 0; g4 < 4; ++g4) { float v[8]; u32x4 o;
; #pragma unroll
;                 for (int i = 0; i < 8; ++i) v[i] = kk0[8 * g4 + i] * __expf(bc0 - bv0[8 * g4 + i]);
;                 o.x = pk2(v[0], v[1]); o.y = pk2(v[2], v[3]); o.z = pk2(v[4], v[5]); o.w = pk2(v[6], v[7]); *(u32x4*)(KHT + tile + k * 32 + 8 * g4) = o;
; #pragma unroll
;                 for (int i = 0; i < 8; ++i) v[i] = kk1[8 * g4 + i] * __expf(bc1 - bv1[8 * g4 + i]);
;                 o.x = pk2(v[0], v[1]); o.y = pk2(v[2], v[3]); o.z = pk2(v[4], v[5]); o.w = pk2(v[6], v[7]); *(u32x4*)(KHT + tile + (k + 1) * 32 + 8 * g4) = o; }
	v_mov_b32_e32 v29, v72
	v_mul_f32_e32 v2, 0x3fb8aa3b, v2
	v_pk_mul_f32 v[24:25], v[28:29], v[24:25]
	v_exp_f32_e32 v28, v2
	v_sub_f32_e32 v2, v31, v137
	v_mul_f32_e32 v2, 0x3fb8aa3b, v2
	v_exp_f32_e32 v29, v2
	v_cvt_pk_bf16_f32 v35, v36, v37
	v_sub_f32_e32 v2, v31, v139
	global_store_dwordx4 v[6:7], v[32:35], off offset:80
	v_mul_f32_e32 v2, 0x3fb8aa3b, v2
	v_mov_b32_e32 v64, v63
	v_mov_b32_e32 v32, v74
	v_mov_b32_e32 v33, v76
	v_pk_mul_f32 v[28:29], v[32:33], v[28:29]
	v_exp_f32_e32 v32, v2
	v_sub_f32_e32 v2, v31, v141
	v_mul_f32_e32 v2, 0x3fb8aa3b, v2
	v_exp_f32_e32 v33, v2
	v_sub_f32_e32 v2, v30, v126
	v_mov_b32_e32 v34, v78
	v_mov_b32_e32 v35, v80
	v_mul_f32_e32 v2, 0x3fb8aa3b, v2
	v_pk_mul_f32 v[36:37], v[34:35], v[32:33]
	v_cvt_pk_bf16_f32 v32, v4, v5
	v_exp_f32_e32 v4, v2
	v_sub_f32_e32 v2, v30, v128
	v_mul_f32_e32 v2, 0x3fb8aa3b, v2
	v_exp_f32_e32 v5, v2
	v_sub_f32_e32 v2, v30, v130
	v_mul_f32_e32 v2, 0x3fb8aa3b, v2
	v_cvt_pk_bf16_f32 v33, v24, v25
	v_exp_f32_e32 v24, v2
	v_sub_f32_e32 v2, v30, v132
	v_mul_f32_e32 v2, 0x3fb8aa3b, v2
	v_exp_f32_e32 v25, v2
	v_sub_f32_e32 v2, v30, v134
	v_mul_f32_e32 v2, 0x3fb8aa3b, v2
	v_cvt_pk_bf16_f32 v34, v28, v29
	v_exp_f32_e32 v28, v2
	v_sub_f32_e32 v2, v30, v136
	v_mul_f32_e32 v2, 0x3fb8aa3b, v2
	v_exp_f32_e32 v29, v2
	v_sub_f32_e32 v2, v30, v138
	v_cvt_pk_bf16_f32 v35, v36, v37
	v_mul_f32_e32 v2, 0x3fb8aa3b, v2
	global_store_dwordx4 v[6:7], v[32:35], off offset:32
	v_pk_mul_f32 v[4:5], v[64:65], v[4:5]
	v_mov_b32_e32 v80, v79
	v_exp_f32_e32 v32, v2
	v_sub_f32_e32 v2, v30, v140
	v_mul_f32_e32 v2, 0x3fb8aa3b, v2
	v_exp_f32_e32 v33, v2
	v_sub_f32_e32 v2, v31, v143
	v_mul_f32_e32 v2, 0x3fb8aa3b, v2
	v_mov_b32_e32 v72, v67
	v_pk_mul_f32 v[36:37], v[80:81], v[32:33]
	v_cvt_pk_bf16_f32 v32, v4, v5
	v_exp_f32_e32 v4, v2
	v_sub_f32_e32 v2, v31, v145
	v_mul_f32_e32 v2, 0x3fb8aa3b, v2
	v_exp_f32_e32 v5, v2
	v_pk_mul_f32 v[24:25], v[72:73], v[24:25]
	v_sub_f32_e32 v2, v31, v147
	v_cvt_pk_bf16_f32 v33, v24, v25
	v_mov_b32_e32 v24, v82
	v_mov_b32_e32 v25, v84
	v_mul_f32_e32 v2, 0x3fb8aa3b, v2
	v_pk_mul_f32 v[4:5], v[24:25], v[4:5]
	v_exp_f32_e32 v24, v2
	v_sub_f32_e32 v2, v31, v149
	v_mul_f32_e32 v2, 0x3fb8aa3b, v2
	v_exp_f32_e32 v25, v2
	v_mov_b32_e32 v76, v75
	v_pk_mul_f32 v[28:29], v[76:77], v[28:29]
	v_sub_f32_e32 v2, v31, v151
	v_cvt_pk_bf16_f32 v34, v28, v29
	v_mov_b32_e32 v28, v86
	v_mov_b32_e32 v29, v88
	v_mul_f32_e32 v2, 0x3fb8aa3b, v2
	v_pk_mul_f32 v[24:25], v[28:29], v[24:25]
	v_exp_f32_e32 v28, v2
	v_sub_f32_e32 v2, v31, v154
	v_mul_f32_e32 v2, 0x3fb8aa3b, v2
	v_exp_f32_e32 v29, v2
	v_cvt_pk_bf16_f32 v35, v36, v37
	v_sub_f32_e32 v2, v31, v155
	global_store_dwordx4 v[6:7], v[32:35], off offset:96
	v_mul_f32_e32 v2, 0x3fb8aa3b, v2
	v_cvt_pk_bf16_f32 v70, v70, v71
	v_mov_b32_e32 v32, v90
	v_mov_b32_e32 v33, v94
	v_pk_mul_f32 v[28:29], v[32:33], v[28:29]
	v_exp_f32_e32 v32, v2
	v_sub_f32_e32 v2, v31, v31
	v_mul_f32_e32 v2, 0x3fb8aa3b, v2
	v_exp_f32_e32 v33, v2
	v_sub_f32_e32 v2, v30, v142
	v_mov_b32_e32 v34, v92
	v_mov_b32_e32 v35, v26
	v_mul_f32_e32 v2, 0x3fb8aa3b, v2
	v_pk_mul_f32 v[36:37], v[34:35], v[32:33]
	v_cvt_pk_bf16_f32 v32, v4, v5
	v_exp_f32_e32 v4, v2
	v_sub_f32_e32 v2, v30, v144
	v_mul_f32_e32 v2, 0x3fb8aa3b, v2
	v_exp_f32_e32 v5, v2
	v_sub_f32_e32 v2, v30, v146
	v_cvt_pk_bf16_f32 v71, v156, v157
	v_cvt_pk_bf16_f32 v33, v24, v25
	v_cvt_pk_bf16_f32 v34, v28, v29
	v_cvt_pk_bf16_f32 v35, v36, v37
	v_mul_f32_e32 v2, 0x3fb8aa3b, v2
	global_store_dwordx4 v[6:7], v[68:71], off
	global_store_dwordx4 v[6:7], v[32:35], off offset:48
	v_exp_f32_e32 v6, v2
	v_sub_f32_e32 v2, v30, v148
	v_mul_f32_e32 v2, 0x3fb8aa3b, v2
	v_exp_f32_e32 v7, v2
	v_sub_f32_e32 v2, v30, v150
	v_mul_f32_e32 v2, 0x3fb8aa3b, v2
	v_exp_f32_e32 v24, v2
	v_sub_f32_e32 v2, v30, v152
	v_mul_f32_e32 v2, 0x3fb8aa3b, v2
	v_exp_f32_e32 v25, v2
	v_sub_f32_e32 v2, v30, v153
	v_mul_f32_e32 v2, 0x3fb8aa3b, v2
	v_exp_f32_e32 v28, v2
	v_sub_f32_e32 v2, v30, v30
	v_mul_f32_e32 v2, 0x3fb8aa3b, v2
	v_exp_f32_e32 v29, v2
	v_mov_b32_e32 v84, v83
	v_mov_b32_e32 v88, v87
	v_mov_b32_e32 v94, v91
	v_mov_b32_e32 v26, v93
	v_pk_mul_f32 v[4:5], v[84:85], v[4:5]
	v_pk_mul_f32 v[6:7], v[88:89], v[6:7]
	v_pk_mul_f32 v[24:25], v[94:95], v[24:25]
	v_pk_mul_f32 v[26:27], v[26:27], v[28:29]
	v_cvt_pk_bf16_f32 v4, v4, v5
	v_cvt_pk_bf16_f32 v5, v6, v7
	v_cvt_pk_bf16_f32 v6, v24, v25
	v_cvt_pk_bf16_f32 v7, v26, v27
	v_mov_b64_e32 v[26:27], 0x1ee00000
	s_branch .LBB0_595

; __device__ __forceinline__ void nsa_mfma_phase(const bf16* z, const bf16* kch, const bf16* kcl, const bf16* vct, const bf16* vst, const bf16* vwt, const float* biasTab, bf16* oc,
;                                                LAS unsigned char* lds, int tid0, int vcu, int G) {
;     ...
;             for (int ti = 0; ti < ntile; ++ti) { tile_st(tb + ti * TILEB, tile_ld(kh + ti * 64 * 64, 64, tid), tid); tile_st(tb + (2 + ti) * TILEB, tile_ld(kl_ + ti * 64 * 64, 64, tid), tid);
;                 tile_st(tb + (4 + ti) * TILEB, tile_ld(vt + ti * 64, 128, tid), tid); }
;             for (int i = tid; i < 64; i += 512) maskS[i] = 0u;
.LBB0_814:
	global_load_dwordx4 v[12:15], v[6:7], off
	v_add_co_u32_e32 v16, vcc, 0x80000, v6
	s_add_i32 s4, s4, -1
	s_nop 0
	v_addc_co_u32_e32 v17, vcc, 0, v7, vcc
	global_load_dwordx4 v[20:23], v[8:9], off
	s_cmp_eq_u32 s4, 0
	v_lshl_add_u64 v[6:7], v[6:7], 0, s[60:61]
	global_load_dwordx4 v[16:19], v[16:17], off
	v_lshl_add_u64 v[8:9], v[8:9], 0, s[70:71]
	s_waitcnt vmcnt(2)
	ds_write_b128 v5, v[12:15]
	s_waitcnt vmcnt(0)
	ds_write_b128 v5, v[16:19] offset:18432
	ds_write_b128 v5, v[20:23] offset:36864
	v_add_u32_e32 v5, 0x2400, v5
	s_cbranch_scc0 .LBB0_814
	v_cmp_gt_i32_e32 vcc, 64, v1
	s_and_saveexec_b64 s[4:5], vcc
	s_cbranch_execz .LBB0_818
	v_add_u32_e32 v5, 0xfffffe00, v1
	v_lshl_add_u32 v6, v1, 2, s94
	s_mov_b64 s[10:11], 0
